# GEMM K-loops: B0 fragment ds_reads moved from phase 1/5 into phase 4/8 (balances LDS read load 12-4-8-0 to 8-4-8-4), counted vmcnt(10) one phase earlier; redundant lgkmcnt(0) removed
# speedup vs baseline: 1.0272x; 1.0097x over previous
; #define PG8_STAGE(bufoff, gbase, voff) do { _Pragma("unroll") for (int _i = 0; _i < 2; ++_i) \
;         __builtin_amdgcn_global_load_lds((const unsigned*)((const char*)(gbase) + (voff)[_i]), (LAS unsigned*)(lds + (bufoff) + ldsw + _i * 8192), 16, 0, 0); } while (0)
; #define PG8_LDA(dst, b, h) do { _Pragma("unroll") for (int m = 0; m < 4; ++m) _Pragma("unroll") for (int k = 0; k < 2; ++k) dst[m][k] = *(const LAS bf16x8*)(lds + PG8_SA(b, h) + aoff + m * 2048 + k * 1024); } while (0)
; #define PG8_LDB(dst, b, h) do { _Pragma("unroll") for (int n = 0; n < 2; ++n) _Pragma("unroll") for (int k = 0; k < 2; ++k) dst[n][k] = *(const LAS bf16x8*)(lds + PG8_SB(b, h) + boff + n * 2048 + k * 1024); } while (0)
; #define PG8_MMA(ai, bj, At, Bt) do { __builtin_amdgcn_s_setprio(1); _Pragma("unroll") for (int m = 0; m < 4; ++m) _Pragma("unroll") for (int n = 0; n < 2; ++n) _Pragma("unroll") for (int k = 0; k < 2; ++k) \
;         acc[ai][bj][m][n] = __builtin_amdgcn_mfma_f32_16x16x32_bf16(Bt[n][k], At[m][k], acc[ai][bj][m][n], 0, 0, 0); __builtin_amdgcn_s_setprio(0); } while (0)
; #define PG8_WAIT_L(n) asm volatile("s_waitcnt lgkmcnt(" #n ")" ::: "memory")
; template <class Epi>
; __device__ __forceinline__ void gemm_phase(LAS unsigned char* lds, const Gemm g, const StaticOrder& S, const Epi& E) {
;     ...
;         const bool has_next = S.next(ui + 1, nxt);
;         const char* nA = has_next ? (const char*)g.A + (size_t)nxt.pm * tstep : cA; const char* nB = has_next ? (const char*)g.Bt + (size_t)nxt.pn * tstep : cB;
;         for (int t = 0; t < nt; t += 2) {
;             const bool last = (t == nt - 2);
;             const char* a1 = cA + (size_t)(t + 1) * kstep;
;             const char* a2 = last ? nA : cA + (size_t)(t + 2) * kstep; const char* b2 = last ? nB : cB + (size_t)(t + 2) * kstep;
;             const char* a3 = a2 + kstep; const char* b3 = b2 + kstep;
;             PG8_LDB(B0, 0, 0); PG8_SCHED; PG8_LDA(At, 0, 0); PG8_STAGE(PG8_SA(1, 1), a1 + hstep, voffA);
;             PG8_WAIT_L(8); PG8_BAR; PG8_WAIT_L(0); PG8_MMA(0, 0, At, B0); PG8_BAR; PG8_SCHED;
;     ...
;         for (int a = 0; a < 2; ++a)
; #pragma unroll
;             for (int b = 0; b < 2; ++b)
; #pragma unroll
;                 for (int m = 0; m < 4; ++m)
; #pragma unroll
;                     for (int n = 0; n < 2; ++n) acc[a][b][m][n] = (f32x4){0.f, 0.f, 0.f, 0.f};
.LBB0_63:
	v_mov_b64_e32 v[2:3], s[42:43]
	s_ashr_i32 s49, s48, 31
	v_cmp_lt_i64_e32 vcc, s[50:51], v[2:3]
	s_lshl_b64 s[50:51], s[48:49], 20
	v_readlane_b32 s52, v254, 8
	v_readlane_b32 s53, v254, 9
	s_add_u32 s50, s52, s50
	s_addc_u32 s51, s53, s51
	s_and_b64 s[52:53], vcc, exec
	s_cselect_b32 s49, s51, s57
	s_cselect_b32 s81, s50, s56
	s_ashr_i32 s47, s46, 31
	s_lshl_b64 s[52:53], s[46:47], 20
	s_add_u32 s52, s65, s52
	s_addc_u32 s53, s68, s53
	s_and_b64 s[60:61], vcc, exec
	s_cselect_b32 s47, s53, s59
	s_cselect_b32 s82, s52, s58
	s_add_u32 s56, s56, 0x80080
	s_addc_u32 s57, s57, 0
	s_add_u32 s83, s58, 0x100
	v_mov_b32_e32 v2, 0
	s_addc_u32 s84, s59, 0
	s_mov_b32 s85, -2
	v_mov_b32_e32 v3, v2
	v_mov_b32_e32 v4, v2
	v_mov_b32_e32 v5, v2
	v_mov_b32_e32 v6, v2
	v_mov_b32_e32 v7, v2
	v_mov_b32_e32 v8, v2
	v_mov_b32_e32 v9, v2
	v_mov_b32_e32 v10, v2
	v_mov_b32_e32 v11, v2
	v_mov_b32_e32 v12, v2
	v_mov_b32_e32 v13, v2
	v_mov_b32_e32 v18, v2
	v_mov_b32_e32 v19, v2
	v_mov_b32_e32 v20, v2
	v_mov_b32_e32 v21, v2
	s_waitcnt vmcnt(0)
	v_mov_b32_e32 v26, v2
	v_mov_b32_e32 v27, v2
	v_mov_b32_e32 v28, v2
	v_mov_b32_e32 v29, v2
	v_mov_b32_e32 v34, v2
	v_mov_b32_e32 v35, v2
	v_mov_b32_e32 v36, v2
	v_mov_b32_e32 v37, v2
	v_mov_b32_e32 v42, v2
	v_mov_b32_e32 v43, v2
	v_mov_b32_e32 v44, v2
	v_mov_b32_e32 v45, v2
	v_mov_b32_e32 v50, v2
	v_mov_b32_e32 v51, v2
	v_mov_b32_e32 v52, v2
	v_mov_b32_e32 v53, v2
	v_mov_b32_e32 v14, v2
	v_mov_b32_e32 v15, v2
	v_mov_b32_e32 v16, v2
	v_mov_b32_e32 v17, v2
	v_mov_b32_e32 v22, v2
	v_mov_b32_e32 v23, v2
	v_mov_b32_e32 v24, v2
	v_mov_b32_e32 v25, v2
	v_mov_b32_e32 v30, v2
	v_mov_b32_e32 v31, v2
	v_mov_b32_e32 v32, v2
	v_mov_b32_e32 v33, v2
	v_mov_b32_e32 v38, v2
	v_mov_b32_e32 v39, v2
	v_mov_b32_e32 v40, v2
	v_mov_b32_e32 v41, v2
	v_mov_b32_e32 v46, v2
	v_mov_b32_e32 v47, v2
	v_mov_b32_e32 v48, v2
	v_mov_b32_e32 v49, v2
	v_mov_b32_e32 v54, v2
	v_mov_b32_e32 v55, v2
	v_mov_b32_e32 v56, v2
	v_mov_b32_e32 v57, v2
	v_mov_b32_e32 v58, v2
	v_mov_b32_e32 v59, v2
	v_mov_b32_e32 v60, v2
	v_mov_b32_e32 v61, v2
	v_mov_b32_e32 v62, v2
	v_mov_b32_e32 v63, v2
	v_mov_b32_e32 v64, v2
	v_mov_b32_e32 v65, v2
	v_mov_b32_e32 v66, v2
	v_mov_b32_e32 v67, v2
	v_mov_b32_e32 v68, v2
	v_mov_b32_e32 v69, v2
	v_mov_b32_e32 v70, v2
	v_mov_b32_e32 v71, v2
	v_mov_b32_e32 v72, v2
	v_mov_b32_e32 v73, v2
	v_mov_b32_e32 v82, v2
	v_mov_b32_e32 v83, v2
	v_mov_b32_e32 v84, v2
	v_mov_b32_e32 v85, v2
	v_mov_b32_e32 v86, v2
	v_mov_b32_e32 v87, v2
	v_mov_b32_e32 v88, v2
	v_mov_b32_e32 v89, v2
	v_mov_b32_e32 v98, v2
	v_mov_b32_e32 v99, v2
	v_mov_b32_e32 v100, v2
	v_mov_b32_e32 v101, v2
	v_mov_b32_e32 v102, v2
	v_mov_b32_e32 v103, v2
	v_mov_b32_e32 v104, v2
	v_mov_b32_e32 v105, v2
	v_mov_b32_e32 v114, v2
	v_mov_b32_e32 v115, v2
	v_mov_b32_e32 v116, v2
	v_mov_b32_e32 v117, v2
	v_mov_b32_e32 v118, v2
	v_mov_b32_e32 v119, v2
	v_mov_b32_e32 v120, v2
	v_mov_b32_e32 v121, v2
	v_mov_b32_e32 v74, v2
	v_mov_b32_e32 v75, v2
	v_mov_b32_e32 v76, v2
	v_mov_b32_e32 v77, v2
	v_mov_b32_e32 v78, v2
	v_mov_b32_e32 v79, v2
	v_mov_b32_e32 v80, v2
	v_mov_b32_e32 v81, v2
	v_mov_b32_e32 v90, v2
	v_mov_b32_e32 v91, v2
	v_mov_b32_e32 v92, v2
	v_mov_b32_e32 v93, v2
	v_mov_b32_e32 v94, v2
	v_mov_b32_e32 v95, v2
	v_mov_b32_e32 v96, v2
	v_mov_b32_e32 v97, v2
	v_mov_b32_e32 v106, v2
	v_mov_b32_e32 v107, v2
	v_mov_b32_e32 v108, v2
	v_mov_b32_e32 v109, v2
	v_mov_b32_e32 v110, v2
	v_mov_b32_e32 v111, v2
	v_mov_b32_e32 v112, v2
	v_mov_b32_e32 v113, v2
	v_mov_b32_e32 v122, v2
	v_mov_b32_e32 v123, v2
	v_mov_b32_e32 v124, v2
	v_mov_b32_e32 v125, v2
	v_mov_b32_e32 v126, v2
	v_mov_b32_e32 v127, v2
	v_mov_b32_e32 v128, v2
	v_mov_b32_e32 v129, v2
	v_add_u32_e32 v140, 0x10000, v143
	ds_read_b128 v[154:157], v140
	ds_read_b128 v[158:161], v140 offset:1024
	ds_read_b128 v[162:165], v140 offset:2048
	ds_read_b128 v[166:169], v140 offset:3072
.LBB0_64:
	s_add_u32 s58, s56, 0xfff80080
	s_addc_u32 s59, s57, -1
	s_add_i32 s86, 0, 0x10000
	s_cmp_eq_u32 s85, 28
	s_cselect_b32 s61, s49, s59
	s_cselect_b32 s60, s81, s58
	s_cselect_b32 s59, s47, s84
	s_cselect_b32 s58, s82, s83
	s_add_i32 m0, s55, 0xc000
	ds_read_b128 v[170:173], v151
	ds_read_b128 v[174:177], v151 offset:1024
	ds_read_b128 v[178:181], v151 offset:2048
	ds_read_b128 v[182:185], v151 offset:3072
	ds_read_b128 v[186:189], v151 offset:4096
	ds_read_b128 v[190:193], v151 offset:5120
	ds_read_b128 v[194:197], v151 offset:6144
	ds_read_b128 v[198:201], v151 offset:7168
	global_load_lds_dwordx4 v136, s[56:57]
	s_add_i32 m0, s55, 0xe000
	s_nop 0
	global_load_lds_dwordx4 v138, s[56:57]
	s_waitcnt lgkmcnt(8)
	s_barrier
	s_waitcnt lgkmcnt(0)
	s_setprio 1
	v_mfma_f32_16x16x32_bf16 v[126:129], v[154:157], v[170:173], v[126:129]
	v_mfma_f32_16x16x32_bf16 v[122:125], v[162:165], v[170:173], v[122:125]
	v_mfma_f32_16x16x32_bf16 v[110:113], v[154:157], v[178:181], v[110:113]
	v_mfma_f32_16x16x32_bf16 v[106:109], v[162:165], v[178:181], v[106:109]
	v_mfma_f32_16x16x32_bf16 v[94:97], v[154:157], v[186:189], v[94:97]
	v_mfma_f32_16x16x32_bf16 v[90:93], v[162:165], v[186:189], v[90:93]
	v_mfma_f32_16x16x32_bf16 v[78:81], v[154:157], v[194:197], v[78:81]
	v_mfma_f32_16x16x32_bf16 v[74:77], v[162:165], v[194:197], v[74:77]
	v_mfma_f32_16x16x32_bf16 v[126:129], v[158:161], v[174:177], v[126:129]
	v_mfma_f32_16x16x32_bf16 v[122:125], v[166:169], v[174:177], v[122:125]
	v_mfma_f32_16x16x32_bf16 v[110:113], v[158:161], v[182:185], v[110:113]
	v_mfma_f32_16x16x32_bf16 v[106:109], v[166:169], v[182:185], v[106:109]
	v_mfma_f32_16x16x32_bf16 v[94:97], v[158:161], v[190:193], v[94:97]
	v_mfma_f32_16x16x32_bf16 v[90:93], v[166:169], v[190:193], v[90:93]
	v_mfma_f32_16x16x32_bf16 v[78:81], v[158:161], v[198:201], v[78:81]
	v_mfma_f32_16x16x32_bf16 v[74:77], v[166:169], v[198:201], v[74:77]
	s_setprio 0
	s_barrier
; #define PG8_STAGE(bufoff, gbase, voff) do { _Pragma("unroll") for (int _i = 0; _i < 2; ++_i) \
;         __builtin_amdgcn_global_load_lds((const unsigned*)((const char*)(gbase) + (voff)[_i]), (LAS unsigned*)(lds + (bufoff) + ldsw + _i * 8192), 16, 0, 0); } while (0)
; #define PG8_LDA(dst, b, h) do { _Pragma("unroll") for (int m = 0; m < 4; ++m) _Pragma("unroll") for (int k = 0; k < 2; ++k) dst[m][k] = *(const LAS bf16x8*)(lds + PG8_SA(b, h) + aoff + m * 2048 + k * 1024); } while (0)
; #define PG8_LDB(dst, b, h) do { _Pragma("unroll") for (int n = 0; n < 2; ++n) _Pragma("unroll") for (int k = 0; k < 2; ++k) dst[n][k] = *(const LAS bf16x8*)(lds + PG8_SB(b, h) + boff + n * 2048 + k * 1024); } while (0)
; #define PG8_MMA(ai, bj, At, Bt) do { __builtin_amdgcn_s_setprio(1); _Pragma("unroll") for (int m = 0; m < 4; ++m) _Pragma("unroll") for (int n = 0; n < 2; ++n) _Pragma("unroll") for (int k = 0; k < 2; ++k) \
;         acc[ai][bj][m][n] = __builtin_amdgcn_mfma_f32_16x16x32_bf16(Bt[n][k], At[m][k], acc[ai][bj][m][n], 0, 0, 0); __builtin_amdgcn_s_setprio(0); } while (0)
; #define PG8_WAIT_V(n) asm volatile("s_waitcnt vmcnt(" #n ")" ::: "memory")
; #define PG8_WAIT_L(n) asm volatile("s_waitcnt lgkmcnt(" #n ")" ::: "memory")
; #define PG8_BAR __builtin_amdgcn_s_barrier()
; #define PG8_SCHED __builtin_amdgcn_sched_barrier(0)
; template <class Epi>
; __device__ __forceinline__ void gemm_phase(LAS unsigned char* lds, const Gemm g, const StaticOrder& S, const Epi& E) {
;     ...
;             PG8_LDB(B1, 0, 1); PG8_STAGE(PG8_SB(0, 0), b2, voffB);
;             PG8_BAR; PG8_WAIT_L(0); PG8_MMA(0, 1, At, B1); PG8_BAR;
;             PG8_LDA(At, 0, 1); PG8_STAGE(PG8_SA(0, 0), a2, voffA);
;             PG8_BAR; PG8_WAIT_L(0); PG8_MMA(1, 0, At, B0); PG8_BAR; PG8_SCHED;
;             PG8_STAGE(PG8_SB(0, 1), b2 + hstep, voffB);
;             PG8_WAIT_V(6); PG8_BAR; PG8_MMA(1, 1, At, B1); PG8_BAR;
;             PG8_LDB(B0, 1, 0); PG8_SCHED; PG8_LDA(At, 1, 0); PG8_STAGE(PG8_SA(0, 1), a2 + hstep, voffA);
;             PG8_WAIT_L(8); PG8_BAR; PG8_WAIT_L(0); PG8_MMA(0, 0, At, B0); PG8_BAR; PG8_SCHED;
	s_add_i32 s88, 0, 0x14000
	s_add_i32 s86, s86, s69
	v_add_u32_e32 v140, s88, v143
	s_add_u32 s98, s58, s22
	s_addc_u32 s99, s59, s23
	s_mov_b32 m0, s86
	ds_read_b128 v[208:211], v140
	ds_read_b128 v[212:215], v140 offset:1024
	ds_read_b128 v[216:219], v140 offset:2048
	ds_read_b128 v[220:223], v140 offset:3072
	global_load_lds_dwordx4 v0, s[58:59]
	s_add_i32 m0, s86, 0x2000
	s_nop 0
	global_load_lds_dwordx4 v130, s[58:59]
	s_barrier
	s_waitcnt lgkmcnt(0)
	s_setprio 1
	v_mfma_f32_16x16x32_bf16 v[118:121], v[208:211], v[170:173], v[118:121]
	v_mfma_f32_16x16x32_bf16 v[114:117], v[216:219], v[170:173], v[114:117]
	v_mfma_f32_16x16x32_bf16 v[102:105], v[208:211], v[178:181], v[102:105]
	v_mfma_f32_16x16x32_bf16 v[98:101], v[216:219], v[178:181], v[98:101]
	v_mfma_f32_16x16x32_bf16 v[86:89], v[208:211], v[186:189], v[86:89]
	v_mfma_f32_16x16x32_bf16 v[82:85], v[216:219], v[186:189], v[82:85]
	v_mfma_f32_16x16x32_bf16 v[70:73], v[208:211], v[194:197], v[70:73]
	v_mfma_f32_16x16x32_bf16 v[66:69], v[216:219], v[194:197], v[66:69]
	v_mfma_f32_16x16x32_bf16 v[118:121], v[212:215], v[174:177], v[118:121]
	v_mfma_f32_16x16x32_bf16 v[114:117], v[220:223], v[174:177], v[114:117]
	v_mfma_f32_16x16x32_bf16 v[102:105], v[212:215], v[182:185], v[102:105]
	v_mfma_f32_16x16x32_bf16 v[98:101], v[220:223], v[182:185], v[98:101]
	v_mfma_f32_16x16x32_bf16 v[86:89], v[212:215], v[190:193], v[86:89]
	v_mfma_f32_16x16x32_bf16 v[82:85], v[220:223], v[190:193], v[82:85]
	v_mfma_f32_16x16x32_bf16 v[70:73], v[212:215], v[198:201], v[70:73]
	v_mfma_f32_16x16x32_bf16 v[66:69], v[220:223], v[198:201], v[66:69]
	s_setprio 0
	s_mov_b32 m0, s55
	s_add_u32 s100, s60, s22
	s_addc_u32 s101, s61, s23
	s_barrier
	ds_read_b128 v[170:173], v151 offset:16384
	ds_read_b128 v[174:177], v151 offset:17408
	ds_read_b128 v[178:181], v151 offset:18432
	ds_read_b128 v[182:185], v151 offset:19456
	ds_read_b128 v[186:189], v151 offset:20480
	ds_read_b128 v[190:193], v151 offset:21504
	ds_read_b128 v[194:197], v151 offset:22528
	ds_read_b128 v[198:201], v151 offset:23552
	global_load_lds_dwordx4 v134, s[60:61]
	s_mov_b32 m0, s72
	s_nop 0
	global_load_lds_dwordx4 v132, s[60:61]
	s_waitcnt vmcnt(10)
	s_barrier
	s_waitcnt lgkmcnt(0)
	s_setprio 1
	v_mfma_f32_16x16x32_bf16 v[62:65], v[154:157], v[170:173], v[62:65]
	v_mfma_f32_16x16x32_bf16 v[58:61], v[162:165], v[170:173], v[58:61]
	v_mfma_f32_16x16x32_bf16 v[54:57], v[154:157], v[178:181], v[54:57]
	v_mfma_f32_16x16x32_bf16 v[46:49], v[162:165], v[178:181], v[46:49]
	v_mfma_f32_16x16x32_bf16 v[38:41], v[154:157], v[186:189], v[38:41]
	v_mfma_f32_16x16x32_bf16 v[30:33], v[162:165], v[186:189], v[30:33]
	v_mfma_f32_16x16x32_bf16 v[22:25], v[154:157], v[194:197], v[22:25]
	v_mfma_f32_16x16x32_bf16 v[14:17], v[162:165], v[194:197], v[14:17]
	v_mfma_f32_16x16x32_bf16 v[62:65], v[158:161], v[174:177], v[62:65]
	v_mfma_f32_16x16x32_bf16 v[58:61], v[166:169], v[174:177], v[58:61]
	v_mfma_f32_16x16x32_bf16 v[54:57], v[158:161], v[182:185], v[54:57]
	v_mfma_f32_16x16x32_bf16 v[46:49], v[166:169], v[182:185], v[46:49]
	v_mfma_f32_16x16x32_bf16 v[38:41], v[158:161], v[190:193], v[38:41]
	v_mfma_f32_16x16x32_bf16 v[30:33], v[166:169], v[190:193], v[30:33]
	v_mfma_f32_16x16x32_bf16 v[22:25], v[158:161], v[198:201], v[22:25]
	v_mfma_f32_16x16x32_bf16 v[14:17], v[166:169], v[198:201], v[14:17]
	s_setprio 0
	s_barrier
	v_add_u32_e32 v140, 0x18000, v143
	ds_read_b128 v[154:157], v140
	ds_read_b128 v[158:161], v140 offset:1024
	ds_read_b128 v[162:165], v140 offset:2048
	ds_read_b128 v[166:169], v140 offset:3072
	s_add_u32 s86, s58, 0x80000
	s_addc_u32 s87, s59, 0
	s_add_i32 s88, s88, s69
	s_mov_b32 m0, s88
	s_nop 0
	global_load_lds_dwordx4 v0, s[86:87]
	s_add_i32 m0, s88, 0x2000
	s_nop 0
	global_load_lds_dwordx4 v130, s[86:87]
	s_waitcnt vmcnt(6)
	s_barrier
	s_setprio 1
	v_mfma_f32_16x16x32_bf16 v[50:53], v[208:211], v[170:173], v[50:53]
	v_mfma_f32_16x16x32_bf16 v[42:45], v[216:219], v[170:173], v[42:45]
	v_mfma_f32_16x16x32_bf16 v[34:37], v[208:211], v[178:181], v[34:37]
	v_mfma_f32_16x16x32_bf16 v[26:29], v[216:219], v[178:181], v[26:29]
	v_mfma_f32_16x16x32_bf16 v[18:21], v[208:211], v[186:189], v[18:21]
	v_mfma_f32_16x16x32_bf16 v[10:13], v[216:219], v[186:189], v[10:13]
	v_mfma_f32_16x16x32_bf16 v[6:9], v[208:211], v[194:197], v[6:9]
	v_mfma_f32_16x16x32_bf16 v[2:5], v[216:219], v[194:197], v[2:5]
	v_mfma_f32_16x16x32_bf16 v[50:53], v[212:215], v[174:177], v[50:53]
	v_mfma_f32_16x16x32_bf16 v[42:45], v[220:223], v[174:177], v[42:45]
	v_mfma_f32_16x16x32_bf16 v[34:37], v[212:215], v[182:185], v[34:37]
	v_mfma_f32_16x16x32_bf16 v[26:29], v[220:223], v[182:185], v[26:29]
	v_mfma_f32_16x16x32_bf16 v[18:21], v[212:215], v[190:193], v[18:21]
	v_mfma_f32_16x16x32_bf16 v[10:13], v[220:223], v[190:193], v[10:13]
	v_mfma_f32_16x16x32_bf16 v[6:9], v[212:215], v[198:201], v[6:9]
	v_mfma_f32_16x16x32_bf16 v[2:5], v[220:223], v[198:201], v[2:5]
	s_setprio 0
	s_add_i32 s86, 0, 0x18000
	s_barrier
	s_add_u32 s60, s60, 0x80000
	s_addc_u32 s61, s61, 0
	s_mov_b32 m0, s73
	ds_read_b128 v[170:173], v151 offset:32768
	ds_read_b128 v[174:177], v151 offset:33792
	ds_read_b128 v[178:181], v151 offset:34816
	ds_read_b128 v[182:185], v151 offset:35840
	ds_read_b128 v[186:189], v151 offset:36864
	ds_read_b128 v[190:193], v151 offset:37888
	ds_read_b128 v[194:197], v151 offset:38912
	ds_read_b128 v[198:201], v151 offset:39936
	global_load_lds_dwordx4 v134, s[60:61]
	s_mov_b32 m0, s74
	s_nop 0
	global_load_lds_dwordx4 v132, s[60:61]
	s_waitcnt lgkmcnt(8)
	s_barrier
; #define PG8_STAGE(bufoff, gbase, voff) do { _Pragma("unroll") for (int _i = 0; _i < 2; ++_i) \
;         __builtin_amdgcn_global_load_lds((const unsigned*)((const char*)(gbase) + (voff)[_i]), (LAS unsigned*)(lds + (bufoff) + ldsw + _i * 8192), 16, 0, 0); } while (0)
; #define PG8_LDA(dst, b, h) do { _Pragma("unroll") for (int m = 0; m < 4; ++m) _Pragma("unroll") for (int k = 0; k < 2; ++k) dst[m][k] = *(const LAS bf16x8*)(lds + PG8_SA(b, h) + aoff + m * 2048 + k * 1024); } while (0)
; #define PG8_LDB(dst, b, h) do { _Pragma("unroll") for (int n = 0; n < 2; ++n) _Pragma("unroll") for (int k = 0; k < 2; ++k) dst[n][k] = *(const LAS bf16x8*)(lds + PG8_SB(b, h) + boff + n * 2048 + k * 1024); } while (0)
; #define PG8_MMA(ai, bj, At, Bt) do { __builtin_amdgcn_s_setprio(1); _Pragma("unroll") for (int m = 0; m < 4; ++m) _Pragma("unroll") for (int n = 0; n < 2; ++n) _Pragma("unroll") for (int k = 0; k < 2; ++k) \
;         acc[ai][bj][m][n] = __builtin_amdgcn_mfma_f32_16x16x32_bf16(Bt[n][k], At[m][k], acc[ai][bj][m][n], 0, 0, 0); __builtin_amdgcn_s_setprio(0); } while (0)
; #define PG8_WAIT_V(n) asm volatile("s_waitcnt vmcnt(" #n ")" ::: "memory")
; #define PG8_WAIT_L(n) asm volatile("s_waitcnt lgkmcnt(" #n ")" ::: "memory")
; #define PG8_BAR __builtin_amdgcn_s_barrier()
; #define PG8_SCHED __builtin_amdgcn_sched_barrier(0)
; template <class Epi>
; __device__ __forceinline__ void gemm_phase(LAS unsigned char* lds, const Gemm g, const StaticOrder& S, const Epi& E) {
;     ...
;             PG8_WAIT_L(8); PG8_BAR; PG8_WAIT_L(0); PG8_MMA(0, 0, At, B0); PG8_BAR; PG8_SCHED;
;             PG8_LDB(B1, 1, 1); PG8_STAGE(PG8_SB(1, 0), b3, voffB);
;             PG8_BAR; PG8_WAIT_L(0); PG8_MMA(0, 1, At, B1); PG8_BAR;
;             PG8_LDA(At, 1, 1); PG8_STAGE(PG8_SA(1, 0), a3, voffA);
;             PG8_BAR; PG8_WAIT_L(0); PG8_MMA(1, 0, At, B0); PG8_BAR; PG8_SCHED;
;             PG8_STAGE(PG8_SB(1, 1), b3 + hstep, voffB);
;             PG8_WAIT_V(6); PG8_BAR; PG8_MMA(1, 1, At, B1); PG8_BAR;
	s_waitcnt lgkmcnt(0)
	s_setprio 1
	v_mfma_f32_16x16x32_bf16 v[126:129], v[154:157], v[170:173], v[126:129]
	v_mfma_f32_16x16x32_bf16 v[122:125], v[162:165], v[170:173], v[122:125]
	v_mfma_f32_16x16x32_bf16 v[110:113], v[154:157], v[178:181], v[110:113]
	v_mfma_f32_16x16x32_bf16 v[106:109], v[162:165], v[178:181], v[106:109]
	v_mfma_f32_16x16x32_bf16 v[94:97], v[154:157], v[186:189], v[94:97]
	v_mfma_f32_16x16x32_bf16 v[90:93], v[162:165], v[186:189], v[90:93]
	v_mfma_f32_16x16x32_bf16 v[78:81], v[154:157], v[194:197], v[78:81]
	v_mfma_f32_16x16x32_bf16 v[74:77], v[162:165], v[194:197], v[74:77]
	v_mfma_f32_16x16x32_bf16 v[126:129], v[158:161], v[174:177], v[126:129]
	v_mfma_f32_16x16x32_bf16 v[122:125], v[166:169], v[174:177], v[122:125]
	v_mfma_f32_16x16x32_bf16 v[110:113], v[158:161], v[182:185], v[110:113]
	v_mfma_f32_16x16x32_bf16 v[106:109], v[166:169], v[182:185], v[106:109]
	v_mfma_f32_16x16x32_bf16 v[94:97], v[158:161], v[190:193], v[94:97]
	v_mfma_f32_16x16x32_bf16 v[90:93], v[166:169], v[190:193], v[90:93]
	v_mfma_f32_16x16x32_bf16 v[78:81], v[158:161], v[198:201], v[78:81]
	v_mfma_f32_16x16x32_bf16 v[74:77], v[166:169], v[198:201], v[74:77]
	s_setprio 0
	s_barrier
	s_add_i32 s60, 0, 0x1c000
	s_add_i32 s61, s86, s69
	v_add_u32_e32 v140, s60, v143
	s_mov_b32 m0, s61
	ds_read_b128 v[208:211], v140
	ds_read_b128 v[212:215], v140 offset:1024
	ds_read_b128 v[216:219], v140 offset:2048
	ds_read_b128 v[220:223], v140 offset:3072
	global_load_lds_dwordx4 v0, s[98:99]
	s_add_i32 m0, s61, 0x2000
	s_nop 0
	global_load_lds_dwordx4 v130, s[98:99]
	s_barrier
	s_waitcnt lgkmcnt(0)
	s_setprio 1
	v_mfma_f32_16x16x32_bf16 v[118:121], v[208:211], v[170:173], v[118:121]
	v_mfma_f32_16x16x32_bf16 v[114:117], v[216:219], v[170:173], v[114:117]
	v_mfma_f32_16x16x32_bf16 v[102:105], v[208:211], v[178:181], v[102:105]
	v_mfma_f32_16x16x32_bf16 v[98:101], v[216:219], v[178:181], v[98:101]
	v_mfma_f32_16x16x32_bf16 v[86:89], v[208:211], v[186:189], v[86:89]
	v_mfma_f32_16x16x32_bf16 v[82:85], v[216:219], v[186:189], v[82:85]
	v_mfma_f32_16x16x32_bf16 v[70:73], v[208:211], v[194:197], v[70:73]
	v_mfma_f32_16x16x32_bf16 v[66:69], v[216:219], v[194:197], v[66:69]
	v_mfma_f32_16x16x32_bf16 v[118:121], v[212:215], v[174:177], v[118:121]
	v_mfma_f32_16x16x32_bf16 v[114:117], v[220:223], v[174:177], v[114:117]
	v_mfma_f32_16x16x32_bf16 v[102:105], v[212:215], v[182:185], v[102:105]
	v_mfma_f32_16x16x32_bf16 v[98:101], v[220:223], v[182:185], v[98:101]
	v_mfma_f32_16x16x32_bf16 v[86:89], v[212:215], v[190:193], v[86:89]
	v_mfma_f32_16x16x32_bf16 v[82:85], v[220:223], v[190:193], v[82:85]
	v_mfma_f32_16x16x32_bf16 v[70:73], v[212:215], v[198:201], v[70:73]
	v_mfma_f32_16x16x32_bf16 v[66:69], v[220:223], v[198:201], v[66:69]
	s_setprio 0
	s_mov_b32 m0, s76
	s_barrier
	ds_read_b128 v[170:173], v151 offset:49152
	ds_read_b128 v[174:177], v151 offset:50176
	ds_read_b128 v[178:181], v151 offset:51200
	ds_read_b128 v[182:185], v151 offset:52224
	ds_read_b128 v[186:189], v151 offset:53248
	ds_read_b128 v[190:193], v151 offset:54272
	ds_read_b128 v[194:197], v151 offset:55296
	ds_read_b128 v[198:201], v151 offset:56320
	global_load_lds_dwordx4 v134, s[100:101]
	s_mov_b32 m0, s77
	s_nop 0
	global_load_lds_dwordx4 v132, s[100:101]
	s_waitcnt vmcnt(10)
	s_barrier
	s_waitcnt lgkmcnt(0)
	s_setprio 1
	v_mfma_f32_16x16x32_bf16 v[62:65], v[154:157], v[170:173], v[62:65]
	v_mfma_f32_16x16x32_bf16 v[58:61], v[162:165], v[170:173], v[58:61]
	v_mfma_f32_16x16x32_bf16 v[54:57], v[154:157], v[178:181], v[54:57]
	v_mfma_f32_16x16x32_bf16 v[46:49], v[162:165], v[178:181], v[46:49]
	v_mfma_f32_16x16x32_bf16 v[38:41], v[154:157], v[186:189], v[38:41]
	v_mfma_f32_16x16x32_bf16 v[30:33], v[162:165], v[186:189], v[30:33]
	v_mfma_f32_16x16x32_bf16 v[22:25], v[154:157], v[194:197], v[22:25]
	v_mfma_f32_16x16x32_bf16 v[14:17], v[162:165], v[194:197], v[14:17]
	v_mfma_f32_16x16x32_bf16 v[62:65], v[158:161], v[174:177], v[62:65]
	v_mfma_f32_16x16x32_bf16 v[58:61], v[166:169], v[174:177], v[58:61]
	v_mfma_f32_16x16x32_bf16 v[54:57], v[158:161], v[182:185], v[54:57]
	v_mfma_f32_16x16x32_bf16 v[46:49], v[166:169], v[182:185], v[46:49]
	v_mfma_f32_16x16x32_bf16 v[38:41], v[158:161], v[190:193], v[38:41]
	v_mfma_f32_16x16x32_bf16 v[30:33], v[166:169], v[190:193], v[30:33]
	v_mfma_f32_16x16x32_bf16 v[22:25], v[158:161], v[198:201], v[22:25]
	v_mfma_f32_16x16x32_bf16 v[14:17], v[166:169], v[198:201], v[14:17]
	s_setprio 0
	s_barrier
	v_add_u32_e32 v140, 0x10000, v143
	ds_read_b128 v[154:157], v140
	ds_read_b128 v[158:161], v140 offset:1024
	ds_read_b128 v[162:165], v140 offset:2048
	ds_read_b128 v[166:169], v140 offset:3072
	s_add_u32 s58, s58, 0x80080
	s_addc_u32 s59, s59, 0
	s_add_i32 s60, s60, s69
	s_mov_b32 m0, s60
	s_nop 0
	global_load_lds_dwordx4 v0, s[58:59]
	s_add_i32 m0, s60, 0x2000
	s_nop 0
	global_load_lds_dwordx4 v130, s[58:59]
	s_waitcnt vmcnt(6)
	s_barrier
	s_setprio 1
	v_mfma_f32_16x16x32_bf16 v[50:53], v[208:211], v[170:173], v[50:53]
	v_mfma_f32_16x16x32_bf16 v[42:45], v[216:219], v[170:173], v[42:45]
	v_mfma_f32_16x16x32_bf16 v[34:37], v[208:211], v[178:181], v[34:37]
	v_mfma_f32_16x16x32_bf16 v[26:29], v[216:219], v[178:181], v[26:29]
	v_mfma_f32_16x16x32_bf16 v[18:21], v[208:211], v[186:189], v[18:21]
	v_mfma_f32_16x16x32_bf16 v[10:13], v[216:219], v[186:189], v[10:13]
	v_mfma_f32_16x16x32_bf16 v[6:9], v[208:211], v[194:197], v[6:9]
	v_mfma_f32_16x16x32_bf16 v[2:5], v[216:219], v[194:197], v[2:5]
	v_mfma_f32_16x16x32_bf16 v[50:53], v[212:215], v[174:177], v[50:53]
	v_mfma_f32_16x16x32_bf16 v[42:45], v[220:223], v[174:177], v[42:45]
	v_mfma_f32_16x16x32_bf16 v[34:37], v[212:215], v[182:185], v[34:37]
	v_mfma_f32_16x16x32_bf16 v[26:29], v[220:223], v[182:185], v[26:29]
	v_mfma_f32_16x16x32_bf16 v[18:21], v[212:215], v[190:193], v[18:21]
	v_mfma_f32_16x16x32_bf16 v[10:13], v[220:223], v[190:193], v[10:13]
	v_mfma_f32_16x16x32_bf16 v[6:9], v[212:215], v[198:201], v[6:9]
	v_mfma_f32_16x16x32_bf16 v[2:5], v[220:223], v[198:201], v[2:5]
	s_setprio 0
	s_add_i32 s85, s85, 2
	s_add_u32 s56, s56, 0x100
	s_addc_u32 s57, s57, 0
	s_add_u32 s83, s83, 0x100
	s_addc_u32 s84, s84, 0
	s_cmp_gt_u32 s85, 29
	s_barrier
; __device__ __forceinline__ unsigned pk2(float lo, float hi) { f32x2 v = {lo, hi}; bf16x2_t b = __builtin_convertvector(v, bf16x2_t); return __builtin_bit_cast(unsigned, b); }
;     __device__ __forceinline__ void operator()(const AccT& acc, const Unit& u, int wr, int wc, int fr, int fq) const {
;     ...
;         float rsv[8];
;         if (ss) {
;             const int ln = (fq << 4) | fr;
;             float sa = ss[u.pm * BM + wr * 64 + ln], sb = ss[u.pm * BM + HALF + wr * 64 + ln];
;             sa = __builtin_amdgcn_rsqf(sa * (1.0f / DM) + EPS); sb = __builtin_amdgcn_rsqf(sb * (1.0f / DM) + EPS);
; #pragma unroll
;             for (int m = 0; m < 4; ++m) { rsv[m] = __shfl(sa, 16 * m + fr); rsv[4 + m] = __shfl(sb, 16 * m + fr); }
;         } else {
; #pragma unroll
;             for (int i = 0; i < 8; ++i) rsv[i] = 1.0f;
;         }
; #pragma unroll
;         for (int ai = 0; ai < 2; ++ai)
; #pragma unroll
;             for (int m = 0; m < 4; ++m) {
;                 const int row = row0 + ai * HALF + m * 16;
;                 const float rs = rsv[ai * 4 + m];
; #pragma unroll
;                 for (int bj = 0; bj < 2; ++bj) {
;                     const f32x4 v0 = acc[ai][bj][m][0] * rs, v1 = acc[ai][bj][m][1] * rs;
;                     u32x4 w; w.x = pk2(v0[0], v0[1]); w.y = pk2(v0[2], v0[3]); w.z = pk2(v1[0], v1[1]); w.w = pk2(v1[2], v1[3]);
;                     *(u32x4*)(out + (size_t)row * ldo + col0 + bj * HALF) = w;
	s_cbranch_scc0 .LBB0_64
	s_waitcnt lgkmcnt(0)
	s_lshl_b32 s47, s54, 8
	s_add_i32 s47, s47, s75
	v_or_b32_e32 v154, s47, v145
	v_ashrrev_i32_e32 v155, 31, v154
	v_lshl_add_u64 v[154:155], v[154:155], 2, s[2:3]
	global_load_dword v140, v[154:155], off
	v_add_u32_e32 v154, s47, v147
	v_ashrrev_i32_e32 v155, 31, v154
	v_lshl_add_u64 v[154:155], v[154:155], 2, s[2:3]
	global_load_dword v142, v[154:155], off
	v_lshl_or_b32 v158, s80, 8, v149
	v_ashrrev_i32_e32 v159, 31, v158
	s_and_b64 vcc, exec, s[36:37]
	s_mov_b32 s80, s46
	s_mov_b32 s54, s48
	s_mov_b64 s[58:59], s[52:53]
	s_waitcnt vmcnt(0)
	v_fmamk_f32 v140, v140, 0x3a000000, v233
	v_rsq_f32_e32 v140, v140
	v_fmamk_f32 v142, v142, 0x3a000000, v233
	ds_bpermute_b32 v154, v152, v140
	v_rsq_f32_e32 v153, v142
	ds_bpermute_b32 v156, v152, v140 offset:64
	ds_bpermute_b32 v150, v152, v140 offset:128
	ds_bpermute_b32 v148, v152, v140 offset:192
	ds_bpermute_b32 v146, v152, v153
	ds_bpermute_b32 v144, v152, v153 offset:64
	ds_bpermute_b32 v142, v152, v153 offset:128
	ds_bpermute_b32 v140, v152, v153 offset:192
	v_or_b32_e32 v153, s47, v141
	s_waitcnt lgkmcnt(0)
	v_pk_mul_f32 v[126:127], v[126:127], v[154:155] op_sel_hi:[1,0]
	v_pk_mul_f32 v[122:123], v[122:123], v[154:155] op_sel_hi:[1,0]
	v_pk_mul_f32 v[128:129], v[128:129], v[154:155] op_sel_hi:[1,0]
	v_pk_mul_f32 v[160:161], v[124:125], v[154:155] op_sel_hi:[1,0]
	v_cvt_pk_bf16_f32 v124, v126, v127
	v_cvt_pk_bf16_f32 v126, v122, v123
	v_mad_i64_i32 v[122:123], s[56:57], v153, s63, 0
	v_cvt_pk_bf16_f32 v125, v128, v129
	v_lshl_add_u64 v[128:129], v[122:123], 1, s[44:45]
	v_lshlrev_b64 v[122:123], 1, v[158:159]
	v_cvt_pk_bf16_f32 v127, v160, v161
	v_lshl_add_u64 v[128:129], v[128:129], 0, v[122:123]
	global_store_dwordx4 v[128:129], v[124:127], off
	v_pk_mul_f32 v[120:121], v[120:121], v[154:155] op_sel_hi:[1,0]
	v_pk_mul_f32 v[118:119], v[118:119], v[154:155] op_sel_hi:[1,0]
	v_pk_mul_f32 v[124:125], v[116:117], v[154:155] op_sel_hi:[1,0]
	v_pk_mul_f32 v[116:117], v[114:115], v[154:155] op_sel_hi:[1,0]
	v_cvt_pk_bf16_f32 v114, v118, v119
	v_cvt_pk_bf16_f32 v115, v120, v121
	v_cvt_pk_bf16_f32 v116, v116, v117
	v_cvt_pk_bf16_f32 v117, v124, v125
	global_store_dwordx4 v[128:129], v[114:117], off offset:256
	v_pk_mul_f32 v[110:111], v[110:111], v[156:157] op_sel_hi:[1,0]
	v_pk_mul_f32 v[112:113], v[112:113], v[156:157] op_sel_hi:[1,0]
	v_or_b32_e32 v116, 16, v153
	v_pk_mul_f32 v[114:115], v[108:109], v[156:157] op_sel_hi:[1,0]
	v_pk_mul_f32 v[108:109], v[106:107], v[156:157] op_sel_hi:[1,0]
	v_cvt_pk_bf16_f32 v106, v110, v111
	v_mad_i64_i32 v[110:111], s[56:57], v116, s63, 0
	v_lshl_add_u64 v[110:111], v[110:111], 1, s[44:45]
	v_cvt_pk_bf16_f32 v107, v112, v113
	v_cvt_pk_bf16_f32 v108, v108, v109
	v_cvt_pk_bf16_f32 v109, v114, v115
	v_lshl_add_u64 v[110:111], v[110:111], 0, v[122:123]
	global_store_dwordx4 v[110:111], v[106:109], off
	v_pk_mul_f32 v[104:105], v[104:105], v[156:157] op_sel_hi:[1,0]
	v_pk_mul_f32 v[102:103], v[102:103], v[156:157] op_sel_hi:[1,0]
	v_pk_mul_f32 v[106:107], v[100:101], v[156:157] op_sel_hi:[1,0]
	v_pk_mul_f32 v[100:101], v[98:99], v[156:157] op_sel_hi:[1,0]
	v_cvt_pk_bf16_f32 v98, v102, v103
	v_cvt_pk_bf16_f32 v99, v104, v105
	v_cvt_pk_bf16_f32 v100, v100, v101
	v_cvt_pk_bf16_f32 v101, v106, v107
	global_store_dwordx4 v[110:111], v[98:101], off offset:256
	v_pk_mul_f32 v[94:95], v[94:95], v[150:151] op_sel_hi:[1,0]
	v_pk_mul_f32 v[96:97], v[96:97], v[150:151] op_sel_hi:[1,0]
	v_or_b32_e32 v100, 32, v153
	v_pk_mul_f32 v[98:99], v[92:93], v[150:151] op_sel_hi:[1,0]
	v_pk_mul_f32 v[92:93], v[90:91], v[150:151] op_sel_hi:[1,0]
	v_cvt_pk_bf16_f32 v90, v94, v95
	v_mad_i64_i32 v[94:95], s[56:57], v100, s63, 0
	v_lshl_add_u64 v[94:95], v[94:95], 1, s[44:45]
	v_cvt_pk_bf16_f32 v91, v96, v97
	v_cvt_pk_bf16_f32 v92, v92, v93
	v_cvt_pk_bf16_f32 v93, v98, v99
	v_lshl_add_u64 v[94:95], v[94:95], 0, v[122:123]
	global_store_dwordx4 v[94:95], v[90:93], off
	v_pk_mul_f32 v[88:89], v[88:89], v[150:151] op_sel_hi:[1,0]
	v_pk_mul_f32 v[86:87], v[86:87], v[150:151] op_sel_hi:[1,0]
	v_pk_mul_f32 v[90:91], v[84:85], v[150:151] op_sel_hi:[1,0]
	v_pk_mul_f32 v[84:85], v[82:83], v[150:151] op_sel_hi:[1,0]
	v_cvt_pk_bf16_f32 v82, v86, v87
	v_cvt_pk_bf16_f32 v83, v88, v89
	v_cvt_pk_bf16_f32 v84, v84, v85
	v_cvt_pk_bf16_f32 v85, v90, v91
	global_store_dwordx4 v[94:95], v[82:85], off offset:256
	v_pk_mul_f32 v[78:79], v[78:79], v[148:149] op_sel_hi:[1,0]
	v_pk_mul_f32 v[80:81], v[80:81], v[148:149] op_sel_hi:[1,0]
	v_or_b32_e32 v84, 48, v153
	v_pk_mul_f32 v[82:83], v[76:77], v[148:149] op_sel_hi:[1,0]
	v_pk_mul_f32 v[76:77], v[74:75], v[148:149] op_sel_hi:[1,0]
	v_cvt_pk_bf16_f32 v74, v78, v79
	v_mad_i64_i32 v[78:79], s[56:57], v84, s63, 0
	v_lshl_add_u64 v[78:79], v[78:79], 1, s[44:45]
	v_cvt_pk_bf16_f32 v75, v80, v81
; __device__ __forceinline__ unsigned pk2(float lo, float hi) { f32x2 v = {lo, hi}; bf16x2_t b = __builtin_convertvector(v, bf16x2_t); return __builtin_bit_cast(unsigned, b); }
; #define PG8_WAIT_V(n) asm volatile("s_waitcnt vmcnt(" #n ")" ::: "memory")
; #define PG8_BAR __builtin_amdgcn_s_barrier()
;     __device__ __forceinline__ void operator()(const AccT& acc, const Unit& u, int wr, int wc, int fr, int fq) const {
;     ...
;             for (int m = 0; m < 4; ++m) {
;                 const int row = row0 + ai * HALF + m * 16;
;                 const float rs = rsv[ai * 4 + m];
; #pragma unroll
;                 for (int bj = 0; bj < 2; ++bj) {
;                     const f32x4 v0 = acc[ai][bj][m][0] * rs, v1 = acc[ai][bj][m][1] * rs;
;                     u32x4 w; w.x = pk2(v0[0], v0[1]); w.y = pk2(v0[2], v0[3]); w.z = pk2(v1[0], v1[1]); w.w = pk2(v1[2], v1[3]);
;                     *(u32x4*)(out + (size_t)row * ldo + col0 + bj * HALF) = w;
;                 }
;             }
; template <class Epi>
; __device__ __forceinline__ void gemm_phase(LAS unsigned char* lds, const Gemm g, const StaticOrder& S, const Epi& E) {
;     ...
;     PG8_WAIT_V(0);
;     if (wr == 0) PG8_BAR;
;     PG8_BAR;
	v_cvt_pk_bf16_f32 v76, v76, v77
	v_cvt_pk_bf16_f32 v77, v82, v83
	v_lshl_add_u64 v[78:79], v[78:79], 0, v[122:123]
	global_store_dwordx4 v[78:79], v[74:77], off
	v_pk_mul_f32 v[72:73], v[72:73], v[148:149] op_sel_hi:[1,0]
	v_pk_mul_f32 v[70:71], v[70:71], v[148:149] op_sel_hi:[1,0]
	v_pk_mul_f32 v[74:75], v[68:69], v[148:149] op_sel_hi:[1,0]
	v_pk_mul_f32 v[68:69], v[66:67], v[148:149] op_sel_hi:[1,0]
	v_cvt_pk_bf16_f32 v66, v70, v71
	v_cvt_pk_bf16_f32 v67, v72, v73
	v_cvt_pk_bf16_f32 v68, v68, v69
	v_cvt_pk_bf16_f32 v69, v74, v75
	global_store_dwordx4 v[78:79], v[66:69], off offset:256
	v_pk_mul_f32 v[62:63], v[62:63], v[146:147] op_sel_hi:[1,0]
	v_pk_mul_f32 v[64:65], v[64:65], v[146:147] op_sel_hi:[1,0]
	v_add_u32_e32 v68, 0x80, v153
	v_pk_mul_f32 v[66:67], v[60:61], v[146:147] op_sel_hi:[1,0]
	v_pk_mul_f32 v[60:61], v[58:59], v[146:147] op_sel_hi:[1,0]
	v_cvt_pk_bf16_f32 v58, v62, v63
	v_mad_i64_i32 v[62:63], s[56:57], v68, s63, 0
	v_lshl_add_u64 v[62:63], v[62:63], 1, s[44:45]
	v_cvt_pk_bf16_f32 v59, v64, v65
	v_cvt_pk_bf16_f32 v60, v60, v61
	v_cvt_pk_bf16_f32 v61, v66, v67
	v_lshl_add_u64 v[62:63], v[62:63], 0, v[122:123]
	global_store_dwordx4 v[62:63], v[58:61], off
	v_pk_mul_f32 v[52:53], v[52:53], v[146:147] op_sel_hi:[1,0]
	v_pk_mul_f32 v[50:51], v[50:51], v[146:147] op_sel_hi:[1,0]
	v_pk_mul_f32 v[58:59], v[44:45], v[146:147] op_sel_hi:[1,0]
	v_pk_mul_f32 v[44:45], v[42:43], v[146:147] op_sel_hi:[1,0]
	v_cvt_pk_bf16_f32 v42, v50, v51
	v_cvt_pk_bf16_f32 v43, v52, v53
	v_cvt_pk_bf16_f32 v44, v44, v45
	v_cvt_pk_bf16_f32 v45, v58, v59
	global_store_dwordx4 v[62:63], v[42:45], off offset:256
	v_add_u32_e32 v50, 0x90, v153
	v_pk_mul_f32 v[46:47], v[46:47], v[144:145] op_sel_hi:[1,0]
	v_pk_mul_f32 v[44:45], v[56:57], v[144:145] op_sel_hi:[1,0]
	v_pk_mul_f32 v[42:43], v[54:55], v[144:145] op_sel_hi:[1,0]
	v_pk_mul_f32 v[48:49], v[48:49], v[144:145] op_sel_hi:[1,0]
	v_cvt_pk_bf16_f32 v42, v42, v43
	v_cvt_pk_bf16_f32 v43, v44, v45
	v_cvt_pk_bf16_f32 v44, v46, v47
	v_mad_i64_i32 v[46:47], s[56:57], v50, s63, 0
	v_lshl_add_u64 v[46:47], v[46:47], 1, s[44:45]
	v_cvt_pk_bf16_f32 v45, v48, v49
	v_lshl_add_u64 v[46:47], v[46:47], 0, v[122:123]
	global_store_dwordx4 v[46:47], v[42:45], off
	v_pk_mul_f32 v[36:37], v[36:37], v[144:145] op_sel_hi:[1,0]
	v_pk_mul_f32 v[34:35], v[34:35], v[144:145] op_sel_hi:[1,0]
	v_pk_mul_f32 v[42:43], v[28:29], v[144:145] op_sel_hi:[1,0]
	v_pk_mul_f32 v[28:29], v[26:27], v[144:145] op_sel_hi:[1,0]
	v_cvt_pk_bf16_f32 v26, v34, v35
	v_cvt_pk_bf16_f32 v27, v36, v37
	v_cvt_pk_bf16_f32 v28, v28, v29
	v_cvt_pk_bf16_f32 v29, v42, v43
	global_store_dwordx4 v[46:47], v[26:29], off offset:256
	v_add_u32_e32 v34, 0xa0, v153
	v_pk_mul_f32 v[30:31], v[30:31], v[142:143] op_sel_hi:[1,0]
	v_pk_mul_f32 v[28:29], v[40:41], v[142:143] op_sel_hi:[1,0]
	v_pk_mul_f32 v[26:27], v[38:39], v[142:143] op_sel_hi:[1,0]
	v_pk_mul_f32 v[32:33], v[32:33], v[142:143] op_sel_hi:[1,0]
	v_cvt_pk_bf16_f32 v26, v26, v27
	v_cvt_pk_bf16_f32 v27, v28, v29
	v_cvt_pk_bf16_f32 v28, v30, v31
	v_mad_i64_i32 v[30:31], s[56:57], v34, s63, 0
	v_lshl_add_u64 v[30:31], v[30:31], 1, s[44:45]
	v_cvt_pk_bf16_f32 v29, v32, v33
	v_lshl_add_u64 v[30:31], v[30:31], 0, v[122:123]
	global_store_dwordx4 v[30:31], v[26:29], off
	v_pk_mul_f32 v[20:21], v[20:21], v[142:143] op_sel_hi:[1,0]
	v_pk_mul_f32 v[18:19], v[18:19], v[142:143] op_sel_hi:[1,0]
	v_pk_mul_f32 v[26:27], v[12:13], v[142:143] op_sel_hi:[1,0]
	v_pk_mul_f32 v[12:13], v[10:11], v[142:143] op_sel_hi:[1,0]
	v_cvt_pk_bf16_f32 v10, v18, v19
	v_cvt_pk_bf16_f32 v11, v20, v21
	v_cvt_pk_bf16_f32 v12, v12, v13
	v_cvt_pk_bf16_f32 v13, v26, v27
	global_store_dwordx4 v[30:31], v[10:13], off offset:256
	v_add_u32_e32 v18, 0xb0, v153
	v_pk_mul_f32 v[14:15], v[14:15], v[140:141] op_sel_hi:[1,0]
	v_pk_mul_f32 v[12:13], v[24:25], v[140:141] op_sel_hi:[1,0]
	v_pk_mul_f32 v[10:11], v[22:23], v[140:141] op_sel_hi:[1,0]
	v_pk_mul_f32 v[16:17], v[16:17], v[140:141] op_sel_hi:[1,0]
	v_cvt_pk_bf16_f32 v10, v10, v11
	v_cvt_pk_bf16_f32 v11, v12, v13
	v_cvt_pk_bf16_f32 v12, v14, v15
	v_mad_i64_i32 v[14:15], s[56:57], v18, s63, 0
	v_lshl_add_u64 v[14:15], v[14:15], 1, s[44:45]
	v_cvt_pk_bf16_f32 v13, v16, v17
	v_lshl_add_u64 v[14:15], v[14:15], 0, v[122:123]
	global_store_dwordx4 v[14:15], v[10:13], off
	v_pk_mul_f32 v[8:9], v[8:9], v[140:141] op_sel_hi:[1,0]
	v_pk_mul_f32 v[6:7], v[6:7], v[140:141] op_sel_hi:[1,0]
	v_pk_mul_f32 v[10:11], v[4:5], v[140:141] op_sel_hi:[1,0]
	v_pk_mul_f32 v[4:5], v[2:3], v[140:141] op_sel_hi:[1,0]
	v_cvt_pk_bf16_f32 v2, v6, v7
	v_cvt_pk_bf16_f32 v3, v8, v9
	v_cvt_pk_bf16_f32 v4, v4, v5
	v_cvt_pk_bf16_f32 v5, v10, v11
	s_mov_b64 s[56:57], s[50:51]
	global_store_dwordx4 v[14:15], v[2:5], off offset:256
	s_cbranch_vccz .LBB0_61
	s_waitcnt vmcnt(0)
	s_cmpk_gt_u32 s64, 0xff
	s_cbranch_scc1 .LBB0_68
	s_barrier

; #define PG8_STAGE(bufoff, gbase, voff) do { _Pragma("unroll") for (int _i = 0; _i < 2; ++_i) \
;         __builtin_amdgcn_global_load_lds((const unsigned*)((const char*)(gbase) + (voff)[_i]), (LAS unsigned*)(lds + (bufoff) + ldsw + _i * 8192), 16, 0, 0); } while (0)
; #define PG8_LDA(dst, b, h) do { _Pragma("unroll") for (int m = 0; m < 4; ++m) _Pragma("unroll") for (int k = 0; k < 2; ++k) dst[m][k] = *(const LAS bf16x8*)(lds + PG8_SA(b, h) + aoff + m * 2048 + k * 1024); } while (0)
; #define PG8_LDB(dst, b, h) do { _Pragma("unroll") for (int n = 0; n < 2; ++n) _Pragma("unroll") for (int k = 0; k < 2; ++k) dst[n][k] = *(const LAS bf16x8*)(lds + PG8_SB(b, h) + boff + n * 2048 + k * 1024); } while (0)
; #define PG8_MMA(ai, bj, At, Bt) do { __builtin_amdgcn_s_setprio(1); _Pragma("unroll") for (int m = 0; m < 4; ++m) _Pragma("unroll") for (int n = 0; n < 2; ++n) _Pragma("unroll") for (int k = 0; k < 2; ++k) \
;         acc[ai][bj][m][n] = __builtin_amdgcn_mfma_f32_16x16x32_bf16(Bt[n][k], At[m][k], acc[ai][bj][m][n], 0, 0, 0); __builtin_amdgcn_s_setprio(0); } while (0)
; #define PG8_WAIT_L(n) asm volatile("s_waitcnt lgkmcnt(" #n ")" ::: "memory")
; #define PG8_BAR __builtin_amdgcn_s_barrier()
; #define PG8_SCHED __builtin_amdgcn_sched_barrier(0)
; template <class Epi>
; __device__ __forceinline__ void gemm_phase(LAS unsigned char* lds, const Gemm g, const StaticOrder& S, const Epi& E) {
;     ...
;         for (int t = 0; t < nt; t += 2) {
;             const bool last = (t == nt - 2);
;             const char* a1 = cA + (size_t)(t + 1) * kstep;
;             const char* a2 = last ? nA : cA + (size_t)(t + 2) * kstep; const char* b2 = last ? nB : cB + (size_t)(t + 2) * kstep;
;             const char* a3 = a2 + kstep; const char* b3 = b2 + kstep;
;             PG8_LDB(B0, 0, 0); PG8_SCHED; PG8_LDA(At, 0, 0); PG8_STAGE(PG8_SA(1, 1), a1 + hstep, voffA);
;             PG8_WAIT_L(8); PG8_BAR; PG8_WAIT_L(0); PG8_MMA(0, 0, At, B0); PG8_BAR; PG8_SCHED;
;     ...
; #pragma unroll
;         for (int a = 0; a < 2; ++a)
; #pragma unroll
;             for (int b = 0; b < 2; ++b)
; #pragma unroll
;                 for (int m = 0; m < 4; ++m)
; #pragma unroll
;                     for (int n = 0; n < 2; ++n) acc[a][b][m][n] = (f32x4){0.f, 0.f, 0.f, 0.f};
;         cur = nxt; cA = nA; cB = nB; ++ui;
.LBB0_76:
	s_ashr_i32 s49, s48, 31
	v_cmp_lt_i64_e64 s[58:59], s[50:51], 4
	s_lshl_b64 s[50:51], s[48:49], 20
	s_add_u32 s50, s36, s50
	s_addc_u32 s51, s37, s51
	s_and_b64 s[52:53], s[58:59], exec
	s_cselect_b32 s49, s51, s55
	s_cselect_b32 s76, s50, s54
	s_ashr_i32 s47, s46, 31
	s_lshl_b64 s[52:53], s[46:47], 20
	s_add_u32 s52, s61, s52
	s_addc_u32 s53, s63, s53
	s_and_b64 s[58:59], s[58:59], exec
	s_cselect_b32 s47, s53, s57
	s_cselect_b32 s77, s52, s56
	s_add_u32 s54, s54, 0x80080
	s_addc_u32 s55, s55, 0
	s_add_u32 s78, s56, 0x100
	v_mov_b32_e32 v2, 0
	s_addc_u32 s79, s57, 0
	s_mov_b32 s80, -2
	v_mov_b32_e32 v3, v2
	v_mov_b32_e32 v4, v2
	v_mov_b32_e32 v5, v2
	v_mov_b32_e32 v6, v2
	v_mov_b32_e32 v7, v2
	v_mov_b32_e32 v8, v2
	v_mov_b32_e32 v9, v2
	v_mov_b32_e32 v10, v2
	v_mov_b32_e32 v11, v2
	v_mov_b32_e32 v12, v2
	v_mov_b32_e32 v13, v2
	v_mov_b32_e32 v14, v2
	v_mov_b32_e32 v15, v2
	v_mov_b32_e32 v16, v2
	v_mov_b32_e32 v17, v2
	v_mov_b32_e32 v26, v2
	v_mov_b32_e32 v27, v2
	v_mov_b32_e32 v28, v2
	v_mov_b32_e32 v29, v2
	v_mov_b32_e32 v30, v2
	v_mov_b32_e32 v31, v2
	v_mov_b32_e32 v32, v2
	v_mov_b32_e32 v33, v2
	v_mov_b32_e32 v42, v2
	v_mov_b32_e32 v43, v2
	v_mov_b32_e32 v44, v2
	v_mov_b32_e32 v45, v2
	v_mov_b32_e32 v46, v2
	v_mov_b32_e32 v47, v2
	v_mov_b32_e32 v48, v2
	v_mov_b32_e32 v49, v2
	v_mov_b32_e32 v18, v2
	v_mov_b32_e32 v19, v2
	v_mov_b32_e32 v20, v2
	v_mov_b32_e32 v21, v2
	v_mov_b32_e32 v22, v2
	v_mov_b32_e32 v23, v2
	v_mov_b32_e32 v24, v2
	v_mov_b32_e32 v25, v2
	v_mov_b32_e32 v34, v2
	v_mov_b32_e32 v35, v2
	v_mov_b32_e32 v36, v2
	v_mov_b32_e32 v37, v2
	v_mov_b32_e32 v38, v2
	v_mov_b32_e32 v39, v2
	v_mov_b32_e32 v40, v2
	v_mov_b32_e32 v41, v2
	v_mov_b32_e32 v50, v2
	v_mov_b32_e32 v51, v2
	v_mov_b32_e32 v52, v2
	v_mov_b32_e32 v53, v2
	v_mov_b32_e32 v54, v2
	v_mov_b32_e32 v55, v2
	v_mov_b32_e32 v56, v2
	v_mov_b32_e32 v57, v2
	v_mov_b32_e32 v58, v2
	v_mov_b32_e32 v59, v2
	v_mov_b32_e32 v60, v2
	v_mov_b32_e32 v61, v2
	v_mov_b32_e32 v62, v2
	v_mov_b32_e32 v63, v2
	v_mov_b32_e32 v64, v2
	v_mov_b32_e32 v65, v2
	v_mov_b32_e32 v66, v2
	v_mov_b32_e32 v67, v2
	v_mov_b32_e32 v68, v2
	v_mov_b32_e32 v69, v2
	v_mov_b32_e32 v70, v2
	v_mov_b32_e32 v71, v2
	v_mov_b32_e32 v72, v2
	v_mov_b32_e32 v73, v2
	v_mov_b32_e32 v74, v2
	v_mov_b32_e32 v75, v2
	v_mov_b32_e32 v76, v2
	v_mov_b32_e32 v77, v2
	v_mov_b32_e32 v78, v2
	v_mov_b32_e32 v79, v2
	v_mov_b32_e32 v80, v2
	v_mov_b32_e32 v81, v2
	v_mov_b32_e32 v90, v2
	v_mov_b32_e32 v91, v2
	v_mov_b32_e32 v92, v2
	v_mov_b32_e32 v93, v2
	v_mov_b32_e32 v94, v2
	v_mov_b32_e32 v95, v2
	v_mov_b32_e32 v96, v2
	v_mov_b32_e32 v97, v2
	v_mov_b32_e32 v106, v2
	v_mov_b32_e32 v107, v2
	v_mov_b32_e32 v108, v2
	v_mov_b32_e32 v109, v2
	v_mov_b32_e32 v110, v2
	v_mov_b32_e32 v111, v2
	v_mov_b32_e32 v112, v2
	v_mov_b32_e32 v113, v2
	v_mov_b32_e32 v82, v2
	v_mov_b32_e32 v83, v2
	v_mov_b32_e32 v84, v2
	v_mov_b32_e32 v85, v2
	v_mov_b32_e32 v86, v2
	v_mov_b32_e32 v87, v2
	v_mov_b32_e32 v88, v2
	v_mov_b32_e32 v89, v2
	v_mov_b32_e32 v98, v2
	v_mov_b32_e32 v99, v2
	v_mov_b32_e32 v100, v2
	v_mov_b32_e32 v101, v2
	v_mov_b32_e32 v102, v2
	v_mov_b32_e32 v103, v2
	v_mov_b32_e32 v104, v2
	v_mov_b32_e32 v105, v2
	v_mov_b32_e32 v114, v2
	v_mov_b32_e32 v115, v2
	v_mov_b32_e32 v116, v2
	v_mov_b32_e32 v117, v2
	v_mov_b32_e32 v118, v2
	v_mov_b32_e32 v119, v2
	v_mov_b32_e32 v120, v2
	v_mov_b32_e32 v121, v2
	v_mov_b32_e32 v122, v2
	v_mov_b32_e32 v123, v2
	v_mov_b32_e32 v124, v2
	v_mov_b32_e32 v125, v2
	v_mov_b32_e32 v126, v2
	v_mov_b32_e32 v127, v2
	v_mov_b32_e32 v128, v2
	v_mov_b32_e32 v129, v2
	v_add_u32_e32 v156, 0x10000, v141
	ds_read_b128 v[144:147], v156
	ds_read_b128 v[148:151], v156 offset:1024
	ds_read_b128 v[152:155], v156 offset:2048
	ds_read_b128 v[156:159], v156 offset:3072
.LBB0_77:
	s_add_u32 s56, s54, 0xfff80080
	s_addc_u32 s57, s55, -1
	s_add_i32 s81, 0, 0x10000
	s_cmp_eq_u32 s80, 28
	s_cselect_b32 s59, s49, s57
	s_cselect_b32 s58, s76, s56
	s_cselect_b32 s57, s47, s79
	s_cselect_b32 s56, s77, s78
	s_add_i32 m0, s65, 0xc000
	ds_read_b128 v[160:163], v143
	ds_read_b128 v[164:167], v143 offset:1024
	ds_read_b128 v[168:171], v143 offset:2048
	ds_read_b128 v[172:175], v143 offset:3072
	ds_read_b128 v[176:179], v143 offset:4096
	ds_read_b128 v[180:183], v143 offset:5120
	ds_read_b128 v[184:187], v143 offset:6144
	ds_read_b128 v[188:191], v143 offset:7168
	global_load_lds_dwordx4 v136, s[54:55]
	s_add_i32 m0, s65, 0xe000
	s_nop 0
	global_load_lds_dwordx4 v138, s[54:55]
	s_waitcnt lgkmcnt(8)
	s_barrier
	s_waitcnt lgkmcnt(0)
	s_setprio 1
	v_mfma_f32_16x16x32_bf16 v[126:129], v[144:147], v[160:163], v[126:129]
	v_mfma_f32_16x16x32_bf16 v[122:125], v[152:155], v[160:163], v[122:125]
	v_mfma_f32_16x16x32_bf16 v[118:121], v[144:147], v[168:171], v[118:121]
	v_mfma_f32_16x16x32_bf16 v[114:117], v[152:155], v[168:171], v[114:117]
	v_mfma_f32_16x16x32_bf16 v[102:105], v[144:147], v[176:179], v[102:105]
	v_mfma_f32_16x16x32_bf16 v[98:101], v[152:155], v[176:179], v[98:101]
	v_mfma_f32_16x16x32_bf16 v[86:89], v[144:147], v[184:187], v[86:89]
	v_mfma_f32_16x16x32_bf16 v[82:85], v[152:155], v[184:187], v[82:85]
	v_mfma_f32_16x16x32_bf16 v[126:129], v[148:151], v[164:167], v[126:129]
	v_mfma_f32_16x16x32_bf16 v[122:125], v[156:159], v[164:167], v[122:125]
	v_mfma_f32_16x16x32_bf16 v[118:121], v[148:151], v[172:175], v[118:121]
	v_mfma_f32_16x16x32_bf16 v[114:117], v[156:159], v[172:175], v[114:117]
	v_mfma_f32_16x16x32_bf16 v[102:105], v[148:151], v[180:183], v[102:105]
	v_mfma_f32_16x16x32_bf16 v[98:101], v[156:159], v[180:183], v[98:101]
	v_mfma_f32_16x16x32_bf16 v[86:89], v[148:151], v[188:191], v[86:89]
	v_mfma_f32_16x16x32_bf16 v[82:85], v[156:159], v[188:191], v[82:85]
	s_setprio 0
	s_barrier
; #define PG8_STAGE(bufoff, gbase, voff) do { _Pragma("unroll") for (int _i = 0; _i < 2; ++_i) \
;         __builtin_amdgcn_global_load_lds((const unsigned*)((const char*)(gbase) + (voff)[_i]), (LAS unsigned*)(lds + (bufoff) + ldsw + _i * 8192), 16, 0, 0); } while (0)
; #define PG8_LDA(dst, b, h) do { _Pragma("unroll") for (int m = 0; m < 4; ++m) _Pragma("unroll") for (int k = 0; k < 2; ++k) dst[m][k] = *(const LAS bf16x8*)(lds + PG8_SA(b, h) + aoff + m * 2048 + k * 1024); } while (0)
; #define PG8_LDB(dst, b, h) do { _Pragma("unroll") for (int n = 0; n < 2; ++n) _Pragma("unroll") for (int k = 0; k < 2; ++k) dst[n][k] = *(const LAS bf16x8*)(lds + PG8_SB(b, h) + boff + n * 2048 + k * 1024); } while (0)
; #define PG8_MMA(ai, bj, At, Bt) do { __builtin_amdgcn_s_setprio(1); _Pragma("unroll") for (int m = 0; m < 4; ++m) _Pragma("unroll") for (int n = 0; n < 2; ++n) _Pragma("unroll") for (int k = 0; k < 2; ++k) \
;         acc[ai][bj][m][n] = __builtin_amdgcn_mfma_f32_16x16x32_bf16(Bt[n][k], At[m][k], acc[ai][bj][m][n], 0, 0, 0); __builtin_amdgcn_s_setprio(0); } while (0)
; #define PG8_WAIT_V(n) asm volatile("s_waitcnt vmcnt(" #n ")" ::: "memory")
; #define PG8_WAIT_L(n) asm volatile("s_waitcnt lgkmcnt(" #n ")" ::: "memory")
; #define PG8_BAR __builtin_amdgcn_s_barrier()
; #define PG8_SCHED __builtin_amdgcn_sched_barrier(0)
; template <class Epi>
; __device__ __forceinline__ void gemm_phase(LAS unsigned char* lds, const Gemm g, const StaticOrder& S, const Epi& E) {
;     ...
;             PG8_LDB(B0, 0, 0); PG8_SCHED; PG8_LDA(At, 0, 0); PG8_STAGE(PG8_SA(1, 1), a1 + hstep, voffA);
;             PG8_WAIT_L(8); PG8_BAR; PG8_WAIT_L(0); PG8_MMA(0, 0, At, B0); PG8_BAR; PG8_SCHED;
;             PG8_LDB(B1, 0, 1); PG8_STAGE(PG8_SB(0, 0), b2, voffB);
;             PG8_BAR; PG8_WAIT_L(0); PG8_MMA(0, 1, At, B1); PG8_BAR;
;             PG8_LDA(At, 0, 1); PG8_STAGE(PG8_SA(0, 0), a2, voffA);
;             PG8_BAR; PG8_WAIT_L(0); PG8_MMA(1, 0, At, B0); PG8_BAR; PG8_SCHED;
;             PG8_STAGE(PG8_SB(0, 1), b2 + hstep, voffB);
;             PG8_WAIT_V(6); PG8_BAR; PG8_MMA(1, 1, At, B1); PG8_BAR;
;             PG8_LDB(B0, 1, 0); PG8_SCHED; PG8_LDA(At, 1, 0); PG8_STAGE(PG8_SA(0, 1), a2 + hstep, voffA);
	s_add_i32 s84, 0, 0x14000
	v_add_u32_e32 v200, s84, v141
	s_add_i32 s81, s81, s64
	ds_read_b128 v[192:195], v200
	ds_read_b128 v[196:199], v200 offset:1024
	ds_read_b128 v[208:211], v200 offset:2048
	ds_read_b128 v[212:215], v200 offset:3072
	s_mov_b32 m0, s81
	s_add_u32 s98, s56, s22
	s_addc_u32 s99, s57, s23
	global_load_lds_dwordx4 v0, s[56:57]
	s_add_i32 m0, s81, 0x2000
	s_nop 0
	global_load_lds_dwordx4 v130, s[56:57]
	s_barrier
	s_waitcnt lgkmcnt(0)
	s_setprio 1
	v_mfma_f32_16x16x32_bf16 v[110:113], v[192:195], v[160:163], v[110:113]
	v_mfma_f32_16x16x32_bf16 v[106:109], v[208:211], v[160:163], v[106:109]
	v_mfma_f32_16x16x32_bf16 v[94:97], v[192:195], v[168:171], v[94:97]
	v_mfma_f32_16x16x32_bf16 v[90:93], v[208:211], v[168:171], v[90:93]
	v_mfma_f32_16x16x32_bf16 v[78:81], v[192:195], v[176:179], v[78:81]
	v_mfma_f32_16x16x32_bf16 v[74:77], v[208:211], v[176:179], v[74:77]
	v_mfma_f32_16x16x32_bf16 v[70:73], v[192:195], v[184:187], v[70:73]
	v_mfma_f32_16x16x32_bf16 v[66:69], v[208:211], v[184:187], v[66:69]
	v_mfma_f32_16x16x32_bf16 v[110:113], v[196:199], v[164:167], v[110:113]
	v_mfma_f32_16x16x32_bf16 v[106:109], v[212:215], v[164:167], v[106:109]
	v_mfma_f32_16x16x32_bf16 v[94:97], v[196:199], v[172:175], v[94:97]
	v_mfma_f32_16x16x32_bf16 v[90:93], v[212:215], v[172:175], v[90:93]
	v_mfma_f32_16x16x32_bf16 v[78:81], v[196:199], v[180:183], v[78:81]
	v_mfma_f32_16x16x32_bf16 v[74:77], v[212:215], v[180:183], v[74:77]
	v_mfma_f32_16x16x32_bf16 v[70:73], v[196:199], v[188:191], v[70:73]
	v_mfma_f32_16x16x32_bf16 v[66:69], v[212:215], v[188:191], v[66:69]
	s_setprio 0
	s_mov_b32 m0, s65
	s_add_u32 s100, s58, s22
	s_addc_u32 s101, s59, s23
	s_barrier
	ds_read_b128 v[160:163], v143 offset:16384
	ds_read_b128 v[164:167], v143 offset:17408
	ds_read_b128 v[168:171], v143 offset:18432
	ds_read_b128 v[172:175], v143 offset:19456
	ds_read_b128 v[176:179], v143 offset:20480
	ds_read_b128 v[180:183], v143 offset:21504
	ds_read_b128 v[184:187], v143 offset:22528
	ds_read_b128 v[188:191], v143 offset:23552
	global_load_lds_dwordx4 v134, s[58:59]
	s_mov_b32 m0, s68
	s_nop 0
	global_load_lds_dwordx4 v132, s[58:59]
	s_waitcnt vmcnt(10)
	s_barrier
	s_waitcnt lgkmcnt(0)
	s_setprio 1
	v_mfma_f32_16x16x32_bf16 v[62:65], v[144:147], v[160:163], v[62:65]
	v_mfma_f32_16x16x32_bf16 v[58:61], v[152:155], v[160:163], v[58:61]
	v_mfma_f32_16x16x32_bf16 v[54:57], v[144:147], v[168:171], v[54:57]
	v_mfma_f32_16x16x32_bf16 v[50:53], v[152:155], v[168:171], v[50:53]
	v_mfma_f32_16x16x32_bf16 v[38:41], v[144:147], v[176:179], v[38:41]
	v_mfma_f32_16x16x32_bf16 v[34:37], v[152:155], v[176:179], v[34:37]
	v_mfma_f32_16x16x32_bf16 v[22:25], v[144:147], v[184:187], v[22:25]
	v_mfma_f32_16x16x32_bf16 v[18:21], v[152:155], v[184:187], v[18:21]
	v_mfma_f32_16x16x32_bf16 v[62:65], v[148:151], v[164:167], v[62:65]
	v_mfma_f32_16x16x32_bf16 v[58:61], v[156:159], v[164:167], v[58:61]
	v_mfma_f32_16x16x32_bf16 v[54:57], v[148:151], v[172:175], v[54:57]
	v_mfma_f32_16x16x32_bf16 v[50:53], v[156:159], v[172:175], v[50:53]
	v_mfma_f32_16x16x32_bf16 v[38:41], v[148:151], v[180:183], v[38:41]
	v_mfma_f32_16x16x32_bf16 v[34:37], v[156:159], v[180:183], v[34:37]
	v_mfma_f32_16x16x32_bf16 v[22:25], v[148:151], v[188:191], v[22:25]
	v_mfma_f32_16x16x32_bf16 v[18:21], v[156:159], v[188:191], v[18:21]
	s_setprio 0
	s_barrier
	v_add_u32_e32 v156, 0x18000, v141
	ds_read_b128 v[144:147], v156
	ds_read_b128 v[148:151], v156 offset:1024
	ds_read_b128 v[152:155], v156 offset:2048
	ds_read_b128 v[156:159], v156 offset:3072
	s_add_u32 s82, s56, 0x80000
	s_addc_u32 s83, s57, 0
	s_add_i32 s81, s84, s64
	s_mov_b32 m0, s81
	s_nop 0
	global_load_lds_dwordx4 v0, s[82:83]
	s_add_i32 m0, s81, 0x2000
	s_nop 0
	global_load_lds_dwordx4 v130, s[82:83]
	s_waitcnt vmcnt(6)
	s_barrier
	s_setprio 1
	v_mfma_f32_16x16x32_bf16 v[46:49], v[192:195], v[160:163], v[46:49]
	v_mfma_f32_16x16x32_bf16 v[42:45], v[208:211], v[160:163], v[42:45]
	v_mfma_f32_16x16x32_bf16 v[30:33], v[192:195], v[168:171], v[30:33]
	v_mfma_f32_16x16x32_bf16 v[26:29], v[208:211], v[168:171], v[26:29]
	v_mfma_f32_16x16x32_bf16 v[14:17], v[192:195], v[176:179], v[14:17]
	v_mfma_f32_16x16x32_bf16 v[10:13], v[208:211], v[176:179], v[10:13]
	v_mfma_f32_16x16x32_bf16 v[6:9], v[192:195], v[184:187], v[6:9]
	v_mfma_f32_16x16x32_bf16 v[2:5], v[208:211], v[184:187], v[2:5]
	v_mfma_f32_16x16x32_bf16 v[46:49], v[196:199], v[164:167], v[46:49]
	v_mfma_f32_16x16x32_bf16 v[42:45], v[212:215], v[164:167], v[42:45]
	v_mfma_f32_16x16x32_bf16 v[30:33], v[196:199], v[172:175], v[30:33]
	v_mfma_f32_16x16x32_bf16 v[26:29], v[212:215], v[172:175], v[26:29]
	v_mfma_f32_16x16x32_bf16 v[14:17], v[196:199], v[180:183], v[14:17]
	v_mfma_f32_16x16x32_bf16 v[10:13], v[212:215], v[180:183], v[10:13]
	v_mfma_f32_16x16x32_bf16 v[6:9], v[196:199], v[188:191], v[6:9]
	v_mfma_f32_16x16x32_bf16 v[2:5], v[212:215], v[188:191], v[2:5]
	s_setprio 0
	s_add_i32 s81, 0, 0x18000
	s_barrier
	s_add_u32 s58, s58, 0x80000
	s_addc_u32 s59, s59, 0
	s_mov_b32 m0, s69
	ds_read_b128 v[160:163], v143 offset:32768
	ds_read_b128 v[164:167], v143 offset:33792
	ds_read_b128 v[168:171], v143 offset:34816
	ds_read_b128 v[172:175], v143 offset:35840
	ds_read_b128 v[176:179], v143 offset:36864
	ds_read_b128 v[180:183], v143 offset:37888
	ds_read_b128 v[184:187], v143 offset:38912
	ds_read_b128 v[188:191], v143 offset:39936
	global_load_lds_dwordx4 v134, s[58:59]
	s_mov_b32 m0, s70
	s_nop 0
	global_load_lds_dwordx4 v132, s[58:59]
	s_waitcnt lgkmcnt(8)
	s_barrier
; #define PG8_STAGE(bufoff, gbase, voff) do { _Pragma("unroll") for (int _i = 0; _i < 2; ++_i) \
;         __builtin_amdgcn_global_load_lds((const unsigned*)((const char*)(gbase) + (voff)[_i]), (LAS unsigned*)(lds + (bufoff) + ldsw + _i * 8192), 16, 0, 0); } while (0)
; #define PG8_LDA(dst, b, h) do { _Pragma("unroll") for (int m = 0; m < 4; ++m) _Pragma("unroll") for (int k = 0; k < 2; ++k) dst[m][k] = *(const LAS bf16x8*)(lds + PG8_SA(b, h) + aoff + m * 2048 + k * 1024); } while (0)
; #define PG8_LDB(dst, b, h) do { _Pragma("unroll") for (int n = 0; n < 2; ++n) _Pragma("unroll") for (int k = 0; k < 2; ++k) dst[n][k] = *(const LAS bf16x8*)(lds + PG8_SB(b, h) + boff + n * 2048 + k * 1024); } while (0)
; #define PG8_MMA(ai, bj, At, Bt) do { __builtin_amdgcn_s_setprio(1); _Pragma("unroll") for (int m = 0; m < 4; ++m) _Pragma("unroll") for (int n = 0; n < 2; ++n) _Pragma("unroll") for (int k = 0; k < 2; ++k) \
;         acc[ai][bj][m][n] = __builtin_amdgcn_mfma_f32_16x16x32_bf16(Bt[n][k], At[m][k], acc[ai][bj][m][n], 0, 0, 0); __builtin_amdgcn_s_setprio(0); } while (0)
; #define PG8_WAIT_V(n) asm volatile("s_waitcnt vmcnt(" #n ")" ::: "memory")
; #define PG8_WAIT_L(n) asm volatile("s_waitcnt lgkmcnt(" #n ")" ::: "memory")
; #define PG8_BAR __builtin_amdgcn_s_barrier()
; #define PG8_SCHED __builtin_amdgcn_sched_barrier(0)
; template <class Epi>
; __device__ __forceinline__ void gemm_phase(LAS unsigned char* lds, const Gemm g, const StaticOrder& S, const Epi& E) {
;     ...
;             PG8_LDB(B0, 1, 0); PG8_SCHED; PG8_LDA(At, 1, 0); PG8_STAGE(PG8_SA(0, 1), a2 + hstep, voffA);
;             PG8_WAIT_L(8); PG8_BAR; PG8_WAIT_L(0); PG8_MMA(0, 0, At, B0); PG8_BAR; PG8_SCHED;
;             PG8_LDB(B1, 1, 1); PG8_STAGE(PG8_SB(1, 0), b3, voffB);
;             PG8_BAR; PG8_WAIT_L(0); PG8_MMA(0, 1, At, B1); PG8_BAR;
;             PG8_LDA(At, 1, 1); PG8_STAGE(PG8_SA(1, 0), a3, voffA);
;             PG8_BAR; PG8_WAIT_L(0); PG8_MMA(1, 0, At, B0); PG8_BAR; PG8_SCHED;
;             PG8_STAGE(PG8_SB(1, 1), b3 + hstep, voffB);
;             PG8_WAIT_V(6); PG8_BAR; PG8_MMA(1, 1, At, B1); PG8_BAR;
	s_waitcnt lgkmcnt(0)
	s_setprio 1
	v_mfma_f32_16x16x32_bf16 v[126:129], v[144:147], v[160:163], v[126:129]
	v_mfma_f32_16x16x32_bf16 v[122:125], v[152:155], v[160:163], v[122:125]
	v_mfma_f32_16x16x32_bf16 v[118:121], v[144:147], v[168:171], v[118:121]
	v_mfma_f32_16x16x32_bf16 v[114:117], v[152:155], v[168:171], v[114:117]
	v_mfma_f32_16x16x32_bf16 v[102:105], v[144:147], v[176:179], v[102:105]
	v_mfma_f32_16x16x32_bf16 v[98:101], v[152:155], v[176:179], v[98:101]
	v_mfma_f32_16x16x32_bf16 v[86:89], v[144:147], v[184:187], v[86:89]
	v_mfma_f32_16x16x32_bf16 v[82:85], v[152:155], v[184:187], v[82:85]
	v_mfma_f32_16x16x32_bf16 v[126:129], v[148:151], v[164:167], v[126:129]
	v_mfma_f32_16x16x32_bf16 v[122:125], v[156:159], v[164:167], v[122:125]
	v_mfma_f32_16x16x32_bf16 v[118:121], v[148:151], v[172:175], v[118:121]
	v_mfma_f32_16x16x32_bf16 v[114:117], v[156:159], v[172:175], v[114:117]
	v_mfma_f32_16x16x32_bf16 v[102:105], v[148:151], v[180:183], v[102:105]
	v_mfma_f32_16x16x32_bf16 v[98:101], v[156:159], v[180:183], v[98:101]
	v_mfma_f32_16x16x32_bf16 v[86:89], v[148:151], v[188:191], v[86:89]
	v_mfma_f32_16x16x32_bf16 v[82:85], v[156:159], v[188:191], v[82:85]
	s_setprio 0
	s_barrier
	s_add_i32 s58, 0, 0x1c000
	s_add_i32 s59, s81, s64
	v_add_u32_e32 v212, s58, v141
	s_mov_b32 m0, s59
	ds_read_b128 v[192:195], v212
	ds_read_b128 v[196:199], v212 offset:1024
	ds_read_b128 v[208:211], v212 offset:2048
	ds_read_b128 v[212:215], v212 offset:3072
	global_load_lds_dwordx4 v0, s[98:99]
	s_add_i32 m0, s59, 0x2000
	s_nop 0
	global_load_lds_dwordx4 v130, s[98:99]
	s_barrier
	s_waitcnt lgkmcnt(0)
	s_setprio 1
	v_mfma_f32_16x16x32_bf16 v[110:113], v[192:195], v[160:163], v[110:113]
	v_mfma_f32_16x16x32_bf16 v[106:109], v[208:211], v[160:163], v[106:109]
	v_mfma_f32_16x16x32_bf16 v[94:97], v[192:195], v[168:171], v[94:97]
	v_mfma_f32_16x16x32_bf16 v[90:93], v[208:211], v[168:171], v[90:93]
	v_mfma_f32_16x16x32_bf16 v[78:81], v[192:195], v[176:179], v[78:81]
	v_mfma_f32_16x16x32_bf16 v[74:77], v[208:211], v[176:179], v[74:77]
	v_mfma_f32_16x16x32_bf16 v[70:73], v[192:195], v[184:187], v[70:73]
	v_mfma_f32_16x16x32_bf16 v[66:69], v[208:211], v[184:187], v[66:69]
	v_mfma_f32_16x16x32_bf16 v[110:113], v[196:199], v[164:167], v[110:113]
	v_mfma_f32_16x16x32_bf16 v[106:109], v[212:215], v[164:167], v[106:109]
	v_mfma_f32_16x16x32_bf16 v[94:97], v[196:199], v[172:175], v[94:97]
	v_mfma_f32_16x16x32_bf16 v[90:93], v[212:215], v[172:175], v[90:93]
	v_mfma_f32_16x16x32_bf16 v[78:81], v[196:199], v[180:183], v[78:81]
	v_mfma_f32_16x16x32_bf16 v[74:77], v[212:215], v[180:183], v[74:77]
	v_mfma_f32_16x16x32_bf16 v[70:73], v[196:199], v[188:191], v[70:73]
	v_mfma_f32_16x16x32_bf16 v[66:69], v[212:215], v[188:191], v[66:69]
	s_setprio 0
	s_mov_b32 m0, s71
	s_barrier
	ds_read_b128 v[160:163], v143 offset:49152
	ds_read_b128 v[164:167], v143 offset:50176
	ds_read_b128 v[168:171], v143 offset:51200
	ds_read_b128 v[172:175], v143 offset:52224
	ds_read_b128 v[176:179], v143 offset:53248
	ds_read_b128 v[180:183], v143 offset:54272
	ds_read_b128 v[184:187], v143 offset:55296
	ds_read_b128 v[188:191], v143 offset:56320
	global_load_lds_dwordx4 v134, s[100:101]
	s_mov_b32 m0, s72
	s_nop 0
	global_load_lds_dwordx4 v132, s[100:101]
	s_waitcnt vmcnt(10)
	s_barrier
	s_waitcnt lgkmcnt(0)
	s_setprio 1
	v_mfma_f32_16x16x32_bf16 v[62:65], v[144:147], v[160:163], v[62:65]
	v_mfma_f32_16x16x32_bf16 v[58:61], v[152:155], v[160:163], v[58:61]
	v_mfma_f32_16x16x32_bf16 v[54:57], v[144:147], v[168:171], v[54:57]
	v_mfma_f32_16x16x32_bf16 v[50:53], v[152:155], v[168:171], v[50:53]
	v_mfma_f32_16x16x32_bf16 v[38:41], v[144:147], v[176:179], v[38:41]
	v_mfma_f32_16x16x32_bf16 v[34:37], v[152:155], v[176:179], v[34:37]
	v_mfma_f32_16x16x32_bf16 v[22:25], v[144:147], v[184:187], v[22:25]
	v_mfma_f32_16x16x32_bf16 v[18:21], v[152:155], v[184:187], v[18:21]
	v_mfma_f32_16x16x32_bf16 v[62:65], v[148:151], v[164:167], v[62:65]
	v_mfma_f32_16x16x32_bf16 v[58:61], v[156:159], v[164:167], v[58:61]
	v_mfma_f32_16x16x32_bf16 v[54:57], v[148:151], v[172:175], v[54:57]
	v_mfma_f32_16x16x32_bf16 v[50:53], v[156:159], v[172:175], v[50:53]
	v_mfma_f32_16x16x32_bf16 v[38:41], v[148:151], v[180:183], v[38:41]
	v_mfma_f32_16x16x32_bf16 v[34:37], v[156:159], v[180:183], v[34:37]
	v_mfma_f32_16x16x32_bf16 v[22:25], v[148:151], v[188:191], v[22:25]
	v_mfma_f32_16x16x32_bf16 v[18:21], v[156:159], v[188:191], v[18:21]
	s_setprio 0
	s_barrier
	v_add_u32_e32 v156, 0x10000, v141
	ds_read_b128 v[144:147], v156
	ds_read_b128 v[148:151], v156 offset:1024
	ds_read_b128 v[152:155], v156 offset:2048
	ds_read_b128 v[156:159], v156 offset:3072
	s_add_u32 s56, s56, 0x80080
	s_addc_u32 s57, s57, 0
	s_add_i32 s58, s58, s64
	s_mov_b32 m0, s58
	s_nop 0
	global_load_lds_dwordx4 v0, s[56:57]
	s_add_i32 m0, s58, 0x2000
	s_nop 0
	global_load_lds_dwordx4 v130, s[56:57]
	s_waitcnt vmcnt(6)
	s_barrier
	s_setprio 1
	v_mfma_f32_16x16x32_bf16 v[46:49], v[192:195], v[160:163], v[46:49]
	v_mfma_f32_16x16x32_bf16 v[42:45], v[208:211], v[160:163], v[42:45]
	v_mfma_f32_16x16x32_bf16 v[30:33], v[192:195], v[168:171], v[30:33]
	v_mfma_f32_16x16x32_bf16 v[26:29], v[208:211], v[168:171], v[26:29]
	v_mfma_f32_16x16x32_bf16 v[14:17], v[192:195], v[176:179], v[14:17]
	v_mfma_f32_16x16x32_bf16 v[10:13], v[208:211], v[176:179], v[10:13]
	v_mfma_f32_16x16x32_bf16 v[6:9], v[192:195], v[184:187], v[6:9]
	v_mfma_f32_16x16x32_bf16 v[2:5], v[208:211], v[184:187], v[2:5]
	v_mfma_f32_16x16x32_bf16 v[46:49], v[196:199], v[164:167], v[46:49]
	v_mfma_f32_16x16x32_bf16 v[42:45], v[212:215], v[164:167], v[42:45]
	v_mfma_f32_16x16x32_bf16 v[30:33], v[196:199], v[172:175], v[30:33]
	v_mfma_f32_16x16x32_bf16 v[26:29], v[212:215], v[172:175], v[26:29]
	v_mfma_f32_16x16x32_bf16 v[14:17], v[196:199], v[180:183], v[14:17]
	v_mfma_f32_16x16x32_bf16 v[10:13], v[212:215], v[180:183], v[10:13]
	v_mfma_f32_16x16x32_bf16 v[6:9], v[196:199], v[188:191], v[6:9]
	v_mfma_f32_16x16x32_bf16 v[2:5], v[212:215], v[188:191], v[2:5]
	s_setprio 0
	s_add_i32 s80, s80, 2
	s_add_u32 s54, s54, 0x100
	s_addc_u32 s55, s55, 0
	s_add_u32 s78, s78, 0x100
	s_addc_u32 s79, s79, 0
	s_cmp_gt_u32 s80, 29
	s_barrier
; __device__ __forceinline__ unsigned pk2(float lo, float hi) { f32x2 v = {lo, hi}; bf16x2_t b = __builtin_convertvector(v, bf16x2_t); return __builtin_bit_cast(unsigned, b); }
; #define PG8_WAIT_V(n) asm volatile("s_waitcnt vmcnt(" #n ")" ::: "memory")
; #define PG8_BAR __builtin_amdgcn_s_barrier()
;     __device__ __forceinline__ void operator()(const AccT& acc, const Unit& u, int wr, int wc, int fr, int fq) const {
;     ...
; #pragma unroll
;         for (int ai = 0; ai < 2; ++ai)
; #pragma unroll
;             for (int m = 0; m < 4; ++m) {
;                 const int row = row0 + ai * HALF + m * 16;
;                 const float rs = rsv[ai * 4 + m];
; #pragma unroll
;                 for (int bj = 0; bj < 2; ++bj) {
;                     const f32x4 v0 = acc[ai][bj][m][0] * rs, v1 = acc[ai][bj][m][1] * rs;
;                     u32x4 w; w.x = pk2(v0[0], v0[1]); w.y = pk2(v0[2], v0[3]); w.z = pk2(v1[0], v1[1]); w.w = pk2(v1[2], v1[3]);
;                     *(u32x4*)(out + (size_t)row * ldo + col0 + bj * HALF) = w;
;                 }
;             }
; template <class Epi>
; __device__ __forceinline__ void gemm_phase(LAS unsigned char* lds, const Gemm g, const StaticOrder& S, const Epi& E) {
;     ...
;     PG8_WAIT_V(0);
;     if (wr == 0) PG8_BAR;
;     PG8_BAR;
	s_cbranch_scc0 .LBB0_77
	s_waitcnt lgkmcnt(0)
	v_lshl_add_u32 v146, s74, 8, v140
	v_lshl_or_b32 v144, s75, 8, v142
	v_ashrrev_i32_e32 v147, 31, v146
	v_ashrrev_i32_e32 v145, 31, v144
	v_cvt_pk_bf16_f32 v126, v126, v127
	v_cvt_pk_bf16_f32 v127, v128, v129
	v_cvt_pk_bf16_f32 v128, v122, v123
	v_lshlrev_b64 v[122:123], 11, v[146:147]
	v_cvt_pk_bf16_f32 v129, v124, v125
	v_lshl_add_u64 v[122:123], s[42:43], 0, v[122:123]
	v_lshlrev_b64 v[124:125], 1, v[144:145]
	v_lshl_add_u64 v[122:123], v[122:123], 0, v[124:125]
	v_cvt_pk_bf16_f32 v110, v110, v111
	v_cvt_pk_bf16_f32 v111, v112, v113
	v_cvt_pk_bf16_f32 v112, v106, v107
	v_cvt_pk_bf16_f32 v113, v108, v109
	global_store_dwordx4 v[122:123], v[110:113], off offset:256
	v_cvt_pk_bf16_f32 v94, v94, v95
	v_cvt_pk_bf16_f32 v95, v96, v97
	v_or_b32_e32 v110, 16, v146
	v_ashrrev_i32_e32 v111, 31, v110
	v_lshlrev_b64 v[110:111], 11, v[110:111]
	v_lshl_add_u64 v[110:111], s[42:43], 0, v[110:111]
	v_lshl_add_u64 v[110:111], v[110:111], 0, v[124:125]
	v_cvt_pk_bf16_f32 v96, v90, v91
	v_cvt_pk_bf16_f32 v97, v92, v93
	global_store_dwordx4 v[110:111], v[94:97], off offset:256
	s_mov_b32 s47, 0x40000
	v_cvt_pk_bf16_f32 v62, v62, v63
	v_or_b32_e32 v94, 32, v146
	v_ashrrev_i32_e32 v95, 31, v94
	v_cvt_pk_bf16_f32 v63, v64, v65
	v_cvt_pk_bf16_f32 v65, v60, v61
	s_mov_b64 s[54:55], 0x40000
	v_add_co_u32_e32 v60, vcc, s47, v122
	v_lshlrev_b64 v[94:95], 11, v[94:95]
	v_cvt_pk_bf16_f32 v64, v58, v59
	v_lshl_add_u64 v[58:59], v[122:123], 0, s[54:55]
	v_addc_co_u32_e32 v61, vcc, 0, v123, vcc
	v_cvt_pk_bf16_f32 v46, v46, v47
	v_cvt_pk_bf16_f32 v47, v48, v49
	v_cvt_pk_bf16_f32 v48, v42, v43
	v_cvt_pk_bf16_f32 v49, v44, v45
	s_mov_b32 s47, 0x48000
	v_lshl_add_u64 v[94:95], s[42:43], 0, v[94:95]
	global_store_dwordx4 v[58:59], v[46:49], off offset:256
	s_mov_b64 s[54:55], 0x48000
	v_lshl_add_u64 v[94:95], v[94:95], 0, v[124:125]
	v_add_co_u32_e32 v48, vcc, s47, v122
	v_cvt_pk_bf16_f32 v78, v78, v79
	v_cvt_pk_bf16_f32 v79, v80, v81
	v_cvt_pk_bf16_f32 v80, v74, v75
	v_cvt_pk_bf16_f32 v81, v76, v77
	v_lshl_add_u64 v[46:47], v[122:123], 0, s[54:55]
	v_addc_co_u32_e32 v49, vcc, 0, v123, vcc
	v_cvt_pk_bf16_f32 v30, v30, v31
	v_cvt_pk_bf16_f32 v31, v32, v33
	v_cvt_pk_bf16_f32 v32, v26, v27
	v_cvt_pk_bf16_f32 v33, v28, v29
	s_mov_b32 s47, 0x50000
	global_store_dwordx4 v[94:95], v[78:81], off offset:256
	global_store_dwordx4 v[46:47], v[30:33], off offset:256
	s_mov_b64 s[54:55], 0x50000
	v_or_b32_e32 v78, 48, v146
	v_add_co_u32_e32 v32, vcc, s47, v122
	v_ashrrev_i32_e32 v79, 31, v78
	v_lshl_add_u64 v[30:31], v[122:123], 0, s[54:55]
	v_addc_co_u32_e32 v33, vcc, 0, v123, vcc
	v_cvt_pk_bf16_f32 v14, v14, v15
	v_cvt_pk_bf16_f32 v15, v16, v17
	v_cvt_pk_bf16_f32 v16, v10, v11
	v_cvt_pk_bf16_f32 v17, v12, v13
	s_mov_b32 s47, 0x58000
	v_lshlrev_b64 v[78:79], 11, v[78:79]
	global_store_dwordx4 v[30:31], v[14:17], off offset:256
	v_lshl_add_u64 v[78:79], s[42:43], 0, v[78:79]
	s_mov_b64 s[54:55], 0x58000
	v_add_co_u32_e32 v16, vcc, s47, v122
	v_cvt_pk_bf16_f32 v106, v118, v119
	s_nop 0
	v_addc_co_u32_e32 v17, vcc, 0, v123, vcc
	v_cvt_pk_bf16_f32 v107, v120, v121
	v_cvt_pk_bf16_f32 v108, v114, v115
	v_cvt_pk_bf16_f32 v109, v116, v117
	v_cvt_pk_bf16_f32 v90, v102, v103
	v_cvt_pk_bf16_f32 v91, v104, v105
	v_cvt_pk_bf16_f32 v92, v98, v99
	v_cvt_pk_bf16_f32 v93, v100, v101
	v_cvt_pk_bf16_f32 v74, v86, v87
	v_cvt_pk_bf16_f32 v75, v88, v89
	v_cvt_pk_bf16_f32 v76, v82, v83
	v_cvt_pk_bf16_f32 v77, v84, v85
	v_lshl_add_u64 v[78:79], v[78:79], 0, v[124:125]
	v_cvt_pk_bf16_f32 v70, v70, v71
	v_cvt_pk_bf16_f32 v71, v72, v73
	v_cvt_pk_bf16_f32 v72, v66, v67
	v_cvt_pk_bf16_f32 v73, v68, v69
	v_cvt_pk_bf16_f32 v42, v54, v55
	v_cvt_pk_bf16_f32 v43, v56, v57
	v_cvt_pk_bf16_f32 v44, v50, v51
	v_cvt_pk_bf16_f32 v45, v52, v53
	v_cvt_pk_bf16_f32 v26, v38, v39
	v_cvt_pk_bf16_f32 v27, v40, v41
	v_cvt_pk_bf16_f32 v28, v34, v35
	v_cvt_pk_bf16_f32 v29, v36, v37
	v_cvt_pk_bf16_f32 v10, v22, v23
	v_cvt_pk_bf16_f32 v11, v24, v25
	v_cvt_pk_bf16_f32 v12, v18, v19
	v_cvt_pk_bf16_f32 v13, v20, v21
	v_lshl_add_u64 v[14:15], v[122:123], 0, s[54:55]
	v_cvt_pk_bf16_f32 v6, v6, v7
	v_cvt_pk_bf16_f32 v7, v8, v9
	v_cvt_pk_bf16_f32 v8, v2, v3
	v_cvt_pk_bf16_f32 v9, v4, v5
	s_and_b64 vcc, exec, s[44:45]
	s_mov_b32 s75, s46
	s_mov_b32 s74, s48
	s_mov_b64 s[56:57], s[52:53]
	s_mov_b64 s[54:55], s[50:51]
	global_store_dwordx4 v[122:123], v[126:129], off
	global_store_dwordx4 v[110:111], v[106:109], off
	global_store_dwordx4 v[94:95], v[90:93], off
	global_store_dwordx4 v[78:79], v[74:77], off
	global_store_dwordx4 v[78:79], v[70:73], off offset:256
	global_store_dwordx4 v[60:61], v[62:65], off
	global_store_dwordx4 v[48:49], v[42:45], off
	global_store_dwordx4 v[32:33], v[26:29], off
	global_store_dwordx4 v[16:17], v[10:13], off
	global_store_dwordx4 v[14:15], v[6:9], off offset:256
	s_cbranch_vccz .LBB0_74
	s_waitcnt vmcnt(0)
	s_cmpk_gt_u32 s60, 0xff
	s_cbranch_scc1 .LBB0_81
	s_barrier

; #define PG8_STAGE(bufoff, gbase, voff) do { _Pragma("unroll") for (int _i = 0; _i < 2; ++_i) \
;         __builtin_amdgcn_global_load_lds((const unsigned*)((const char*)(gbase) + (voff)[_i]), (LAS unsigned*)(lds + (bufoff) + ldsw + _i * 8192), 16, 0, 0); } while (0)
; #define PG8_LDA(dst, b, h) do { _Pragma("unroll") for (int m = 0; m < 4; ++m) _Pragma("unroll") for (int k = 0; k < 2; ++k) dst[m][k] = *(const LAS bf16x8*)(lds + PG8_SA(b, h) + aoff + m * 2048 + k * 1024); } while (0)
; #define PG8_LDB(dst, b, h) do { _Pragma("unroll") for (int n = 0; n < 2; ++n) _Pragma("unroll") for (int k = 0; k < 2; ++k) dst[n][k] = *(const LAS bf16x8*)(lds + PG8_SB(b, h) + boff + n * 2048 + k * 1024); } while (0)
; #define PG8_MMA(ai, bj, At, Bt) do { __builtin_amdgcn_s_setprio(1); _Pragma("unroll") for (int m = 0; m < 4; ++m) _Pragma("unroll") for (int n = 0; n < 2; ++n) _Pragma("unroll") for (int k = 0; k < 2; ++k) \
;         acc[ai][bj][m][n] = __builtin_amdgcn_mfma_f32_16x16x32_bf16(Bt[n][k], At[m][k], acc[ai][bj][m][n], 0, 0, 0); __builtin_amdgcn_s_setprio(0); } while (0)
; #define PG8_WAIT_L(n) asm volatile("s_waitcnt lgkmcnt(" #n ")" ::: "memory")
; #define PG8_BAR __builtin_amdgcn_s_barrier()
; #define PG8_SCHED __builtin_amdgcn_sched_barrier(0)
; template <class Epi>
; __device__ __forceinline__ void gemm_phase(LAS unsigned char* lds, const Gemm g, const StaticOrder& S, const Epi& E) {
;     ...
;         for (int t = 0; t < nt; t += 2) {
;             const bool last = (t == nt - 2);
;             const char* a1 = cA + (size_t)(t + 1) * kstep;
;             const char* a2 = last ? nA : cA + (size_t)(t + 2) * kstep; const char* b2 = last ? nB : cB + (size_t)(t + 2) * kstep;
;             const char* a3 = a2 + kstep; const char* b3 = b2 + kstep;
;             PG8_LDB(B0, 0, 0); PG8_SCHED; PG8_LDA(At, 0, 0); PG8_STAGE(PG8_SA(1, 1), a1 + hstep, voffA);
;             PG8_WAIT_L(8); PG8_BAR; PG8_WAIT_L(0); PG8_MMA(0, 0, At, B0); PG8_BAR; PG8_SCHED;
;     ...
; #pragma unroll
;         for (int a = 0; a < 2; ++a)
; #pragma unroll
;             for (int b = 0; b < 2; ++b)
; #pragma unroll
;                 for (int m = 0; m < 4; ++m)
; #pragma unroll
;                     for (int n = 0; n < 2; ++n) acc[a][b][m][n] = (f32x4){0.f, 0.f, 0.f, 0.f};
;         cur = nxt; cA = nA; cB = nB; ++ui;
.LBB0_89:
	v_mov_b64_e32 v[2:3], 0x580
	s_ashr_i32 s41, s40, 31
	v_cmp_lt_i64_e32 vcc, s[42:43], v[2:3]
	s_lshl_b64 s[42:43], s[40:41], 20
	v_readlane_b32 s44, v254, 8
	v_readlane_b32 s45, v254, 9
	s_add_u32 s42, s44, s42
	s_addc_u32 s43, s45, s43
	s_and_b64 s[44:45], vcc, exec
	s_cselect_b32 s41, s43, s47
	s_cselect_b32 s69, s42, s46
	s_ashr_i32 s39, s38, 31
	s_lshl_b64 s[44:45], s[38:39], 20
	s_add_u32 s44, s53, s44
	s_addc_u32 s45, s54, s45
	s_and_b64 s[50:51], vcc, exec
	s_cselect_b32 s39, s45, s49
	s_cselect_b32 s70, s44, s48
	s_add_u32 s46, s46, 0x80080
	s_addc_u32 s47, s47, 0
	s_add_u32 s71, s48, 0x100
	v_mov_b32_e32 v2, 0
	s_addc_u32 s72, s49, 0
	s_mov_b32 s73, -2
	v_mov_b32_e32 v3, v2
	v_mov_b32_e32 v4, v2
	v_mov_b32_e32 v5, v2
	v_mov_b32_e32 v10, v2
	v_mov_b32_e32 v11, v2
	v_mov_b32_e32 v12, v2
	v_mov_b32_e32 v13, v2
	v_mov_b32_e32 v18, v2
	v_mov_b32_e32 v19, v2
	v_mov_b32_e32 v20, v2
	v_mov_b32_e32 v21, v2
	s_waitcnt vmcnt(0)
	v_mov_b32_e32 v26, v2
	v_mov_b32_e32 v27, v2
	v_mov_b32_e32 v28, v2
	v_mov_b32_e32 v29, v2
	v_mov_b32_e32 v34, v2
	v_mov_b32_e32 v35, v2
	v_mov_b32_e32 v36, v2
	v_mov_b32_e32 v37, v2
	v_mov_b32_e32 v42, v2
	v_mov_b32_e32 v43, v2
	v_mov_b32_e32 v44, v2
	v_mov_b32_e32 v45, v2
	v_mov_b32_e32 v50, v2
	v_mov_b32_e32 v51, v2
	v_mov_b32_e32 v52, v2
	v_mov_b32_e32 v53, v2
	v_mov_b32_e32 v58, v2
	v_mov_b32_e32 v59, v2
	v_mov_b32_e32 v60, v2
	v_mov_b32_e32 v61, v2
	v_mov_b32_e32 v6, v2
	v_mov_b32_e32 v7, v2
	v_mov_b32_e32 v8, v2
	v_mov_b32_e32 v9, v2
	v_mov_b32_e32 v14, v2
	v_mov_b32_e32 v15, v2
	v_mov_b32_e32 v16, v2
	v_mov_b32_e32 v17, v2
	v_mov_b32_e32 v22, v2
	v_mov_b32_e32 v23, v2
	v_mov_b32_e32 v24, v2
	v_mov_b32_e32 v25, v2
	v_mov_b32_e32 v30, v2
	v_mov_b32_e32 v31, v2
	v_mov_b32_e32 v32, v2
	v_mov_b32_e32 v33, v2
	v_mov_b32_e32 v38, v2
	v_mov_b32_e32 v39, v2
	v_mov_b32_e32 v40, v2
	v_mov_b32_e32 v41, v2
	v_mov_b32_e32 v46, v2
	v_mov_b32_e32 v47, v2
	v_mov_b32_e32 v48, v2
	v_mov_b32_e32 v49, v2
	v_mov_b32_e32 v54, v2
	v_mov_b32_e32 v55, v2
	v_mov_b32_e32 v56, v2
	v_mov_b32_e32 v57, v2
	v_mov_b32_e32 v62, v2
	v_mov_b32_e32 v63, v2
	v_mov_b32_e32 v64, v2
	v_mov_b32_e32 v65, v2
	v_mov_b32_e32 v66, v2
	v_mov_b32_e32 v67, v2
	v_mov_b32_e32 v68, v2
	v_mov_b32_e32 v69, v2
	v_mov_b32_e32 v74, v2
	v_mov_b32_e32 v75, v2
	v_mov_b32_e32 v76, v2
	v_mov_b32_e32 v77, v2
	v_mov_b32_e32 v82, v2
	v_mov_b32_e32 v83, v2
	v_mov_b32_e32 v84, v2
	v_mov_b32_e32 v85, v2
	v_mov_b32_e32 v90, v2
	v_mov_b32_e32 v91, v2
	v_mov_b32_e32 v92, v2
	v_mov_b32_e32 v93, v2
	v_mov_b32_e32 v98, v2
	v_mov_b32_e32 v99, v2
	v_mov_b32_e32 v100, v2
	v_mov_b32_e32 v101, v2
	v_mov_b32_e32 v106, v2
	v_mov_b32_e32 v107, v2
	v_mov_b32_e32 v108, v2
	v_mov_b32_e32 v109, v2
	v_mov_b32_e32 v114, v2
	v_mov_b32_e32 v115, v2
	v_mov_b32_e32 v116, v2
	v_mov_b32_e32 v117, v2
	v_mov_b32_e32 v118, v2
	v_mov_b32_e32 v119, v2
	v_mov_b32_e32 v120, v2
	v_mov_b32_e32 v121, v2
	v_mov_b32_e32 v70, v2
	v_mov_b32_e32 v71, v2
	v_mov_b32_e32 v72, v2
	v_mov_b32_e32 v73, v2
	v_mov_b32_e32 v78, v2
	v_mov_b32_e32 v79, v2
	v_mov_b32_e32 v80, v2
	v_mov_b32_e32 v81, v2
	v_mov_b32_e32 v86, v2
	v_mov_b32_e32 v87, v2
	v_mov_b32_e32 v88, v2
	v_mov_b32_e32 v89, v2
	v_mov_b32_e32 v94, v2
	v_mov_b32_e32 v95, v2
	v_mov_b32_e32 v96, v2
	v_mov_b32_e32 v97, v2
	v_mov_b32_e32 v102, v2
	v_mov_b32_e32 v103, v2
	v_mov_b32_e32 v104, v2
	v_mov_b32_e32 v105, v2
	v_mov_b32_e32 v110, v2
	v_mov_b32_e32 v111, v2
	v_mov_b32_e32 v112, v2
	v_mov_b32_e32 v113, v2
	v_mov_b32_e32 v122, v2
	v_mov_b32_e32 v123, v2
	v_mov_b32_e32 v124, v2
	v_mov_b32_e32 v125, v2
	v_mov_b32_e32 v126, v2
	v_mov_b32_e32 v127, v2
	v_mov_b32_e32 v128, v2
	v_mov_b32_e32 v129, v2
	v_add_u32_e32 v140, 0x10000, v143
	ds_read_b128 v[152:155], v140
	ds_read_b128 v[156:159], v140 offset:1024
	ds_read_b128 v[160:163], v140 offset:2048
	ds_read_b128 v[164:167], v140 offset:3072
.LBB0_90:
	s_add_u32 s48, s46, 0xfff80080
	s_addc_u32 s49, s47, -1
	s_add_i32 s74, 0, 0x10000
	s_cmp_eq_u32 s73, 28
	s_cselect_b32 s51, s41, s49
	s_cselect_b32 s50, s69, s48
	s_cselect_b32 s49, s39, s72
	s_cselect_b32 s48, s70, s71
	s_add_i32 m0, s56, 0xc000
	ds_read_b128 v[168:171], v151
	ds_read_b128 v[172:175], v151 offset:1024
	ds_read_b128 v[176:179], v151 offset:2048
	ds_read_b128 v[180:183], v151 offset:3072
	ds_read_b128 v[184:187], v151 offset:4096
	ds_read_b128 v[188:191], v151 offset:5120
	ds_read_b128 v[192:195], v151 offset:6144
	ds_read_b128 v[196:199], v151 offset:7168
	global_load_lds_dwordx4 v136, s[46:47]
	s_add_i32 m0, s56, 0xe000
	s_nop 0
	global_load_lds_dwordx4 v138, s[46:47]
	s_waitcnt lgkmcnt(8)
	s_barrier
	s_waitcnt lgkmcnt(0)
	s_setprio 1
	v_mfma_f32_16x16x32_bf16 v[126:129], v[152:155], v[168:171], v[126:129]
	v_mfma_f32_16x16x32_bf16 v[122:125], v[160:163], v[168:171], v[122:125]
	v_mfma_f32_16x16x32_bf16 v[110:113], v[152:155], v[176:179], v[110:113]
	v_mfma_f32_16x16x32_bf16 v[102:105], v[160:163], v[176:179], v[102:105]
	v_mfma_f32_16x16x32_bf16 v[94:97], v[152:155], v[184:187], v[94:97]
	v_mfma_f32_16x16x32_bf16 v[86:89], v[160:163], v[184:187], v[86:89]
	v_mfma_f32_16x16x32_bf16 v[78:81], v[152:155], v[192:195], v[78:81]
	v_mfma_f32_16x16x32_bf16 v[70:73], v[160:163], v[192:195], v[70:73]
	v_mfma_f32_16x16x32_bf16 v[126:129], v[156:159], v[172:175], v[126:129]
	v_mfma_f32_16x16x32_bf16 v[122:125], v[164:167], v[172:175], v[122:125]
	v_mfma_f32_16x16x32_bf16 v[110:113], v[156:159], v[180:183], v[110:113]
	v_mfma_f32_16x16x32_bf16 v[102:105], v[164:167], v[180:183], v[102:105]
	v_mfma_f32_16x16x32_bf16 v[94:97], v[156:159], v[188:191], v[94:97]
	v_mfma_f32_16x16x32_bf16 v[86:89], v[164:167], v[188:191], v[86:89]
	v_mfma_f32_16x16x32_bf16 v[78:81], v[156:159], v[196:199], v[78:81]
	v_mfma_f32_16x16x32_bf16 v[70:73], v[164:167], v[196:199], v[70:73]
	s_setprio 0
	s_barrier
; #define PG8_STAGE(bufoff, gbase, voff) do { _Pragma("unroll") for (int _i = 0; _i < 2; ++_i) \
;         __builtin_amdgcn_global_load_lds((const unsigned*)((const char*)(gbase) + (voff)[_i]), (LAS unsigned*)(lds + (bufoff) + ldsw + _i * 8192), 16, 0, 0); } while (0)
; #define PG8_LDA(dst, b, h) do { _Pragma("unroll") for (int m = 0; m < 4; ++m) _Pragma("unroll") for (int k = 0; k < 2; ++k) dst[m][k] = *(const LAS bf16x8*)(lds + PG8_SA(b, h) + aoff + m * 2048 + k * 1024); } while (0)
; #define PG8_LDB(dst, b, h) do { _Pragma("unroll") for (int n = 0; n < 2; ++n) _Pragma("unroll") for (int k = 0; k < 2; ++k) dst[n][k] = *(const LAS bf16x8*)(lds + PG8_SB(b, h) + boff + n * 2048 + k * 1024); } while (0)
; #define PG8_MMA(ai, bj, At, Bt) do { __builtin_amdgcn_s_setprio(1); _Pragma("unroll") for (int m = 0; m < 4; ++m) _Pragma("unroll") for (int n = 0; n < 2; ++n) _Pragma("unroll") for (int k = 0; k < 2; ++k) \
;         acc[ai][bj][m][n] = __builtin_amdgcn_mfma_f32_16x16x32_bf16(Bt[n][k], At[m][k], acc[ai][bj][m][n], 0, 0, 0); __builtin_amdgcn_s_setprio(0); } while (0)
; #define PG8_WAIT_V(n) asm volatile("s_waitcnt vmcnt(" #n ")" ::: "memory")
; #define PG8_WAIT_L(n) asm volatile("s_waitcnt lgkmcnt(" #n ")" ::: "memory")
; #define PG8_BAR __builtin_amdgcn_s_barrier()
; #define PG8_SCHED __builtin_amdgcn_sched_barrier(0)
; template <class Epi>
; __device__ __forceinline__ void gemm_phase(LAS unsigned char* lds, const Gemm g, const StaticOrder& S, const Epi& E) {
;     ...
;             PG8_LDB(B0, 0, 0); PG8_SCHED; PG8_LDA(At, 0, 0); PG8_STAGE(PG8_SA(1, 1), a1 + hstep, voffA);
;             PG8_WAIT_L(8); PG8_BAR; PG8_WAIT_L(0); PG8_MMA(0, 0, At, B0); PG8_BAR; PG8_SCHED;
;             PG8_LDB(B1, 0, 1); PG8_STAGE(PG8_SB(0, 0), b2, voffB);
;             PG8_BAR; PG8_WAIT_L(0); PG8_MMA(0, 1, At, B1); PG8_BAR;
;             PG8_LDA(At, 0, 1); PG8_STAGE(PG8_SA(0, 0), a2, voffA);
;             PG8_BAR; PG8_WAIT_L(0); PG8_MMA(1, 0, At, B0); PG8_BAR; PG8_SCHED;
;             PG8_STAGE(PG8_SB(0, 1), b2 + hstep, voffB);
;             PG8_WAIT_V(6); PG8_BAR; PG8_MMA(1, 1, At, B1); PG8_BAR;
;             PG8_LDB(B0, 1, 0); PG8_SCHED; PG8_LDA(At, 1, 0); PG8_STAGE(PG8_SA(0, 1), a2 + hstep, voffA);
	s_add_i32 s76, 0, 0x14000
	s_add_i32 s74, s74, s55
	v_add_u32_e32 v140, s76, v143
	s_mov_b32 m0, s74
	ds_read_b128 v[208:211], v140
	ds_read_b128 v[212:215], v140 offset:1024
	ds_read_b128 v[216:219], v140 offset:2048
	ds_read_b128 v[220:223], v140 offset:3072
	global_load_lds_dwordx4 v0, s[48:49]
	s_add_i32 m0, s74, 0x2000
	s_add_u32 s98, s48, s22
	global_load_lds_dwordx4 v130, s[48:49]
	s_addc_u32 s99, s49, s23
	s_barrier
	s_waitcnt lgkmcnt(0)
	s_setprio 1
	v_mfma_f32_16x16x32_bf16 v[118:121], v[208:211], v[168:171], v[118:121]
	v_mfma_f32_16x16x32_bf16 v[114:117], v[216:219], v[168:171], v[114:117]
	v_mfma_f32_16x16x32_bf16 v[106:109], v[208:211], v[176:179], v[106:109]
	v_mfma_f32_16x16x32_bf16 v[98:101], v[216:219], v[176:179], v[98:101]
	v_mfma_f32_16x16x32_bf16 v[90:93], v[208:211], v[184:187], v[90:93]
	v_mfma_f32_16x16x32_bf16 v[82:85], v[216:219], v[184:187], v[82:85]
	v_mfma_f32_16x16x32_bf16 v[74:77], v[208:211], v[192:195], v[74:77]
	v_mfma_f32_16x16x32_bf16 v[66:69], v[216:219], v[192:195], v[66:69]
	v_mfma_f32_16x16x32_bf16 v[118:121], v[212:215], v[172:175], v[118:121]
	v_mfma_f32_16x16x32_bf16 v[114:117], v[220:223], v[172:175], v[114:117]
	v_mfma_f32_16x16x32_bf16 v[106:109], v[212:215], v[180:183], v[106:109]
	v_mfma_f32_16x16x32_bf16 v[98:101], v[220:223], v[180:183], v[98:101]
	v_mfma_f32_16x16x32_bf16 v[90:93], v[212:215], v[188:191], v[90:93]
	v_mfma_f32_16x16x32_bf16 v[82:85], v[220:223], v[188:191], v[82:85]
	v_mfma_f32_16x16x32_bf16 v[74:77], v[212:215], v[196:199], v[74:77]
	v_mfma_f32_16x16x32_bf16 v[66:69], v[220:223], v[196:199], v[66:69]
	s_setprio 0
	s_mov_b32 m0, s56
	s_add_u32 s100, s50, s22
	s_addc_u32 s101, s51, s23
	s_barrier
	ds_read_b128 v[168:171], v151 offset:16384
	ds_read_b128 v[172:175], v151 offset:17408
	ds_read_b128 v[176:179], v151 offset:18432
	ds_read_b128 v[180:183], v151 offset:19456
	ds_read_b128 v[184:187], v151 offset:20480
	ds_read_b128 v[188:191], v151 offset:21504
	ds_read_b128 v[192:195], v151 offset:22528
	ds_read_b128 v[196:199], v151 offset:23552
	global_load_lds_dwordx4 v134, s[50:51]
	s_mov_b32 m0, s57
	s_nop 0
	global_load_lds_dwordx4 v132, s[50:51]
	s_waitcnt vmcnt(10)
	s_barrier
	s_waitcnt lgkmcnt(0)
	s_setprio 1
	v_mfma_f32_16x16x32_bf16 v[62:65], v[152:155], v[168:171], v[62:65]
	v_mfma_f32_16x16x32_bf16 v[54:57], v[160:163], v[168:171], v[54:57]
	v_mfma_f32_16x16x32_bf16 v[46:49], v[152:155], v[176:179], v[46:49]
	v_mfma_f32_16x16x32_bf16 v[38:41], v[160:163], v[176:179], v[38:41]
	v_mfma_f32_16x16x32_bf16 v[30:33], v[152:155], v[184:187], v[30:33]
	v_mfma_f32_16x16x32_bf16 v[22:25], v[160:163], v[184:187], v[22:25]
	v_mfma_f32_16x16x32_bf16 v[14:17], v[152:155], v[192:195], v[14:17]
	v_mfma_f32_16x16x32_bf16 v[6:9], v[160:163], v[192:195], v[6:9]
	v_mfma_f32_16x16x32_bf16 v[62:65], v[156:159], v[172:175], v[62:65]
	v_mfma_f32_16x16x32_bf16 v[54:57], v[164:167], v[172:175], v[54:57]
	v_mfma_f32_16x16x32_bf16 v[46:49], v[156:159], v[180:183], v[46:49]
	v_mfma_f32_16x16x32_bf16 v[38:41], v[164:167], v[180:183], v[38:41]
	v_mfma_f32_16x16x32_bf16 v[30:33], v[156:159], v[188:191], v[30:33]
	v_mfma_f32_16x16x32_bf16 v[22:25], v[164:167], v[188:191], v[22:25]
	v_mfma_f32_16x16x32_bf16 v[14:17], v[156:159], v[196:199], v[14:17]
	v_mfma_f32_16x16x32_bf16 v[6:9], v[164:167], v[196:199], v[6:9]
	s_setprio 0
	s_barrier
	v_add_u32_e32 v140, 0x18000, v143
	ds_read_b128 v[152:155], v140
	ds_read_b128 v[156:159], v140 offset:1024
	ds_read_b128 v[160:163], v140 offset:2048
	ds_read_b128 v[164:167], v140 offset:3072
	s_add_u32 s74, s48, 0x80000
	s_addc_u32 s75, s49, 0
	s_add_i32 s76, s76, s55
	s_mov_b32 m0, s76
	s_nop 0
	global_load_lds_dwordx4 v0, s[74:75]
	s_add_i32 m0, s76, 0x2000
	s_nop 0
	global_load_lds_dwordx4 v130, s[74:75]
	s_waitcnt vmcnt(6)
	s_barrier
	s_setprio 1
	v_mfma_f32_16x16x32_bf16 v[58:61], v[208:211], v[168:171], v[58:61]
	v_mfma_f32_16x16x32_bf16 v[50:53], v[216:219], v[168:171], v[50:53]
	v_mfma_f32_16x16x32_bf16 v[42:45], v[208:211], v[176:179], v[42:45]
	v_mfma_f32_16x16x32_bf16 v[34:37], v[216:219], v[176:179], v[34:37]
	v_mfma_f32_16x16x32_bf16 v[26:29], v[208:211], v[184:187], v[26:29]
	v_mfma_f32_16x16x32_bf16 v[18:21], v[216:219], v[184:187], v[18:21]
	v_mfma_f32_16x16x32_bf16 v[10:13], v[208:211], v[192:195], v[10:13]
	v_mfma_f32_16x16x32_bf16 v[2:5], v[216:219], v[192:195], v[2:5]
	v_mfma_f32_16x16x32_bf16 v[58:61], v[212:215], v[172:175], v[58:61]
	v_mfma_f32_16x16x32_bf16 v[50:53], v[220:223], v[172:175], v[50:53]
	v_mfma_f32_16x16x32_bf16 v[42:45], v[212:215], v[180:183], v[42:45]
	v_mfma_f32_16x16x32_bf16 v[34:37], v[220:223], v[180:183], v[34:37]
	v_mfma_f32_16x16x32_bf16 v[26:29], v[212:215], v[188:191], v[26:29]
	v_mfma_f32_16x16x32_bf16 v[18:21], v[220:223], v[188:191], v[18:21]
	v_mfma_f32_16x16x32_bf16 v[10:13], v[212:215], v[196:199], v[10:13]
	v_mfma_f32_16x16x32_bf16 v[2:5], v[220:223], v[196:199], v[2:5]
	s_setprio 0
	s_add_i32 s74, 0, 0x18000
	s_barrier
	s_add_u32 s50, s50, 0x80000
	s_addc_u32 s51, s51, 0
	s_mov_b32 m0, s58
	ds_read_b128 v[168:171], v151 offset:32768
	ds_read_b128 v[172:175], v151 offset:33792
	ds_read_b128 v[176:179], v151 offset:34816
	ds_read_b128 v[180:183], v151 offset:35840
	ds_read_b128 v[184:187], v151 offset:36864
	ds_read_b128 v[188:191], v151 offset:37888
	ds_read_b128 v[192:195], v151 offset:38912
	ds_read_b128 v[196:199], v151 offset:39936
	global_load_lds_dwordx4 v134, s[50:51]
	s_mov_b32 m0, s59
	s_nop 0
	global_load_lds_dwordx4 v132, s[50:51]
	s_waitcnt lgkmcnt(8)
	s_barrier
; #define PG8_STAGE(bufoff, gbase, voff) do { _Pragma("unroll") for (int _i = 0; _i < 2; ++_i) \
;         __builtin_amdgcn_global_load_lds((const unsigned*)((const char*)(gbase) + (voff)[_i]), (LAS unsigned*)(lds + (bufoff) + ldsw + _i * 8192), 16, 0, 0); } while (0)
; #define PG8_LDA(dst, b, h) do { _Pragma("unroll") for (int m = 0; m < 4; ++m) _Pragma("unroll") for (int k = 0; k < 2; ++k) dst[m][k] = *(const LAS bf16x8*)(lds + PG8_SA(b, h) + aoff + m * 2048 + k * 1024); } while (0)
; #define PG8_LDB(dst, b, h) do { _Pragma("unroll") for (int n = 0; n < 2; ++n) _Pragma("unroll") for (int k = 0; k < 2; ++k) dst[n][k] = *(const LAS bf16x8*)(lds + PG8_SB(b, h) + boff + n * 2048 + k * 1024); } while (0)
; #define PG8_MMA(ai, bj, At, Bt) do { __builtin_amdgcn_s_setprio(1); _Pragma("unroll") for (int m = 0; m < 4; ++m) _Pragma("unroll") for (int n = 0; n < 2; ++n) _Pragma("unroll") for (int k = 0; k < 2; ++k) \
;         acc[ai][bj][m][n] = __builtin_amdgcn_mfma_f32_16x16x32_bf16(Bt[n][k], At[m][k], acc[ai][bj][m][n], 0, 0, 0); __builtin_amdgcn_s_setprio(0); } while (0)
; #define PG8_WAIT_V(n) asm volatile("s_waitcnt vmcnt(" #n ")" ::: "memory")
; #define PG8_WAIT_L(n) asm volatile("s_waitcnt lgkmcnt(" #n ")" ::: "memory")
; #define PG8_BAR __builtin_amdgcn_s_barrier()
; #define PG8_SCHED __builtin_amdgcn_sched_barrier(0)
; template <class Epi>
; __device__ __forceinline__ void gemm_phase(LAS unsigned char* lds, const Gemm g, const StaticOrder& S, const Epi& E) {
;     ...
;             PG8_LDB(B0, 1, 0); PG8_SCHED; PG8_LDA(At, 1, 0); PG8_STAGE(PG8_SA(0, 1), a2 + hstep, voffA);
;             PG8_WAIT_L(8); PG8_BAR; PG8_WAIT_L(0); PG8_MMA(0, 0, At, B0); PG8_BAR; PG8_SCHED;
;             PG8_LDB(B1, 1, 1); PG8_STAGE(PG8_SB(1, 0), b3, voffB);
;             PG8_BAR; PG8_WAIT_L(0); PG8_MMA(0, 1, At, B1); PG8_BAR;
;             PG8_LDA(At, 1, 1); PG8_STAGE(PG8_SA(1, 0), a3, voffA);
;             PG8_BAR; PG8_WAIT_L(0); PG8_MMA(1, 0, At, B0); PG8_BAR; PG8_SCHED;
;             PG8_STAGE(PG8_SB(1, 1), b3 + hstep, voffB);
;             PG8_WAIT_V(6); PG8_BAR; PG8_MMA(1, 1, At, B1); PG8_BAR;
	s_waitcnt lgkmcnt(0)
	s_setprio 1
	v_mfma_f32_16x16x32_bf16 v[126:129], v[152:155], v[168:171], v[126:129]
	v_mfma_f32_16x16x32_bf16 v[122:125], v[160:163], v[168:171], v[122:125]
	v_mfma_f32_16x16x32_bf16 v[110:113], v[152:155], v[176:179], v[110:113]
	v_mfma_f32_16x16x32_bf16 v[102:105], v[160:163], v[176:179], v[102:105]
	v_mfma_f32_16x16x32_bf16 v[94:97], v[152:155], v[184:187], v[94:97]
	v_mfma_f32_16x16x32_bf16 v[86:89], v[160:163], v[184:187], v[86:89]
	v_mfma_f32_16x16x32_bf16 v[78:81], v[152:155], v[192:195], v[78:81]
	v_mfma_f32_16x16x32_bf16 v[70:73], v[160:163], v[192:195], v[70:73]
	v_mfma_f32_16x16x32_bf16 v[126:129], v[156:159], v[172:175], v[126:129]
	v_mfma_f32_16x16x32_bf16 v[122:125], v[164:167], v[172:175], v[122:125]
	v_mfma_f32_16x16x32_bf16 v[110:113], v[156:159], v[180:183], v[110:113]
	v_mfma_f32_16x16x32_bf16 v[102:105], v[164:167], v[180:183], v[102:105]
	v_mfma_f32_16x16x32_bf16 v[94:97], v[156:159], v[188:191], v[94:97]
	v_mfma_f32_16x16x32_bf16 v[86:89], v[164:167], v[188:191], v[86:89]
	v_mfma_f32_16x16x32_bf16 v[78:81], v[156:159], v[196:199], v[78:81]
	v_mfma_f32_16x16x32_bf16 v[70:73], v[164:167], v[196:199], v[70:73]
	s_setprio 0
	s_barrier
	s_add_i32 s50, 0, 0x1c000
	s_add_i32 s51, s74, s55
	v_add_u32_e32 v140, s50, v143
	s_mov_b32 m0, s51
	ds_read_b128 v[208:211], v140
	ds_read_b128 v[212:215], v140 offset:1024
	ds_read_b128 v[216:219], v140 offset:2048
	ds_read_b128 v[220:223], v140 offset:3072
	global_load_lds_dwordx4 v0, s[98:99]
	s_add_i32 m0, s51, 0x2000
	s_nop 0
	global_load_lds_dwordx4 v130, s[98:99]
	s_barrier
	s_waitcnt lgkmcnt(0)
	s_setprio 1
	v_mfma_f32_16x16x32_bf16 v[118:121], v[208:211], v[168:171], v[118:121]
	v_mfma_f32_16x16x32_bf16 v[114:117], v[216:219], v[168:171], v[114:117]
	v_mfma_f32_16x16x32_bf16 v[106:109], v[208:211], v[176:179], v[106:109]
	v_mfma_f32_16x16x32_bf16 v[98:101], v[216:219], v[176:179], v[98:101]
	v_mfma_f32_16x16x32_bf16 v[90:93], v[208:211], v[184:187], v[90:93]
	v_mfma_f32_16x16x32_bf16 v[82:85], v[216:219], v[184:187], v[82:85]
	v_mfma_f32_16x16x32_bf16 v[74:77], v[208:211], v[192:195], v[74:77]
	v_mfma_f32_16x16x32_bf16 v[66:69], v[216:219], v[192:195], v[66:69]
	v_mfma_f32_16x16x32_bf16 v[118:121], v[212:215], v[172:175], v[118:121]
	v_mfma_f32_16x16x32_bf16 v[114:117], v[220:223], v[172:175], v[114:117]
	v_mfma_f32_16x16x32_bf16 v[106:109], v[212:215], v[180:183], v[106:109]
	v_mfma_f32_16x16x32_bf16 v[98:101], v[220:223], v[180:183], v[98:101]
	v_mfma_f32_16x16x32_bf16 v[90:93], v[212:215], v[188:191], v[90:93]
	v_mfma_f32_16x16x32_bf16 v[82:85], v[220:223], v[188:191], v[82:85]
	v_mfma_f32_16x16x32_bf16 v[74:77], v[212:215], v[196:199], v[74:77]
	v_mfma_f32_16x16x32_bf16 v[66:69], v[220:223], v[196:199], v[66:69]
	s_setprio 0
	s_mov_b32 m0, s61
	s_barrier
	ds_read_b128 v[168:171], v151 offset:49152
	ds_read_b128 v[172:175], v151 offset:50176
	ds_read_b128 v[176:179], v151 offset:51200
	ds_read_b128 v[180:183], v151 offset:52224
	ds_read_b128 v[184:187], v151 offset:53248
	ds_read_b128 v[188:191], v151 offset:54272
	ds_read_b128 v[192:195], v151 offset:55296
	ds_read_b128 v[196:199], v151 offset:56320
	global_load_lds_dwordx4 v134, s[100:101]
	s_mov_b32 m0, s63
	s_nop 0
	global_load_lds_dwordx4 v132, s[100:101]
	s_waitcnt vmcnt(10)
	s_barrier
	s_waitcnt lgkmcnt(0)
	s_setprio 1
	v_mfma_f32_16x16x32_bf16 v[62:65], v[152:155], v[168:171], v[62:65]
	v_mfma_f32_16x16x32_bf16 v[54:57], v[160:163], v[168:171], v[54:57]
	v_mfma_f32_16x16x32_bf16 v[46:49], v[152:155], v[176:179], v[46:49]
	v_mfma_f32_16x16x32_bf16 v[38:41], v[160:163], v[176:179], v[38:41]
	v_mfma_f32_16x16x32_bf16 v[30:33], v[152:155], v[184:187], v[30:33]
	v_mfma_f32_16x16x32_bf16 v[22:25], v[160:163], v[184:187], v[22:25]
	v_mfma_f32_16x16x32_bf16 v[14:17], v[152:155], v[192:195], v[14:17]
	v_mfma_f32_16x16x32_bf16 v[6:9], v[160:163], v[192:195], v[6:9]
	v_mfma_f32_16x16x32_bf16 v[62:65], v[156:159], v[172:175], v[62:65]
	v_mfma_f32_16x16x32_bf16 v[54:57], v[164:167], v[172:175], v[54:57]
	v_mfma_f32_16x16x32_bf16 v[46:49], v[156:159], v[180:183], v[46:49]
	v_mfma_f32_16x16x32_bf16 v[38:41], v[164:167], v[180:183], v[38:41]
	v_mfma_f32_16x16x32_bf16 v[30:33], v[156:159], v[188:191], v[30:33]
	v_mfma_f32_16x16x32_bf16 v[22:25], v[164:167], v[188:191], v[22:25]
	v_mfma_f32_16x16x32_bf16 v[14:17], v[156:159], v[196:199], v[14:17]
	v_mfma_f32_16x16x32_bf16 v[6:9], v[164:167], v[196:199], v[6:9]
	s_setprio 0
	s_barrier
	v_add_u32_e32 v140, 0x10000, v143
	ds_read_b128 v[152:155], v140
	ds_read_b128 v[156:159], v140 offset:1024
	ds_read_b128 v[160:163], v140 offset:2048
	ds_read_b128 v[164:167], v140 offset:3072
	s_add_u32 s48, s48, 0x80080
	s_addc_u32 s49, s49, 0
	s_add_i32 s50, s50, s55
	s_mov_b32 m0, s50
	s_nop 0
	global_load_lds_dwordx4 v0, s[48:49]
	s_add_i32 m0, s50, 0x2000
	s_nop 0
	global_load_lds_dwordx4 v130, s[48:49]
	s_waitcnt vmcnt(6)
	s_barrier
	s_setprio 1
	v_mfma_f32_16x16x32_bf16 v[58:61], v[208:211], v[168:171], v[58:61]
	v_mfma_f32_16x16x32_bf16 v[50:53], v[216:219], v[168:171], v[50:53]
	v_mfma_f32_16x16x32_bf16 v[42:45], v[208:211], v[176:179], v[42:45]
	v_mfma_f32_16x16x32_bf16 v[34:37], v[216:219], v[176:179], v[34:37]
	v_mfma_f32_16x16x32_bf16 v[26:29], v[208:211], v[184:187], v[26:29]
	v_mfma_f32_16x16x32_bf16 v[18:21], v[216:219], v[184:187], v[18:21]
	v_mfma_f32_16x16x32_bf16 v[10:13], v[208:211], v[192:195], v[10:13]
	v_mfma_f32_16x16x32_bf16 v[2:5], v[216:219], v[192:195], v[2:5]
	v_mfma_f32_16x16x32_bf16 v[58:61], v[212:215], v[172:175], v[58:61]
	v_mfma_f32_16x16x32_bf16 v[50:53], v[220:223], v[172:175], v[50:53]
	v_mfma_f32_16x16x32_bf16 v[42:45], v[212:215], v[180:183], v[42:45]
	v_mfma_f32_16x16x32_bf16 v[34:37], v[220:223], v[180:183], v[34:37]
	v_mfma_f32_16x16x32_bf16 v[26:29], v[212:215], v[188:191], v[26:29]
	v_mfma_f32_16x16x32_bf16 v[18:21], v[220:223], v[188:191], v[18:21]
	v_mfma_f32_16x16x32_bf16 v[10:13], v[212:215], v[196:199], v[10:13]
	v_mfma_f32_16x16x32_bf16 v[2:5], v[220:223], v[196:199], v[2:5]
	s_setprio 0
	s_add_i32 s73, s73, 2
	s_add_u32 s46, s46, 0x100
	s_addc_u32 s47, s47, 0
	s_add_u32 s71, s71, 0x100
	s_addc_u32 s72, s72, 0
	s_cmp_gt_u32 s73, 29
	s_barrier
; __device__ __forceinline__ unsigned pk2(float lo, float hi) { f32x2 v = {lo, hi}; bf16x2_t b = __builtin_convertvector(v, bf16x2_t); return __builtin_bit_cast(unsigned, b); }
;     __device__ __forceinline__ void operator()(const AccT& acc, const Unit& u, int wr, int wc, int fr, int fq) const {
;         const int row0 = u.pm * BM + wr * 64 + fr, col0 = u.pn * 128 + wc * 32 + 8 * fq;
;         float rsv[8];
;         {
;             const int ln = (fq << 4) | fr;
;             float sa = ss[u.pm * BM + wr * 64 + ln], sb = ss[u.pm * BM + HALF + wr * 64 + ln];
;             sa = __builtin_amdgcn_rsqf(sa * (1.0f / DM) + EPS); sb = __builtin_amdgcn_rsqf(sb * (1.0f / DM) + EPS);
; #pragma unroll
;             for (int m = 0; m < 4; ++m) { rsv[m] = __shfl(sa, 16 * m + fr); rsv[4 + m] = __shfl(sb, 16 * m + fr); }
;         }
; #pragma unroll
;         for (int ai = 0; ai < 2; ++ai)
; #pragma unroll
;             for (int m = 0; m < 4; ++m) {
;                 const int row = row0 + ai * HALF + m * 16;
;                 const float rs = rsv[ai * 4 + m];
;                 float v[8];
; #pragma unroll
;                 for (int n = 0; n < 2; ++n)
; #pragma unroll
;                     for (int j = 0; j < 4; ++j) {
;                         const float g = acc[ai][0][m][n][j] * rs, up = acc[ai][1][m][n][j] * rs;
;                         const float sg = __builtin_amdgcn_rcpf(1.0f + __builtin_amdgcn_exp2f(-g * LOG2E));
;                         v[4 * n + j] = g * sg * up;
;                     }
;                 u32x4 w; w.x = pk2(v[0], v[1]); w.y = pk2(v[2], v[3]); w.z = pk2(v[4], v[5]); w.w = pk2(v[6], v[7]);
;                 *(u32x4*)(mid + (size_t)row * FF + col0) = w;
	s_cbranch_scc0 .LBB0_90
	s_waitcnt lgkmcnt(0)
	s_lshl_b32 s39, s68, 8
	s_add_i32 s39, s39, s60
	v_or_b32_e32 v154, s39, v145
	v_ashrrev_i32_e32 v155, 31, v154
	v_lshl_add_u64 v[154:155], v[154:155], 2, s[2:3]
	global_load_dword v140, v[154:155], off
	v_add_u32_e32 v154, s39, v147
	v_ashrrev_i32_e32 v155, 31, v154
	v_lshl_add_u64 v[154:155], v[154:155], 2, s[2:3]
	global_load_dword v142, v[154:155], off
	v_readlane_b32 s46, v251, 58
	v_readlane_b32 s47, v251, 59
	v_or_b32_e32 v153, s39, v141
	s_movk_i32 s39, 0x2c00
	s_and_b64 vcc, exec, s[36:37]
	s_mov_b32 s68, s40
	s_mov_b64 s[48:49], s[44:45]
	s_waitcnt vmcnt(0)
	v_fmamk_f32 v140, v140, 0x3a000000, v233
	v_rsq_f32_e32 v140, v140
	v_fmamk_f32 v142, v142, 0x3a000000, v233
	v_rsq_f32_e32 v154, v142
	v_and_or_b32 v142, v234, 64, v141
	v_lshlrev_b32_e32 v155, 2, v142
	ds_bpermute_b32 v156, v155, v140
	ds_bpermute_b32 v152, v155, v140 offset:64
	ds_bpermute_b32 v146, v155, v154
	ds_bpermute_b32 v144, v155, v154 offset:64
	ds_bpermute_b32 v150, v155, v140 offset:128
	s_waitcnt lgkmcnt(0)
	v_pk_mul_f32 v[126:127], v[126:127], v[156:157] op_sel_hi:[1,0]
	ds_bpermute_b32 v142, v155, v154 offset:128
	v_mul_f32_e32 v157, 0xbfb8aa3b, v126
	v_exp_f32_e32 v157, v157
	ds_bpermute_b32 v148, v155, v140 offset:192
	ds_bpermute_b32 v140, v155, v154 offset:192
	v_lshl_or_b32 v154, s65, 7, v149
	v_add_f32_e32 v157, 1.0, v157
	v_rcp_f32_e32 v158, v157
	v_pk_mul_f32 v[118:119], v[118:119], v[156:157] op_sel_hi:[1,0]
	v_mul_f32_e32 v157, 0xbfb8aa3b, v127
	v_exp_f32_e32 v157, v157
	v_ashrrev_i32_e32 v155, 31, v154
	v_pk_mul_f32 v[110:111], v[110:111], v[152:153] op_sel_hi:[1,0]
	v_pk_mul_f32 v[106:107], v[106:107], v[152:153] op_sel_hi:[1,0]
	v_add_f32_e32 v157, 1.0, v157
	v_rcp_f32_e32 v159, v157
	v_pk_mul_f32 v[120:121], v[120:121], v[156:157] op_sel_hi:[1,0]
	v_pk_mul_f32 v[122:123], v[122:123], v[156:157] op_sel_hi:[1,0]
	v_pk_mul_f32 v[114:115], v[114:115], v[156:157] op_sel_hi:[1,0]
	v_pk_mul_f32 v[126:127], v[126:127], v[158:159]
	v_pk_mul_f32 v[116:117], v[116:117], v[156:157] op_sel_hi:[1,0]
	v_pk_mul_f32 v[118:119], v[118:119], v[126:127]
	v_pk_mul_f32 v[126:127], v[128:129], v[156:157] op_sel_hi:[1,0]
	v_pk_mul_f32 v[108:109], v[108:109], v[152:153] op_sel_hi:[1,0]
	v_mul_f32_e32 v128, 0xbfb8aa3b, v126
	v_mul_f32_e32 v129, 0xbfb8aa3b, v127
	v_exp_f32_e32 v128, v128
	v_exp_f32_e32 v129, v129
	v_pk_mul_f32 v[102:103], v[102:103], v[152:153] op_sel_hi:[1,0]
	v_pk_mul_f32 v[98:99], v[98:99], v[152:153] op_sel_hi:[1,0]
	v_add_f32_e32 v128, 1.0, v128
	v_add_f32_e32 v129, 1.0, v129
	v_rcp_f32_e32 v128, v128
	v_rcp_f32_e32 v129, v129
	v_pk_mul_f32 v[100:101], v[100:101], v[152:153] op_sel_hi:[1,0]
	v_pk_mul_f32 v[94:95], v[94:95], v[150:151] op_sel_hi:[1,0]
	v_pk_mul_f32 v[90:91], v[90:91], v[150:151] op_sel_hi:[1,0]
	v_pk_mul_f32 v[126:127], v[126:127], v[128:129]
	v_pk_mul_f32 v[92:93], v[92:93], v[150:151] op_sel_hi:[1,0]
	v_pk_mul_f32 v[120:121], v[120:121], v[126:127]
	v_mul_f32_e32 v126, 0xbfb8aa3b, v122
	v_mul_f32_e32 v127, 0xbfb8aa3b, v123
	v_exp_f32_e32 v126, v126
	v_exp_f32_e32 v127, v127
	v_pk_mul_f32 v[86:87], v[86:87], v[150:151] op_sel_hi:[1,0]
	v_pk_mul_f32 v[82:83], v[82:83], v[150:151] op_sel_hi:[1,0]
	v_add_f32_e32 v126, 1.0, v126
	v_add_f32_e32 v127, 1.0, v127
	v_rcp_f32_e32 v126, v126
	v_rcp_f32_e32 v127, v127
	v_pk_mul_f32 v[84:85], v[84:85], v[150:151] op_sel_hi:[1,0]
	s_waitcnt lgkmcnt(1)
	v_pk_mul_f32 v[78:79], v[78:79], v[148:149] op_sel_hi:[1,0]
	v_pk_mul_f32 v[74:75], v[74:75], v[148:149] op_sel_hi:[1,0]
	v_pk_mul_f32 v[122:123], v[122:123], v[126:127]
	v_pk_mul_f32 v[76:77], v[76:77], v[148:149] op_sel_hi:[1,0]
	v_pk_mul_f32 v[122:123], v[114:115], v[122:123]
	v_pk_mul_f32 v[114:115], v[124:125], v[156:157] op_sel_hi:[1,0]
	v_pk_mul_f32 v[70:71], v[70:71], v[148:149] op_sel_hi:[1,0]
	v_mul_f32_e32 v124, 0xbfb8aa3b, v114
	v_mul_f32_e32 v125, 0xbfb8aa3b, v115
	v_exp_f32_e32 v124, v124
	v_exp_f32_e32 v125, v125
	v_pk_mul_f32 v[66:67], v[66:67], v[148:149] op_sel_hi:[1,0]
	v_pk_mul_f32 v[68:69], v[68:69], v[148:149] op_sel_hi:[1,0]
	v_add_f32_e32 v124, 1.0, v124
	v_add_f32_e32 v125, 1.0, v125
	v_rcp_f32_e32 v124, v124
	v_rcp_f32_e32 v125, v125
	v_pk_mul_f32 v[62:63], v[62:63], v[146:147] op_sel_hi:[1,0]
	v_pk_mul_f32 v[58:59], v[58:59], v[146:147] op_sel_hi:[1,0]
	v_pk_mul_f32 v[60:61], v[60:61], v[146:147] op_sel_hi:[1,0]
	v_pk_mul_f32 v[114:115], v[114:115], v[124:125]
	v_pk_mul_f32 v[54:55], v[54:55], v[146:147] op_sel_hi:[1,0]
	v_pk_mul_f32 v[124:125], v[116:117], v[114:115]
	v_cvt_pk_bf16_f32 v114, v118, v119
	v_mov_b64_e32 v[118:119], s[46:47]
	v_cvt_pk_bf16_f32 v115, v120, v121
	v_cvt_pk_bf16_f32 v116, v122, v123
	v_mad_i64_i32 v[122:123], s[46:47], v153, s39, v[118:119]
	v_lshlrev_b64 v[120:121], 1, v[154:155]
	v_cvt_pk_bf16_f32 v117, v124, v125
	v_lshl_add_u64 v[122:123], v[122:123], 0, v[120:121]
	global_store_dwordx4 v[122:123], v[114:117], off
	v_pk_mul_f32 v[50:51], v[50:51], v[146:147] op_sel_hi:[1,0]
	v_pk_mul_f32 v[52:53], v[52:53], v[146:147] op_sel_hi:[1,0]
	v_mul_f32_e32 v114, 0xbfb8aa3b, v110
	v_mul_f32_e32 v115, 0xbfb8aa3b, v111
	v_exp_f32_e32 v114, v114
	v_exp_f32_e32 v115, v115
	v_pk_mul_f32 v[46:47], v[46:47], v[144:145] op_sel_hi:[1,0]
	v_pk_mul_f32 v[42:43], v[42:43], v[144:145] op_sel_hi:[1,0]
	v_add_f32_e32 v114, 1.0, v114
	v_add_f32_e32 v115, 1.0, v115
	v_rcp_f32_e32 v114, v114
	v_rcp_f32_e32 v115, v115
	v_pk_mul_f32 v[44:45], v[44:45], v[144:145] op_sel_hi:[1,0]
	v_pk_mul_f32 v[38:39], v[38:39], v[144:145] op_sel_hi:[1,0]
	v_pk_mul_f32 v[34:35], v[34:35], v[144:145] op_sel_hi:[1,0]
	v_pk_mul_f32 v[110:111], v[110:111], v[114:115]
	v_pk_mul_f32 v[36:37], v[36:37], v[144:145] op_sel_hi:[1,0]
	v_pk_mul_f32 v[106:107], v[106:107], v[110:111]
	v_pk_mul_f32 v[110:111], v[112:113], v[152:153] op_sel_hi:[1,0]
	v_pk_mul_f32 v[30:31], v[30:31], v[142:143] op_sel_hi:[1,0]
	v_mul_f32_e32 v112, 0xbfb8aa3b, v110
	v_mul_f32_e32 v113, 0xbfb8aa3b, v111
	v_exp_f32_e32 v112, v112
	v_exp_f32_e32 v113, v113
	v_pk_mul_f32 v[26:27], v[26:27], v[142:143] op_sel_hi:[1,0]
	v_pk_mul_f32 v[28:29], v[28:29], v[142:143] op_sel_hi:[1,0]
	v_add_f32_e32 v112, 1.0, v112
	v_add_f32_e32 v113, 1.0, v113
	v_rcp_f32_e32 v112, v112
	v_rcp_f32_e32 v113, v113
	v_pk_mul_f32 v[22:23], v[22:23], v[142:143] op_sel_hi:[1,0]
	v_pk_mul_f32 v[18:19], v[18:19], v[142:143] op_sel_hi:[1,0]
	v_pk_mul_f32 v[20:21], v[20:21], v[142:143] op_sel_hi:[1,0]
	v_pk_mul_f32 v[110:111], v[110:111], v[112:113]
	s_waitcnt lgkmcnt(0)
; __device__ __forceinline__ unsigned pk2(float lo, float hi) { f32x2 v = {lo, hi}; bf16x2_t b = __builtin_convertvector(v, bf16x2_t); return __builtin_bit_cast(unsigned, b); }
;     __device__ __forceinline__ void operator()(const AccT& acc, const Unit& u, int wr, int wc, int fr, int fq) const {
;     ...
;         for (int ai = 0; ai < 2; ++ai)
; #pragma unroll
;             for (int m = 0; m < 4; ++m) {
;                 const int row = row0 + ai * HALF + m * 16;
;                 const float rs = rsv[ai * 4 + m];
;                 float v[8];
; #pragma unroll
;                 for (int n = 0; n < 2; ++n)
; #pragma unroll
;                     for (int j = 0; j < 4; ++j) {
;                         const float g = acc[ai][0][m][n][j] * rs, up = acc[ai][1][m][n][j] * rs;
;                         const float sg = __builtin_amdgcn_rcpf(1.0f + __builtin_amdgcn_exp2f(-g * LOG2E));
;                         v[4 * n + j] = g * sg * up;
;                     }
;                 u32x4 w; w.x = pk2(v[0], v[1]); w.y = pk2(v[2], v[3]); w.z = pk2(v[4], v[5]); w.w = pk2(v[6], v[7]);
;                 *(u32x4*)(mid + (size_t)row * FF + col0) = w;
	v_pk_mul_f32 v[14:15], v[14:15], v[140:141] op_sel_hi:[1,0]
	v_pk_mul_f32 v[108:109], v[108:109], v[110:111]
	v_mul_f32_e32 v110, 0xbfb8aa3b, v102
	v_mul_f32_e32 v111, 0xbfb8aa3b, v103
	v_exp_f32_e32 v110, v110
	v_exp_f32_e32 v111, v111
	v_pk_mul_f32 v[10:11], v[10:11], v[140:141] op_sel_hi:[1,0]
	v_pk_mul_f32 v[12:13], v[12:13], v[140:141] op_sel_hi:[1,0]
	v_add_f32_e32 v110, 1.0, v110
	v_add_f32_e32 v111, 1.0, v111
	v_rcp_f32_e32 v110, v110
	v_rcp_f32_e32 v111, v111
	v_pk_mul_f32 v[6:7], v[6:7], v[140:141] op_sel_hi:[1,0]
	v_pk_mul_f32 v[2:3], v[2:3], v[140:141] op_sel_hi:[1,0]
	v_pk_mul_f32 v[4:5], v[4:5], v[140:141] op_sel_hi:[1,0]
	v_pk_mul_f32 v[102:103], v[102:103], v[110:111]
	v_or_b32_e32 v110, 16, v153
	v_pk_mul_f32 v[102:103], v[98:99], v[102:103]
	v_pk_mul_f32 v[98:99], v[104:105], v[152:153] op_sel_hi:[1,0]
	s_mov_b32 s65, s38
	v_mul_f32_e32 v104, 0xbfb8aa3b, v98
	v_mul_f32_e32 v105, 0xbfb8aa3b, v99
	v_exp_f32_e32 v104, v104
	v_exp_f32_e32 v105, v105
	v_add_f32_e32 v104, 1.0, v104
	v_add_f32_e32 v105, 1.0, v105
	v_rcp_f32_e32 v104, v104
	v_rcp_f32_e32 v105, v105
	s_nop 0
	v_pk_mul_f32 v[98:99], v[98:99], v[104:105]
	s_nop 0
	v_pk_mul_f32 v[104:105], v[100:101], v[98:99]
	v_cvt_pk_bf16_f32 v100, v102, v103
	v_mad_i64_i32 v[102:103], s[46:47], v110, s39, v[118:119]
	v_cvt_pk_bf16_f32 v98, v106, v107
	v_cvt_pk_bf16_f32 v99, v108, v109
	v_cvt_pk_bf16_f32 v101, v104, v105
	v_lshl_add_u64 v[102:103], v[102:103], 0, v[120:121]
	global_store_dwordx4 v[102:103], v[98:101], off
	s_nop 1
	v_mul_f32_e32 v98, 0xbfb8aa3b, v94
	v_mul_f32_e32 v99, 0xbfb8aa3b, v95
	v_exp_f32_e32 v98, v98
	v_exp_f32_e32 v99, v99
	v_add_f32_e32 v98, 1.0, v98
	v_add_f32_e32 v99, 1.0, v99
	v_rcp_f32_e32 v98, v98
	v_rcp_f32_e32 v99, v99
	s_nop 0
	v_pk_mul_f32 v[94:95], v[94:95], v[98:99]
	s_nop 0
	v_pk_mul_f32 v[90:91], v[90:91], v[94:95]
	v_pk_mul_f32 v[94:95], v[96:97], v[150:151] op_sel_hi:[1,0]
	s_nop 0
	v_mul_f32_e32 v96, 0xbfb8aa3b, v94
	v_mul_f32_e32 v97, 0xbfb8aa3b, v95
	v_exp_f32_e32 v96, v96
	v_exp_f32_e32 v97, v97
	v_add_f32_e32 v96, 1.0, v96
	v_add_f32_e32 v97, 1.0, v97
	v_rcp_f32_e32 v96, v96
	v_rcp_f32_e32 v97, v97
	s_nop 0
	v_pk_mul_f32 v[94:95], v[94:95], v[96:97]
	s_nop 0
	v_pk_mul_f32 v[92:93], v[92:93], v[94:95]
	v_mul_f32_e32 v94, 0xbfb8aa3b, v86
	v_mul_f32_e32 v95, 0xbfb8aa3b, v87
	v_exp_f32_e32 v94, v94
	v_exp_f32_e32 v95, v95
	v_add_f32_e32 v94, 1.0, v94
	v_add_f32_e32 v95, 1.0, v95
	v_rcp_f32_e32 v94, v94
	v_rcp_f32_e32 v95, v95
	s_nop 0
	v_pk_mul_f32 v[86:87], v[86:87], v[94:95]
	s_nop 0
	v_pk_mul_f32 v[86:87], v[82:83], v[86:87]
	v_pk_mul_f32 v[82:83], v[88:89], v[150:151] op_sel_hi:[1,0]
	v_or_b32_e32 v94, 32, v153
	v_mul_f32_e32 v88, 0xbfb8aa3b, v82
	v_mul_f32_e32 v89, 0xbfb8aa3b, v83
	v_exp_f32_e32 v88, v88
	v_exp_f32_e32 v89, v89
	v_add_f32_e32 v88, 1.0, v88
	v_add_f32_e32 v89, 1.0, v89
	v_rcp_f32_e32 v88, v88
	v_rcp_f32_e32 v89, v89
	s_nop 0
	v_pk_mul_f32 v[82:83], v[82:83], v[88:89]
	s_nop 0
	v_pk_mul_f32 v[88:89], v[84:85], v[82:83]
	v_cvt_pk_bf16_f32 v84, v86, v87
	v_mad_i64_i32 v[86:87], s[46:47], v94, s39, v[118:119]
	v_cvt_pk_bf16_f32 v82, v90, v91
	v_cvt_pk_bf16_f32 v83, v92, v93
	v_cvt_pk_bf16_f32 v85, v88, v89
	v_lshl_add_u64 v[86:87], v[86:87], 0, v[120:121]
	global_store_dwordx4 v[86:87], v[82:85], off
	s_nop 1
	v_mul_f32_e32 v82, 0xbfb8aa3b, v78
	v_mul_f32_e32 v83, 0xbfb8aa3b, v79
	v_exp_f32_e32 v82, v82
	v_exp_f32_e32 v83, v83
	v_add_f32_e32 v82, 1.0, v82
	v_add_f32_e32 v83, 1.0, v83
	v_rcp_f32_e32 v82, v82
	v_rcp_f32_e32 v83, v83
	s_nop 0
	v_pk_mul_f32 v[78:79], v[78:79], v[82:83]
	s_nop 0
	v_pk_mul_f32 v[74:75], v[74:75], v[78:79]
	v_pk_mul_f32 v[78:79], v[80:81], v[148:149] op_sel_hi:[1,0]
	s_nop 0
	v_mul_f32_e32 v80, 0xbfb8aa3b, v78
	v_mul_f32_e32 v81, 0xbfb8aa3b, v79
	v_exp_f32_e32 v80, v80
	v_exp_f32_e32 v81, v81
	v_add_f32_e32 v80, 1.0, v80
	v_add_f32_e32 v81, 1.0, v81
	v_rcp_f32_e32 v80, v80
	v_rcp_f32_e32 v81, v81
	s_nop 0
	v_pk_mul_f32 v[78:79], v[78:79], v[80:81]
	s_nop 0
	v_pk_mul_f32 v[76:77], v[76:77], v[78:79]
	v_mul_f32_e32 v78, 0xbfb8aa3b, v70
	v_mul_f32_e32 v79, 0xbfb8aa3b, v71
	v_exp_f32_e32 v78, v78
	v_exp_f32_e32 v79, v79
	v_add_f32_e32 v78, 1.0, v78
	v_add_f32_e32 v79, 1.0, v79
	v_rcp_f32_e32 v78, v78
	v_rcp_f32_e32 v79, v79
	s_nop 0
	v_pk_mul_f32 v[70:71], v[70:71], v[78:79]
	s_nop 0
	v_pk_mul_f32 v[70:71], v[66:67], v[70:71]
	v_pk_mul_f32 v[66:67], v[72:73], v[148:149] op_sel_hi:[1,0]
	v_or_b32_e32 v78, 48, v153
	v_mul_f32_e32 v72, 0xbfb8aa3b, v66
	v_mul_f32_e32 v73, 0xbfb8aa3b, v67
	v_exp_f32_e32 v72, v72
	v_exp_f32_e32 v73, v73
	v_add_f32_e32 v72, 1.0, v72
	v_add_f32_e32 v73, 1.0, v73
	v_rcp_f32_e32 v72, v72
	v_rcp_f32_e32 v73, v73
	s_nop 0
	v_pk_mul_f32 v[66:67], v[66:67], v[72:73]
	s_nop 0
	v_pk_mul_f32 v[72:73], v[68:69], v[66:67]
	v_cvt_pk_bf16_f32 v68, v70, v71
	v_mad_i64_i32 v[70:71], s[46:47], v78, s39, v[118:119]
	v_cvt_pk_bf16_f32 v66, v74, v75
	v_cvt_pk_bf16_f32 v67, v76, v77
	v_cvt_pk_bf16_f32 v69, v72, v73
	v_lshl_add_u64 v[70:71], v[70:71], 0, v[120:121]
	global_store_dwordx4 v[70:71], v[66:69], off
	s_nop 1
	v_mul_f32_e32 v66, 0xbfb8aa3b, v62
	v_mul_f32_e32 v67, 0xbfb8aa3b, v63
	v_exp_f32_e32 v66, v66
	v_exp_f32_e32 v67, v67
	v_add_u32_e32 v68, 0x80, v153
	v_add_f32_e32 v66, 1.0, v66
	v_add_f32_e32 v67, 1.0, v67
	v_rcp_f32_e32 v66, v66
	v_rcp_f32_e32 v67, v67
	s_nop 0
	v_pk_mul_f32 v[62:63], v[62:63], v[66:67]
	s_nop 0
	v_pk_mul_f32 v[58:59], v[58:59], v[62:63]
	v_pk_mul_f32 v[62:63], v[64:65], v[146:147] op_sel_hi:[1,0]
	s_nop 0
	v_mul_f32_e32 v64, 0xbfb8aa3b, v62
	v_mul_f32_e32 v65, 0xbfb8aa3b, v63
	v_exp_f32_e32 v64, v64
	v_exp_f32_e32 v65, v65
	v_add_f32_e32 v64, 1.0, v64
; __device__ __forceinline__ unsigned pk2(float lo, float hi) { f32x2 v = {lo, hi}; bf16x2_t b = __builtin_convertvector(v, bf16x2_t); return __builtin_bit_cast(unsigned, b); }
; #define PG8_WAIT_V(n) asm volatile("s_waitcnt vmcnt(" #n ")" ::: "memory")
; #define PG8_BAR __builtin_amdgcn_s_barrier()
;     __device__ __forceinline__ void operator()(const AccT& acc, const Unit& u, int wr, int wc, int fr, int fq) const {
;     ...
;         for (int ai = 0; ai < 2; ++ai)
; #pragma unroll
;             for (int m = 0; m < 4; ++m) {
;                 const int row = row0 + ai * HALF + m * 16;
;                 const float rs = rsv[ai * 4 + m];
;                 float v[8];
; #pragma unroll
;                 for (int n = 0; n < 2; ++n)
; #pragma unroll
;                     for (int j = 0; j < 4; ++j) {
;                         const float g = acc[ai][0][m][n][j] * rs, up = acc[ai][1][m][n][j] * rs;
;                         const float sg = __builtin_amdgcn_rcpf(1.0f + __builtin_amdgcn_exp2f(-g * LOG2E));
;                         v[4 * n + j] = g * sg * up;
;                     }
;                 u32x4 w; w.x = pk2(v[0], v[1]); w.y = pk2(v[2], v[3]); w.z = pk2(v[4], v[5]); w.w = pk2(v[6], v[7]);
;                 *(u32x4*)(mid + (size_t)row * FF + col0) = w;
; template <class Epi>
; __device__ __forceinline__ void gemm_phase(LAS unsigned char* lds, const Gemm g, const StaticOrder& S, const Epi& E) {
;     ...
;     PG8_WAIT_V(0);
;     if (wr == 0) PG8_BAR;
;     PG8_BAR;
	v_add_f32_e32 v65, 1.0, v65
	v_rcp_f32_e32 v64, v64
	v_rcp_f32_e32 v65, v65
	s_nop 0
	v_pk_mul_f32 v[62:63], v[62:63], v[64:65]
	s_nop 0
	v_pk_mul_f32 v[60:61], v[60:61], v[62:63]
	v_mul_f32_e32 v62, 0xbfb8aa3b, v54
	v_mul_f32_e32 v63, 0xbfb8aa3b, v55
	v_exp_f32_e32 v62, v62
	v_exp_f32_e32 v63, v63
	v_add_f32_e32 v62, 1.0, v62
	v_add_f32_e32 v63, 1.0, v63
	v_rcp_f32_e32 v62, v62
	v_rcp_f32_e32 v63, v63
	s_nop 0
	v_pk_mul_f32 v[54:55], v[54:55], v[62:63]
	s_nop 0
	v_pk_mul_f32 v[54:55], v[50:51], v[54:55]
	v_pk_mul_f32 v[50:51], v[56:57], v[146:147] op_sel_hi:[1,0]
	s_nop 0
	v_mul_f32_e32 v56, 0xbfb8aa3b, v50
	v_mul_f32_e32 v57, 0xbfb8aa3b, v51
	v_exp_f32_e32 v56, v56
	v_exp_f32_e32 v57, v57
	v_add_f32_e32 v56, 1.0, v56
	v_add_f32_e32 v57, 1.0, v57
	v_rcp_f32_e32 v56, v56
	v_rcp_f32_e32 v57, v57
	s_nop 0
	v_pk_mul_f32 v[50:51], v[50:51], v[56:57]
	s_nop 0
	v_pk_mul_f32 v[56:57], v[52:53], v[50:51]
	v_cvt_pk_bf16_f32 v52, v54, v55
	v_mad_i64_i32 v[54:55], s[46:47], v68, s39, v[118:119]
	v_cvt_pk_bf16_f32 v50, v58, v59
	v_cvt_pk_bf16_f32 v51, v60, v61
	v_cvt_pk_bf16_f32 v53, v56, v57
	v_lshl_add_u64 v[54:55], v[54:55], 0, v[120:121]
	global_store_dwordx4 v[54:55], v[50:53], off
	s_nop 1
	v_mul_f32_e32 v50, 0xbfb8aa3b, v46
	v_mul_f32_e32 v51, 0xbfb8aa3b, v47
	v_exp_f32_e32 v50, v50
	v_exp_f32_e32 v51, v51
	v_add_f32_e32 v50, 1.0, v50
	v_add_f32_e32 v51, 1.0, v51
	v_rcp_f32_e32 v50, v50
	v_rcp_f32_e32 v51, v51
	s_nop 0
	v_pk_mul_f32 v[46:47], v[46:47], v[50:51]
	s_nop 0
	v_pk_mul_f32 v[42:43], v[42:43], v[46:47]
	v_pk_mul_f32 v[46:47], v[48:49], v[144:145] op_sel_hi:[1,0]
	s_nop 0
	v_mul_f32_e32 v48, 0xbfb8aa3b, v46
	v_mul_f32_e32 v49, 0xbfb8aa3b, v47
	v_exp_f32_e32 v48, v48
	v_exp_f32_e32 v49, v49
	v_add_f32_e32 v48, 1.0, v48
	v_add_f32_e32 v49, 1.0, v49
	v_rcp_f32_e32 v48, v48
	v_rcp_f32_e32 v49, v49
	s_nop 0
	v_pk_mul_f32 v[46:47], v[46:47], v[48:49]
	s_nop 0
	v_pk_mul_f32 v[44:45], v[44:45], v[46:47]
	v_mul_f32_e32 v46, 0xbfb8aa3b, v38
	v_mul_f32_e32 v47, 0xbfb8aa3b, v39
	v_exp_f32_e32 v46, v46
	v_exp_f32_e32 v47, v47
	v_add_f32_e32 v46, 1.0, v46
	v_add_f32_e32 v47, 1.0, v47
	v_rcp_f32_e32 v46, v46
	v_rcp_f32_e32 v47, v47
	s_nop 0
	v_pk_mul_f32 v[38:39], v[38:39], v[46:47]
	s_nop 0
	v_pk_mul_f32 v[38:39], v[34:35], v[38:39]
	v_pk_mul_f32 v[34:35], v[40:41], v[144:145] op_sel_hi:[1,0]
	v_add_u32_e32 v46, 0x90, v153
	v_mul_f32_e32 v40, 0xbfb8aa3b, v34
	v_mul_f32_e32 v41, 0xbfb8aa3b, v35
	v_exp_f32_e32 v40, v40
	v_exp_f32_e32 v41, v41
	v_add_f32_e32 v40, 1.0, v40
	v_add_f32_e32 v41, 1.0, v41
	v_rcp_f32_e32 v40, v40
	v_rcp_f32_e32 v41, v41
	s_nop 0
	v_pk_mul_f32 v[34:35], v[34:35], v[40:41]
	s_nop 0
	v_pk_mul_f32 v[40:41], v[36:37], v[34:35]
	v_cvt_pk_bf16_f32 v36, v38, v39
	v_mad_i64_i32 v[38:39], s[46:47], v46, s39, v[118:119]
	v_cvt_pk_bf16_f32 v34, v42, v43
	v_cvt_pk_bf16_f32 v35, v44, v45
	v_cvt_pk_bf16_f32 v37, v40, v41
	v_lshl_add_u64 v[38:39], v[38:39], 0, v[120:121]
	global_store_dwordx4 v[38:39], v[34:37], off
	s_nop 1
	v_mul_f32_e32 v34, 0xbfb8aa3b, v30
	v_mul_f32_e32 v35, 0xbfb8aa3b, v31
	v_exp_f32_e32 v34, v34
	v_exp_f32_e32 v35, v35
	v_add_f32_e32 v34, 1.0, v34
	v_add_f32_e32 v35, 1.0, v35
	v_rcp_f32_e32 v34, v34
	v_rcp_f32_e32 v35, v35
	s_nop 0
	v_pk_mul_f32 v[30:31], v[30:31], v[34:35]
	s_nop 0
	v_pk_mul_f32 v[26:27], v[26:27], v[30:31]
	v_pk_mul_f32 v[30:31], v[32:33], v[142:143] op_sel_hi:[1,0]
	s_nop 0
	v_mul_f32_e32 v32, 0xbfb8aa3b, v30
	v_mul_f32_e32 v33, 0xbfb8aa3b, v31
	v_exp_f32_e32 v32, v32
	v_exp_f32_e32 v33, v33
	v_add_f32_e32 v32, 1.0, v32
	v_add_f32_e32 v33, 1.0, v33
	v_rcp_f32_e32 v32, v32
	v_rcp_f32_e32 v33, v33
	s_nop 0
	v_pk_mul_f32 v[30:31], v[30:31], v[32:33]
	s_nop 0
	v_pk_mul_f32 v[28:29], v[28:29], v[30:31]
	v_mul_f32_e32 v30, 0xbfb8aa3b, v22
	v_mul_f32_e32 v31, 0xbfb8aa3b, v23
	v_exp_f32_e32 v30, v30
	v_exp_f32_e32 v31, v31
	v_add_f32_e32 v30, 1.0, v30
	v_add_f32_e32 v31, 1.0, v31
	v_rcp_f32_e32 v30, v30
	v_rcp_f32_e32 v31, v31
	s_nop 0
	v_pk_mul_f32 v[22:23], v[22:23], v[30:31]
	s_nop 0
	v_pk_mul_f32 v[22:23], v[18:19], v[22:23]
	v_pk_mul_f32 v[18:19], v[24:25], v[142:143] op_sel_hi:[1,0]
	v_add_u32_e32 v30, 0xa0, v153
	v_mul_f32_e32 v24, 0xbfb8aa3b, v18
	v_mul_f32_e32 v25, 0xbfb8aa3b, v19
	v_exp_f32_e32 v24, v24
	v_exp_f32_e32 v25, v25
	v_add_f32_e32 v24, 1.0, v24
	v_add_f32_e32 v25, 1.0, v25
	v_rcp_f32_e32 v24, v24
	v_rcp_f32_e32 v25, v25
	s_nop 0
	v_pk_mul_f32 v[18:19], v[18:19], v[24:25]
	s_nop 0
	v_pk_mul_f32 v[24:25], v[20:21], v[18:19]
	v_cvt_pk_bf16_f32 v20, v22, v23
	v_mad_i64_i32 v[22:23], s[46:47], v30, s39, v[118:119]
	v_cvt_pk_bf16_f32 v18, v26, v27
	v_cvt_pk_bf16_f32 v19, v28, v29
	v_cvt_pk_bf16_f32 v21, v24, v25
	v_lshl_add_u64 v[22:23], v[22:23], 0, v[120:121]
	global_store_dwordx4 v[22:23], v[18:21], off
	s_nop 1
	v_mul_f32_e32 v18, 0xbfb8aa3b, v14
	v_mul_f32_e32 v19, 0xbfb8aa3b, v15
	v_exp_f32_e32 v18, v18
	v_exp_f32_e32 v19, v19
	v_add_f32_e32 v18, 1.0, v18
	v_add_f32_e32 v19, 1.0, v19
	v_rcp_f32_e32 v18, v18
	v_rcp_f32_e32 v19, v19
	s_nop 0
	v_pk_mul_f32 v[14:15], v[14:15], v[18:19]
	s_nop 0
	v_pk_mul_f32 v[10:11], v[10:11], v[14:15]
	v_pk_mul_f32 v[14:15], v[16:17], v[140:141] op_sel_hi:[1,0]
	s_nop 0
	v_mul_f32_e32 v16, 0xbfb8aa3b, v14
	v_mul_f32_e32 v17, 0xbfb8aa3b, v15
	v_exp_f32_e32 v16, v16
	v_exp_f32_e32 v17, v17
	v_add_f32_e32 v16, 1.0, v16
	v_add_f32_e32 v17, 1.0, v17
	v_rcp_f32_e32 v16, v16
	v_rcp_f32_e32 v17, v17
	s_nop 0
	v_pk_mul_f32 v[14:15], v[14:15], v[16:17]
	s_nop 0
	v_pk_mul_f32 v[12:13], v[12:13], v[14:15]
	v_mul_f32_e32 v14, 0xbfb8aa3b, v6
	v_mul_f32_e32 v15, 0xbfb8aa3b, v7
	v_exp_f32_e32 v14, v14
	v_exp_f32_e32 v15, v15
	v_add_f32_e32 v14, 1.0, v14
	v_add_f32_e32 v15, 1.0, v15
	v_rcp_f32_e32 v14, v14
	v_rcp_f32_e32 v15, v15
	s_nop 0
	v_pk_mul_f32 v[6:7], v[6:7], v[14:15]
	s_nop 0
	v_pk_mul_f32 v[6:7], v[2:3], v[6:7]
	v_pk_mul_f32 v[2:3], v[8:9], v[140:141] op_sel_hi:[1,0]
	v_add_u32_e32 v14, 0xb0, v153
	v_mul_f32_e32 v8, 0xbfb8aa3b, v2
	v_mul_f32_e32 v9, 0xbfb8aa3b, v3
	v_exp_f32_e32 v8, v8
	v_exp_f32_e32 v9, v9
	v_add_f32_e32 v8, 1.0, v8
	v_add_f32_e32 v9, 1.0, v9
	v_rcp_f32_e32 v8, v8
	v_rcp_f32_e32 v9, v9
	s_nop 0
	v_pk_mul_f32 v[2:3], v[2:3], v[8:9]
	s_nop 0
	v_pk_mul_f32 v[8:9], v[4:5], v[2:3]
	v_cvt_pk_bf16_f32 v4, v6, v7
	v_mad_i64_i32 v[6:7], s[46:47], v14, s39, v[118:119]
	v_cvt_pk_bf16_f32 v2, v10, v11
	v_cvt_pk_bf16_f32 v3, v12, v13
	v_cvt_pk_bf16_f32 v5, v8, v9
	v_lshl_add_u64 v[6:7], v[6:7], 0, v[120:121]
	s_mov_b64 s[46:47], s[42:43]
	global_store_dwordx4 v[6:7], v[2:5], off
	s_cbranch_vccz .LBB0_87
	s_waitcnt vmcnt(0)
	s_cmpk_gt_u32 s52, 0xff
	s_cbranch_scc1 .LBB0_94
	s_barrier

; #define PG8_STAGE(bufoff, gbase, voff) do { _Pragma("unroll") for (int _i = 0; _i < 2; ++_i) \
;         __builtin_amdgcn_global_load_lds((const unsigned*)((const char*)(gbase) + (voff)[_i]), (LAS unsigned*)(lds + (bufoff) + ldsw + _i * 8192), 16, 0, 0); } while (0)
; #define PG8_LDA(dst, b, h) do { _Pragma("unroll") for (int m = 0; m < 4; ++m) _Pragma("unroll") for (int k = 0; k < 2; ++k) dst[m][k] = *(const LAS bf16x8*)(lds + PG8_SA(b, h) + aoff + m * 2048 + k * 1024); } while (0)
; #define PG8_LDB(dst, b, h) do { _Pragma("unroll") for (int n = 0; n < 2; ++n) _Pragma("unroll") for (int k = 0; k < 2; ++k) dst[n][k] = *(const LAS bf16x8*)(lds + PG8_SB(b, h) + boff + n * 2048 + k * 1024); } while (0)
; #define PG8_MMA(ai, bj, At, Bt) do { __builtin_amdgcn_s_setprio(1); _Pragma("unroll") for (int m = 0; m < 4; ++m) _Pragma("unroll") for (int n = 0; n < 2; ++n) _Pragma("unroll") for (int k = 0; k < 2; ++k) \
;         acc[ai][bj][m][n] = __builtin_amdgcn_mfma_f32_16x16x32_bf16(Bt[n][k], At[m][k], acc[ai][bj][m][n], 0, 0, 0); __builtin_amdgcn_s_setprio(0); } while (0)
; #define PG8_WAIT_L(n) asm volatile("s_waitcnt lgkmcnt(" #n ")" ::: "memory")
; #define PG8_BAR __builtin_amdgcn_s_barrier()
; #define PG8_SCHED __builtin_amdgcn_sched_barrier(0)
; template <class Epi>
; __device__ __forceinline__ void gemm_phase(LAS unsigned char* lds, const Gemm g, const StaticOrder& S, const Epi& E) {
;     ...
;         for (int t = 0; t < nt; t += 2) {
;             const bool last = (t == nt - 2);
;             const char* a1 = cA + (size_t)(t + 1) * kstep;
;             const char* a2 = last ? nA : cA + (size_t)(t + 2) * kstep; const char* b2 = last ? nB : cB + (size_t)(t + 2) * kstep;
;             const char* a3 = a2 + kstep; const char* b3 = b2 + kstep;
;             PG8_LDB(B0, 0, 0); PG8_SCHED; PG8_LDA(At, 0, 0); PG8_STAGE(PG8_SA(1, 1), a1 + hstep, voffA);
;             PG8_WAIT_L(8); PG8_BAR; PG8_WAIT_L(0); PG8_MMA(0, 0, At, B0); PG8_BAR; PG8_SCHED;
;             PG8_LDB(B1, 0, 1); PG8_STAGE(PG8_SB(0, 0), b2, voffB);
;     ...
; #pragma unroll
;         for (int a = 0; a < 2; ++a)
; #pragma unroll
;             for (int b = 0; b < 2; ++b)
; #pragma unroll
;                 for (int m = 0; m < 4; ++m)
; #pragma unroll
;                     for (int n = 0; n < 2; ++n) acc[a][b][m][n] = (f32x4){0.f, 0.f, 0.f, 0.f};
;         cur = nxt; cA = nA; cB = nB; ++ui;
.LBB0_653:
	s_add_u32 s60, s60, 0x80
	s_addc_u32 s61, s61, 0
	s_add_u32 s82, s62, 0x100
	v_mov_b32_e32 v2, 0
	s_addc_u32 s83, s63, 0
	s_mov_b32 s62, 0
	v_mov_b32_e32 v3, v2
	v_mov_b32_e32 v4, v2
	v_mov_b32_e32 v5, v2
	v_mov_b32_e32 v6, v2
	v_mov_b32_e32 v7, v2
	v_mov_b32_e32 v8, v2
	v_mov_b32_e32 v9, v2
	v_mov_b32_e32 v18, v2
	v_mov_b32_e32 v19, v2
	v_mov_b32_e32 v20, v2
	v_mov_b32_e32 v21, v2
	v_mov_b32_e32 v22, v2
	v_mov_b32_e32 v23, v2
	v_mov_b32_e32 v24, v2
	v_mov_b32_e32 v25, v2
	v_mov_b32_e32 v34, v2
	v_mov_b32_e32 v35, v2
	v_mov_b32_e32 v36, v2
	v_mov_b32_e32 v37, v2
	v_mov_b32_e32 v38, v2
	v_mov_b32_e32 v39, v2
	v_mov_b32_e32 v40, v2
	v_mov_b32_e32 v41, v2
	v_mov_b32_e32 v50, v2
	v_mov_b32_e32 v51, v2
	v_mov_b32_e32 v52, v2
	v_mov_b32_e32 v53, v2
	v_mov_b32_e32 v54, v2
	v_mov_b32_e32 v55, v2
	v_mov_b32_e32 v56, v2
	v_mov_b32_e32 v57, v2
	v_mov_b32_e32 v10, v2
	v_mov_b32_e32 v11, v2
	v_mov_b32_e32 v12, v2
	v_mov_b32_e32 v13, v2
	v_mov_b32_e32 v14, v2
	v_mov_b32_e32 v15, v2
	v_mov_b32_e32 v16, v2
	v_mov_b32_e32 v17, v2
	v_mov_b32_e32 v26, v2
	v_mov_b32_e32 v27, v2
	v_mov_b32_e32 v28, v2
	v_mov_b32_e32 v29, v2
	v_mov_b32_e32 v30, v2
	v_mov_b32_e32 v31, v2
	v_mov_b32_e32 v32, v2
	v_mov_b32_e32 v33, v2
	v_mov_b32_e32 v42, v2
	v_mov_b32_e32 v43, v2
	v_mov_b32_e32 v44, v2
	v_mov_b32_e32 v45, v2
	v_mov_b32_e32 v46, v2
	v_mov_b32_e32 v47, v2
	v_mov_b32_e32 v48, v2
	v_mov_b32_e32 v49, v2
	v_mov_b32_e32 v74, v2
	v_mov_b32_e32 v75, v2
	v_mov_b32_e32 v76, v2
	v_mov_b32_e32 v77, v2
	v_mov_b32_e32 v78, v2
	v_mov_b32_e32 v79, v2
	v_mov_b32_e32 v80, v2
	v_mov_b32_e32 v81, v2
	v_mov_b32_e32 v82, v2
	v_mov_b32_e32 v83, v2
	v_mov_b32_e32 v84, v2
	v_mov_b32_e32 v85, v2
	v_mov_b32_e32 v86, v2
	v_mov_b32_e32 v87, v2
	v_mov_b32_e32 v88, v2
	v_mov_b32_e32 v89, v2
	v_mov_b32_e32 v98, v2
	v_mov_b32_e32 v99, v2
	v_mov_b32_e32 v100, v2
	v_mov_b32_e32 v101, v2
	v_mov_b32_e32 v102, v2
	v_mov_b32_e32 v103, v2
	v_mov_b32_e32 v104, v2
	v_mov_b32_e32 v105, v2
	v_mov_b32_e32 v114, v2
	v_mov_b32_e32 v115, v2
	v_mov_b32_e32 v116, v2
	v_mov_b32_e32 v117, v2
	v_mov_b32_e32 v118, v2
	v_mov_b32_e32 v119, v2
	v_mov_b32_e32 v120, v2
	v_mov_b32_e32 v121, v2
	v_mov_b32_e32 v130, v2
	v_mov_b32_e32 v131, v2
	v_mov_b32_e32 v132, v2
	v_mov_b32_e32 v133, v2
	v_mov_b32_e32 v134, v2
	v_mov_b32_e32 v135, v2
	v_mov_b32_e32 v136, v2
	v_mov_b32_e32 v137, v2
	v_mov_b32_e32 v90, v2
	v_mov_b32_e32 v91, v2
	v_mov_b32_e32 v92, v2
	v_mov_b32_e32 v93, v2
	v_mov_b32_e32 v94, v2
	v_mov_b32_e32 v95, v2
	v_mov_b32_e32 v96, v2
	v_mov_b32_e32 v97, v2
	v_mov_b32_e32 v106, v2
	v_mov_b32_e32 v107, v2
	v_mov_b32_e32 v108, v2
	v_mov_b32_e32 v109, v2
	v_mov_b32_e32 v110, v2
	v_mov_b32_e32 v111, v2
	v_mov_b32_e32 v112, v2
	v_mov_b32_e32 v113, v2
	v_mov_b32_e32 v122, v2
	v_mov_b32_e32 v123, v2
	v_mov_b32_e32 v124, v2
	v_mov_b32_e32 v125, v2
	v_mov_b32_e32 v126, v2
	v_mov_b32_e32 v127, v2
	v_mov_b32_e32 v128, v2
	v_mov_b32_e32 v129, v2
	v_mov_b32_e32 v138, v2
	v_mov_b32_e32 v139, v2
	v_mov_b32_e32 v140, v2
	v_mov_b32_e32 v141, v2
	v_mov_b32_e32 v142, v2
	v_mov_b32_e32 v143, v2
	v_mov_b32_e32 v144, v2
	v_mov_b32_e32 v145, v2
	v_add_u32_e32 v70, 0x10000, v241
	ds_read_b128 v[58:61], v70
	ds_read_b128 v[62:65], v70 offset:1024
	ds_read_b128 v[66:69], v70 offset:2048
	ds_read_b128 v[70:73], v70 offset:3072
.LBB0_654:
	s_add_i32 s84, s62, 2
	s_add_u32 s64, s60, 0x80
	s_addc_u32 s63, s61, 0
	s_add_i32 s85, 0, 0x10000
	s_cmp_eq_u32 s77, s62
	s_cselect_b32 s62, s2, s64
	s_cselect_b32 s63, s3, s63
	s_cselect_b32 s65, s41, s83
	s_cselect_b32 s64, s40, s82
	s_add_i32 m0, s70, 0xc000
	ds_read_b128 v[146:149], v243
	ds_read_b128 v[150:153], v243 offset:1024
	ds_read_b128 v[154:157], v243 offset:2048
	ds_read_b128 v[158:161], v243 offset:3072
	ds_read_b128 v[162:165], v243 offset:4096
	ds_read_b128 v[166:169], v243 offset:5120
	ds_read_b128 v[170:173], v243 offset:6144
	ds_read_b128 v[174:177], v243 offset:7168
	global_load_lds_dwordx4 v214, s[60:61]
	s_add_i32 m0, s70, 0xe000
	s_nop 0
	global_load_lds_dwordx4 v216, s[60:61]
	s_waitcnt lgkmcnt(8)
	s_barrier
	s_waitcnt lgkmcnt(0)
	s_setprio 1
	v_mfma_f32_16x16x32_bf16 v[142:145], v[58:61], v[146:149], v[142:145]
	v_mfma_f32_16x16x32_bf16 v[138:141], v[66:69], v[146:149], v[138:141]
	v_mfma_f32_16x16x32_bf16 v[126:129], v[58:61], v[154:157], v[126:129]
	v_mfma_f32_16x16x32_bf16 v[122:125], v[66:69], v[154:157], v[122:125]
	v_mfma_f32_16x16x32_bf16 v[110:113], v[58:61], v[162:165], v[110:113]
	v_mfma_f32_16x16x32_bf16 v[106:109], v[66:69], v[162:165], v[106:109]
	v_mfma_f32_16x16x32_bf16 v[94:97], v[58:61], v[170:173], v[94:97]
	v_mfma_f32_16x16x32_bf16 v[90:93], v[66:69], v[170:173], v[90:93]
	v_mfma_f32_16x16x32_bf16 v[142:145], v[62:65], v[150:153], v[142:145]
	v_mfma_f32_16x16x32_bf16 v[138:141], v[70:73], v[150:153], v[138:141]
	v_mfma_f32_16x16x32_bf16 v[126:129], v[62:65], v[158:161], v[126:129]
	v_mfma_f32_16x16x32_bf16 v[122:125], v[70:73], v[158:161], v[122:125]
	v_mfma_f32_16x16x32_bf16 v[110:113], v[62:65], v[166:169], v[110:113]
	v_mfma_f32_16x16x32_bf16 v[106:109], v[70:73], v[166:169], v[106:109]
	v_mfma_f32_16x16x32_bf16 v[94:97], v[62:65], v[174:177], v[94:97]
	v_mfma_f32_16x16x32_bf16 v[90:93], v[70:73], v[174:177], v[90:93]
	s_setprio 0
	s_barrier
	s_add_i32 s86, 0, 0x14000
	s_add_i32 s85, s85, s69
	v_add_u32_e32 v190, s86, v241
	s_add_u32 s98, s64, s22
	s_addc_u32 s99, s65, s23
	s_mov_b32 m0, s85
	ds_read_b128 v[178:181], v190
	ds_read_b128 v[182:185], v190 offset:1024
	ds_read_b128 v[186:189], v190 offset:2048
	ds_read_b128 v[190:193], v190 offset:3072
	global_load_lds_dwordx4 v0, s[64:65]
	s_add_i32 m0, s85, 0x2000
	s_nop 0
	global_load_lds_dwordx4 v208, s[64:65]
	s_barrier
; #define PG8_STAGE(bufoff, gbase, voff) do { _Pragma("unroll") for (int _i = 0; _i < 2; ++_i) \
;         __builtin_amdgcn_global_load_lds((const unsigned*)((const char*)(gbase) + (voff)[_i]), (LAS unsigned*)(lds + (bufoff) + ldsw + _i * 8192), 16, 0, 0); } while (0)
; #define PG8_LDA(dst, b, h) do { _Pragma("unroll") for (int m = 0; m < 4; ++m) _Pragma("unroll") for (int k = 0; k < 2; ++k) dst[m][k] = *(const LAS bf16x8*)(lds + PG8_SA(b, h) + aoff + m * 2048 + k * 1024); } while (0)
; #define PG8_LDB(dst, b, h) do { _Pragma("unroll") for (int n = 0; n < 2; ++n) _Pragma("unroll") for (int k = 0; k < 2; ++k) dst[n][k] = *(const LAS bf16x8*)(lds + PG8_SB(b, h) + boff + n * 2048 + k * 1024); } while (0)
; #define PG8_MMA(ai, bj, At, Bt) do { __builtin_amdgcn_s_setprio(1); _Pragma("unroll") for (int m = 0; m < 4; ++m) _Pragma("unroll") for (int n = 0; n < 2; ++n) _Pragma("unroll") for (int k = 0; k < 2; ++k) \
;         acc[ai][bj][m][n] = __builtin_amdgcn_mfma_f32_16x16x32_bf16(Bt[n][k], At[m][k], acc[ai][bj][m][n], 0, 0, 0); __builtin_amdgcn_s_setprio(0); } while (0)
; #define PG8_WAIT_V(n) asm volatile("s_waitcnt vmcnt(" #n ")" ::: "memory")
; #define PG8_WAIT_L(n) asm volatile("s_waitcnt lgkmcnt(" #n ")" ::: "memory")
; #define PG8_BAR __builtin_amdgcn_s_barrier()
; #define PG8_SCHED __builtin_amdgcn_sched_barrier(0)
; template <class Epi>
; __device__ __forceinline__ void gemm_phase(LAS unsigned char* lds, const Gemm g, const StaticOrder& S, const Epi& E) {
;     ...
;             PG8_LDB(B1, 0, 1); PG8_STAGE(PG8_SB(0, 0), b2, voffB);
;             PG8_BAR; PG8_WAIT_L(0); PG8_MMA(0, 1, At, B1); PG8_BAR;
;             PG8_LDA(At, 0, 1); PG8_STAGE(PG8_SA(0, 0), a2, voffA);
;             PG8_BAR; PG8_WAIT_L(0); PG8_MMA(1, 0, At, B0); PG8_BAR; PG8_SCHED;
;             PG8_STAGE(PG8_SB(0, 1), b2 + hstep, voffB);
;             PG8_WAIT_V(6); PG8_BAR; PG8_MMA(1, 1, At, B1); PG8_BAR;
;             PG8_LDB(B0, 1, 0); PG8_SCHED; PG8_LDA(At, 1, 0); PG8_STAGE(PG8_SA(0, 1), a2 + hstep, voffA);
	s_waitcnt lgkmcnt(0)
	s_setprio 1
	v_mfma_f32_16x16x32_bf16 v[134:137], v[178:181], v[146:149], v[134:137]
	v_mfma_f32_16x16x32_bf16 v[130:133], v[186:189], v[146:149], v[130:133]
	v_mfma_f32_16x16x32_bf16 v[118:121], v[178:181], v[154:157], v[118:121]
	v_mfma_f32_16x16x32_bf16 v[114:117], v[186:189], v[154:157], v[114:117]
	v_mfma_f32_16x16x32_bf16 v[102:105], v[178:181], v[162:165], v[102:105]
	v_mfma_f32_16x16x32_bf16 v[98:101], v[186:189], v[162:165], v[98:101]
	v_mfma_f32_16x16x32_bf16 v[86:89], v[178:181], v[170:173], v[86:89]
	v_mfma_f32_16x16x32_bf16 v[82:85], v[186:189], v[170:173], v[82:85]
	v_mfma_f32_16x16x32_bf16 v[134:137], v[182:185], v[150:153], v[134:137]
	v_mfma_f32_16x16x32_bf16 v[130:133], v[190:193], v[150:153], v[130:133]
	v_mfma_f32_16x16x32_bf16 v[118:121], v[182:185], v[158:161], v[118:121]
	v_mfma_f32_16x16x32_bf16 v[114:117], v[190:193], v[158:161], v[114:117]
	v_mfma_f32_16x16x32_bf16 v[102:105], v[182:185], v[166:169], v[102:105]
	v_mfma_f32_16x16x32_bf16 v[98:101], v[190:193], v[166:169], v[98:101]
	v_mfma_f32_16x16x32_bf16 v[86:89], v[182:185], v[174:177], v[86:89]
	v_mfma_f32_16x16x32_bf16 v[82:85], v[190:193], v[174:177], v[82:85]
	s_setprio 0
	s_mov_b32 m0, s70
	s_add_u32 s100, s62, s22
	s_addc_u32 s101, s63, s23
	s_barrier
	ds_read_b128 v[146:149], v243 offset:16384
	ds_read_b128 v[150:153], v243 offset:17408
	ds_read_b128 v[154:157], v243 offset:18432
	ds_read_b128 v[158:161], v243 offset:19456
	ds_read_b128 v[162:165], v243 offset:20480
	ds_read_b128 v[166:169], v243 offset:21504
	ds_read_b128 v[170:173], v243 offset:22528
	ds_read_b128 v[174:177], v243 offset:23552
	global_load_lds_dwordx4 v212, s[62:63]
	s_mov_b32 m0, s71
	s_nop 0
	global_load_lds_dwordx4 v210, s[62:63]
	s_waitcnt vmcnt(10)
	s_barrier
	s_waitcnt lgkmcnt(0)
	s_setprio 1
	v_mfma_f32_16x16x32_bf16 v[78:81], v[58:61], v[146:149], v[78:81]
	v_mfma_f32_16x16x32_bf16 v[74:77], v[66:69], v[146:149], v[74:77]
	v_mfma_f32_16x16x32_bf16 v[46:49], v[58:61], v[154:157], v[46:49]
	v_mfma_f32_16x16x32_bf16 v[42:45], v[66:69], v[154:157], v[42:45]
	v_mfma_f32_16x16x32_bf16 v[30:33], v[58:61], v[162:165], v[30:33]
	v_mfma_f32_16x16x32_bf16 v[26:29], v[66:69], v[162:165], v[26:29]
	v_mfma_f32_16x16x32_bf16 v[14:17], v[58:61], v[170:173], v[14:17]
	v_mfma_f32_16x16x32_bf16 v[10:13], v[66:69], v[170:173], v[10:13]
	v_mfma_f32_16x16x32_bf16 v[78:81], v[62:65], v[150:153], v[78:81]
	v_mfma_f32_16x16x32_bf16 v[74:77], v[70:73], v[150:153], v[74:77]
	v_mfma_f32_16x16x32_bf16 v[46:49], v[62:65], v[158:161], v[46:49]
	v_mfma_f32_16x16x32_bf16 v[42:45], v[70:73], v[158:161], v[42:45]
	v_mfma_f32_16x16x32_bf16 v[30:33], v[62:65], v[166:169], v[30:33]
	v_mfma_f32_16x16x32_bf16 v[26:29], v[70:73], v[166:169], v[26:29]
	v_mfma_f32_16x16x32_bf16 v[14:17], v[62:65], v[174:177], v[14:17]
	v_mfma_f32_16x16x32_bf16 v[10:13], v[70:73], v[174:177], v[10:13]
	s_setprio 0
	s_barrier
	v_add_u32_e32 v70, 0x18000, v241
	ds_read_b128 v[58:61], v70
	ds_read_b128 v[62:65], v70 offset:1024
	ds_read_b128 v[66:69], v70 offset:2048
	ds_read_b128 v[70:73], v70 offset:3072
	s_add_u32 s64, s64, s50
	s_addc_u32 s65, s65, 0
	s_add_i32 s85, s86, s69
	s_mov_b32 m0, s85
	s_add_u32 vcc_lo, s64, s22
	s_addc_u32 vcc_hi, s65, s23
	global_load_lds_dwordx4 v0, s[64:65]
	s_add_i32 m0, s85, 0x2000
	s_nop 0
	global_load_lds_dwordx4 v208, s[64:65]
	s_waitcnt vmcnt(6)
	s_barrier
	s_setprio 1
	v_mfma_f32_16x16x32_bf16 v[54:57], v[178:181], v[146:149], v[54:57]
	v_mfma_f32_16x16x32_bf16 v[50:53], v[186:189], v[146:149], v[50:53]
	v_mfma_f32_16x16x32_bf16 v[38:41], v[178:181], v[154:157], v[38:41]
	v_mfma_f32_16x16x32_bf16 v[34:37], v[186:189], v[154:157], v[34:37]
	v_mfma_f32_16x16x32_bf16 v[22:25], v[178:181], v[162:165], v[22:25]
	v_mfma_f32_16x16x32_bf16 v[18:21], v[186:189], v[162:165], v[18:21]
	v_mfma_f32_16x16x32_bf16 v[6:9], v[178:181], v[170:173], v[6:9]
	v_mfma_f32_16x16x32_bf16 v[2:5], v[186:189], v[170:173], v[2:5]
	v_mfma_f32_16x16x32_bf16 v[54:57], v[182:185], v[150:153], v[54:57]
	v_mfma_f32_16x16x32_bf16 v[50:53], v[190:193], v[150:153], v[50:53]
	v_mfma_f32_16x16x32_bf16 v[38:41], v[182:185], v[158:161], v[38:41]
	v_mfma_f32_16x16x32_bf16 v[34:37], v[190:193], v[158:161], v[34:37]
	v_mfma_f32_16x16x32_bf16 v[22:25], v[182:185], v[166:169], v[22:25]
	v_mfma_f32_16x16x32_bf16 v[18:21], v[190:193], v[166:169], v[18:21]
	v_mfma_f32_16x16x32_bf16 v[6:9], v[182:185], v[174:177], v[6:9]
	v_mfma_f32_16x16x32_bf16 v[2:5], v[190:193], v[174:177], v[2:5]
	s_setprio 0
	s_add_i32 s64, 0, 0x18000
	s_barrier
	s_add_u32 s62, s62, s50
	s_addc_u32 s63, s63, 0
	s_mov_b32 m0, s72
	ds_read_b128 v[146:149], v243 offset:32768
	ds_read_b128 v[150:153], v243 offset:33792
	ds_read_b128 v[154:157], v243 offset:34816
	ds_read_b128 v[158:161], v243 offset:35840
	ds_read_b128 v[162:165], v243 offset:36864
	ds_read_b128 v[166:169], v243 offset:37888
	ds_read_b128 v[170:173], v243 offset:38912
	ds_read_b128 v[174:177], v243 offset:39936
	global_load_lds_dwordx4 v212, s[62:63]
	s_mov_b32 m0, s73
	s_nop 0
	global_load_lds_dwordx4 v210, s[62:63]
	s_waitcnt lgkmcnt(8)
	s_barrier
; #define PG8_STAGE(bufoff, gbase, voff) do { _Pragma("unroll") for (int _i = 0; _i < 2; ++_i) \
;         __builtin_amdgcn_global_load_lds((const unsigned*)((const char*)(gbase) + (voff)[_i]), (LAS unsigned*)(lds + (bufoff) + ldsw + _i * 8192), 16, 0, 0); } while (0)
; #define PG8_LDA(dst, b, h) do { _Pragma("unroll") for (int m = 0; m < 4; ++m) _Pragma("unroll") for (int k = 0; k < 2; ++k) dst[m][k] = *(const LAS bf16x8*)(lds + PG8_SA(b, h) + aoff + m * 2048 + k * 1024); } while (0)
; #define PG8_LDB(dst, b, h) do { _Pragma("unroll") for (int n = 0; n < 2; ++n) _Pragma("unroll") for (int k = 0; k < 2; ++k) dst[n][k] = *(const LAS bf16x8*)(lds + PG8_SB(b, h) + boff + n * 2048 + k * 1024); } while (0)
; #define PG8_MMA(ai, bj, At, Bt) do { __builtin_amdgcn_s_setprio(1); _Pragma("unroll") for (int m = 0; m < 4; ++m) _Pragma("unroll") for (int n = 0; n < 2; ++n) _Pragma("unroll") for (int k = 0; k < 2; ++k) \
;         acc[ai][bj][m][n] = __builtin_amdgcn_mfma_f32_16x16x32_bf16(Bt[n][k], At[m][k], acc[ai][bj][m][n], 0, 0, 0); __builtin_amdgcn_s_setprio(0); } while (0)
; #define PG8_WAIT_V(n) asm volatile("s_waitcnt vmcnt(" #n ")" ::: "memory")
; #define PG8_WAIT_L(n) asm volatile("s_waitcnt lgkmcnt(" #n ")" ::: "memory")
; #define PG8_BAR __builtin_amdgcn_s_barrier()
; #define PG8_SCHED __builtin_amdgcn_sched_barrier(0)
; template <class Epi>
; __device__ __forceinline__ void gemm_phase(LAS unsigned char* lds, const Gemm g, const StaticOrder& S, const Epi& E) {
;     ...
;             PG8_LDB(B0, 1, 0); PG8_SCHED; PG8_LDA(At, 1, 0); PG8_STAGE(PG8_SA(0, 1), a2 + hstep, voffA);
;             PG8_WAIT_L(8); PG8_BAR; PG8_WAIT_L(0); PG8_MMA(0, 0, At, B0); PG8_BAR; PG8_SCHED;
;             PG8_LDB(B1, 1, 1); PG8_STAGE(PG8_SB(1, 0), b3, voffB);
;             PG8_BAR; PG8_WAIT_L(0); PG8_MMA(0, 1, At, B1); PG8_BAR;
;             PG8_LDA(At, 1, 1); PG8_STAGE(PG8_SA(1, 0), a3, voffA);
;             PG8_BAR; PG8_WAIT_L(0); PG8_MMA(1, 0, At, B0); PG8_BAR; PG8_SCHED;
;             PG8_STAGE(PG8_SB(1, 1), b3 + hstep, voffB);
;             PG8_WAIT_V(6); PG8_BAR; PG8_MMA(1, 1, At, B1); PG8_BAR;
	s_waitcnt lgkmcnt(0)
	s_setprio 1
	v_mfma_f32_16x16x32_bf16 v[142:145], v[58:61], v[146:149], v[142:145]
	v_mfma_f32_16x16x32_bf16 v[138:141], v[66:69], v[146:149], v[138:141]
	v_mfma_f32_16x16x32_bf16 v[126:129], v[58:61], v[154:157], v[126:129]
	v_mfma_f32_16x16x32_bf16 v[122:125], v[66:69], v[154:157], v[122:125]
	v_mfma_f32_16x16x32_bf16 v[110:113], v[58:61], v[162:165], v[110:113]
	v_mfma_f32_16x16x32_bf16 v[106:109], v[66:69], v[162:165], v[106:109]
	v_mfma_f32_16x16x32_bf16 v[94:97], v[58:61], v[170:173], v[94:97]
	v_mfma_f32_16x16x32_bf16 v[90:93], v[66:69], v[170:173], v[90:93]
	v_mfma_f32_16x16x32_bf16 v[142:145], v[62:65], v[150:153], v[142:145]
	v_mfma_f32_16x16x32_bf16 v[138:141], v[70:73], v[150:153], v[138:141]
	v_mfma_f32_16x16x32_bf16 v[126:129], v[62:65], v[158:161], v[126:129]
	v_mfma_f32_16x16x32_bf16 v[122:125], v[70:73], v[158:161], v[122:125]
	v_mfma_f32_16x16x32_bf16 v[110:113], v[62:65], v[166:169], v[110:113]
	v_mfma_f32_16x16x32_bf16 v[106:109], v[70:73], v[166:169], v[106:109]
	v_mfma_f32_16x16x32_bf16 v[94:97], v[62:65], v[174:177], v[94:97]
	v_mfma_f32_16x16x32_bf16 v[90:93], v[70:73], v[174:177], v[90:93]
	s_setprio 0
	s_barrier
	s_add_i32 s62, 0, 0x1c000
	s_add_i32 s63, s64, s69
	v_add_u32_e32 v190, s62, v241
	s_mov_b32 m0, s63
	ds_read_b128 v[178:181], v190
	ds_read_b128 v[182:185], v190 offset:1024
	ds_read_b128 v[186:189], v190 offset:2048
	ds_read_b128 v[190:193], v190 offset:3072
	global_load_lds_dwordx4 v0, s[98:99]
	s_add_i32 m0, s63, 0x2000
	s_nop 0
	global_load_lds_dwordx4 v208, s[98:99]
	s_barrier
	s_waitcnt lgkmcnt(0)
	s_setprio 1
	v_mfma_f32_16x16x32_bf16 v[134:137], v[178:181], v[146:149], v[134:137]
	v_mfma_f32_16x16x32_bf16 v[130:133], v[186:189], v[146:149], v[130:133]
	v_mfma_f32_16x16x32_bf16 v[118:121], v[178:181], v[154:157], v[118:121]
	v_mfma_f32_16x16x32_bf16 v[114:117], v[186:189], v[154:157], v[114:117]
	v_mfma_f32_16x16x32_bf16 v[102:105], v[178:181], v[162:165], v[102:105]
	v_mfma_f32_16x16x32_bf16 v[98:101], v[186:189], v[162:165], v[98:101]
	v_mfma_f32_16x16x32_bf16 v[86:89], v[178:181], v[170:173], v[86:89]
	v_mfma_f32_16x16x32_bf16 v[82:85], v[186:189], v[170:173], v[82:85]
	v_mfma_f32_16x16x32_bf16 v[134:137], v[182:185], v[150:153], v[134:137]
	v_mfma_f32_16x16x32_bf16 v[130:133], v[190:193], v[150:153], v[130:133]
	v_mfma_f32_16x16x32_bf16 v[118:121], v[182:185], v[158:161], v[118:121]
	v_mfma_f32_16x16x32_bf16 v[114:117], v[190:193], v[158:161], v[114:117]
	v_mfma_f32_16x16x32_bf16 v[102:105], v[182:185], v[166:169], v[102:105]
	v_mfma_f32_16x16x32_bf16 v[98:101], v[190:193], v[166:169], v[98:101]
	v_mfma_f32_16x16x32_bf16 v[86:89], v[182:185], v[174:177], v[86:89]
	v_mfma_f32_16x16x32_bf16 v[82:85], v[190:193], v[174:177], v[82:85]
	s_setprio 0
	s_mov_b32 m0, s75
	s_barrier
	ds_read_b128 v[146:149], v243 offset:49152
	ds_read_b128 v[150:153], v243 offset:50176
	ds_read_b128 v[154:157], v243 offset:51200
	ds_read_b128 v[158:161], v243 offset:52224
	ds_read_b128 v[162:165], v243 offset:53248
	ds_read_b128 v[166:169], v243 offset:54272
	ds_read_b128 v[170:173], v243 offset:55296
	ds_read_b128 v[174:177], v243 offset:56320
	global_load_lds_dwordx4 v212, s[100:101]
	s_mov_b32 m0, s76
	s_nop 0
	global_load_lds_dwordx4 v210, s[100:101]
	s_waitcnt vmcnt(10)
	s_barrier
	s_waitcnt lgkmcnt(0)
	s_setprio 1
	v_mfma_f32_16x16x32_bf16 v[78:81], v[58:61], v[146:149], v[78:81]
	v_mfma_f32_16x16x32_bf16 v[74:77], v[66:69], v[146:149], v[74:77]
	v_mfma_f32_16x16x32_bf16 v[46:49], v[58:61], v[154:157], v[46:49]
	v_mfma_f32_16x16x32_bf16 v[42:45], v[66:69], v[154:157], v[42:45]
	v_mfma_f32_16x16x32_bf16 v[30:33], v[58:61], v[162:165], v[30:33]
	v_mfma_f32_16x16x32_bf16 v[26:29], v[66:69], v[162:165], v[26:29]
	v_mfma_f32_16x16x32_bf16 v[14:17], v[58:61], v[170:173], v[14:17]
	v_mfma_f32_16x16x32_bf16 v[10:13], v[66:69], v[170:173], v[10:13]
	v_mfma_f32_16x16x32_bf16 v[78:81], v[62:65], v[150:153], v[78:81]
	v_mfma_f32_16x16x32_bf16 v[74:77], v[70:73], v[150:153], v[74:77]
	v_mfma_f32_16x16x32_bf16 v[46:49], v[62:65], v[158:161], v[46:49]
	v_mfma_f32_16x16x32_bf16 v[42:45], v[70:73], v[158:161], v[42:45]
	v_mfma_f32_16x16x32_bf16 v[30:33], v[62:65], v[166:169], v[30:33]
	v_mfma_f32_16x16x32_bf16 v[26:29], v[70:73], v[166:169], v[26:29]
	v_mfma_f32_16x16x32_bf16 v[14:17], v[62:65], v[174:177], v[14:17]
	v_mfma_f32_16x16x32_bf16 v[10:13], v[70:73], v[174:177], v[10:13]
	s_setprio 0
	s_barrier
	v_add_u32_e32 v70, 0x10000, v241
	ds_read_b128 v[58:61], v70
	ds_read_b128 v[62:65], v70 offset:1024
	ds_read_b128 v[66:69], v70 offset:2048
	ds_read_b128 v[70:73], v70 offset:3072
	s_add_i32 s62, s62, s69
	s_mov_b32 m0, s62
	s_nop 0
	global_load_lds_dwordx4 v0, vcc
	s_add_i32 m0, s62, 0x2000
	s_nop 0
	global_load_lds_dwordx4 v208, vcc
	s_waitcnt vmcnt(6)
	s_barrier
	s_setprio 1
	v_mfma_f32_16x16x32_bf16 v[54:57], v[178:181], v[146:149], v[54:57]
	v_mfma_f32_16x16x32_bf16 v[50:53], v[186:189], v[146:149], v[50:53]
	v_mfma_f32_16x16x32_bf16 v[38:41], v[178:181], v[154:157], v[38:41]
	v_mfma_f32_16x16x32_bf16 v[34:37], v[186:189], v[154:157], v[34:37]
	v_mfma_f32_16x16x32_bf16 v[22:25], v[178:181], v[162:165], v[22:25]
	v_mfma_f32_16x16x32_bf16 v[18:21], v[186:189], v[162:165], v[18:21]
	v_mfma_f32_16x16x32_bf16 v[6:9], v[178:181], v[170:173], v[6:9]
	v_mfma_f32_16x16x32_bf16 v[2:5], v[186:189], v[170:173], v[2:5]
	v_mfma_f32_16x16x32_bf16 v[54:57], v[182:185], v[150:153], v[54:57]
	v_mfma_f32_16x16x32_bf16 v[50:53], v[190:193], v[150:153], v[50:53]
	v_mfma_f32_16x16x32_bf16 v[38:41], v[182:185], v[158:161], v[38:41]
	v_mfma_f32_16x16x32_bf16 v[34:37], v[190:193], v[158:161], v[34:37]
	v_mfma_f32_16x16x32_bf16 v[22:25], v[182:185], v[166:169], v[22:25]
	v_mfma_f32_16x16x32_bf16 v[18:21], v[190:193], v[166:169], v[18:21]
	v_mfma_f32_16x16x32_bf16 v[6:9], v[182:185], v[174:177], v[6:9]
	v_mfma_f32_16x16x32_bf16 v[2:5], v[190:193], v[174:177], v[2:5]
	s_setprio 0
	s_add_u32 s60, s60, 0x100
	s_addc_u32 s61, s61, 0
	s_add_u32 s82, s82, 0x100
	s_addc_u32 s83, s83, 0
	s_cmp_ge_u32 s84, s74
	s_mov_b32 s62, s84
	s_barrier
; __device__ __forceinline__ unsigned pk2(float lo, float hi) { f32x2 v = {lo, hi}; bf16x2_t b = __builtin_convertvector(v, bf16x2_t); return __builtin_bit_cast(unsigned, b); }
;     __device__ __forceinline__ void operator()(const AccT& acc, const Unit& u, int wr, int wc, int fr, int fq) const {
;         const int row0 = u.pm * BM + wr * 64 + fr, col0 = u.pn * BM + wc * 32 + 8 * fq;
;         f32x4 gv[2][2];
; #pragma unroll
;         for (int bj = 0; bj < 2; ++bj)
; #pragma unroll
;             for (int n = 0; n < 2; ++n) gv[bj][n] = *(const f32x4*)(g + col0 + bj * HALF + 4 * n);
; #pragma unroll
;         for (int ai = 0; ai < 2; ++ai) {
;             f32x4 xv[4][2][2];
; #pragma unroll
;             for (int m = 0; m < 4; ++m)
; #pragma unroll
;                 for (int bj = 0; bj < 2; ++bj) {
;                     const size_t p = (size_t)(row0 + ai * HALF + m * 16) * DM + col0 + bj * HALF;
;                     xv[m][bj][0] = __builtin_nontemporal_load((const f32x4*)(xin + p)); xv[m][bj][1] = __builtin_nontemporal_load((const f32x4*)(xin + p + 4));
;                 }
; #pragma unroll
;             for (int m = 0; m < 4; ++m) {
;                 const int row = row0 + ai * HALF + m * 16;
;                 float ssa = 0.f;
; #pragma unroll
;                 for (int bj = 0; bj < 2; ++bj) {
;                     const size_t p = (size_t)row * DM + col0 + bj * HALF;
;                     const f32x4 x0 = xv[m][bj][0] + acc[ai][bj][m][0] * alpha, x1 = xv[m][bj][1] + acc[ai][bj][m][1] * alpha;
;                     __builtin_nontemporal_store(x0, (f32x4*)(xout + p)); __builtin_nontemporal_store(x1, (f32x4*)(xout + p + 4));
;                     ssa += (x0[0] * x0[0] + x0[1] * x0[1]) + (x0[2] * x0[2] + x0[3] * x0[3]) + (x1[0] * x1[0] + x1[1] * x1[1]) + (x1[2] * x1[2] + x1[3] * x1[3]);
;                     const f32x4 h0 = x0 * gv[bj][0], h1 = x1 * gv[bj][1];
;                     u32x4 w; w.x = pk2(h0[0], h0[1]); w.y = pk2(h0[2], h0[3]); w.z = pk2(h1[0], h1[1]); w.w = pk2(h1[2], h1[3]);
;                     *(u32x4*)(h + p) = w;
;                 }
;                 ssa += __shfl_xor(ssa, 16); ssa += __shfl_xor(ssa, 32);
;                 if (fq == 0) unsafeAtomicAdd(ssout + row, ssa);
	s_cbranch_scc0 .LBB0_654
	s_waitcnt lgkmcnt(0)
	v_lshl_or_b32 v218, s81, 8, v242
	v_ashrrev_i32_e32 v219, 31, v218
	v_lshl_add_u32 v220, s80, 8, v240
	v_lshlrev_b64 v[146:147], 2, v[218:219]
	v_ashrrev_i32_e32 v221, 31, v220
	v_lshl_add_u64 v[62:63], s[44:45], 0, v[146:147]
	v_lshl_add_u64 v[222:223], s[54:55], 0, v[146:147]
	v_lshlrev_b64 v[146:147], 13, v[220:221]
	v_lshl_add_u64 v[146:147], v[222:223], 0, v[146:147]
	global_load_dwordx4 v[66:69], v[62:63], off offset:16
	global_load_dwordx4 v[70:73], v[62:63], off
	global_load_dwordx4 v[58:61], v[62:63], off offset:528
	s_nop 0
	global_load_dwordx4 v[62:65], v[62:63], off offset:512
	s_nop 0
	global_load_dwordx4 v[246:249], v[146:147], off offset:16 nt
	global_load_dwordx4 v[202:205], v[146:147], off nt
	global_load_dwordx4 v[194:197], v[146:147], off offset:528 nt
	global_load_dwordx4 v[198:201], v[146:147], off offset:512 nt
	v_or_b32_e32 v228, 16, v220
	v_and_b32_e32 v149, 64, v234
	v_ashrrev_i32_e32 v229, 31, v228
	v_xor_b32_e32 v148, 16, v234
	v_add_u32_e32 v149, 64, v149
	v_lshlrev_b64 v[146:147], 13, v[228:229]
	v_or_b32_e32 v226, 32, v220
	v_cmp_lt_i32_e32 vcc, v148, v149
	v_lshl_add_u64 v[146:147], v[222:223], 0, v[146:147]
	v_ashrrev_i32_e32 v227, 31, v226
	v_cndmask_b32_e32 v148, v234, v148, vcc
	global_load_dwordx4 v[186:189], v[146:147], off offset:16 nt
	global_load_dwordx4 v[190:193], v[146:147], off nt
	global_load_dwordx4 v[178:181], v[146:147], off offset:528 nt
	global_load_dwordx4 v[182:185], v[146:147], off offset:512 nt
	v_lshlrev_b64 v[146:147], 13, v[226:227]
	v_or_b32_e32 v224, 48, v220
	v_lshlrev_b32_e32 v245, 2, v148
	v_xor_b32_e32 v148, 32, v234
	v_lshl_add_u64 v[146:147], v[222:223], 0, v[146:147]
	v_ashrrev_i32_e32 v225, 31, v224
	v_cmp_lt_i32_e32 vcc, v148, v149
	global_load_dwordx4 v[170:173], v[146:147], off offset:16 nt
	global_load_dwordx4 v[174:177], v[146:147], off nt
	global_load_dwordx4 v[154:157], v[146:147], off offset:528 nt
	global_load_dwordx4 v[158:161], v[146:147], off offset:512 nt
	v_lshlrev_b64 v[146:147], 13, v[224:225]
	v_cndmask_b32_e32 v148, v234, v148, vcc
	v_lshl_add_u64 v[150:151], v[222:223], 0, v[146:147]
	v_lshlrev_b32_e32 v244, 2, v148
	global_load_dwordx4 v[162:165], v[150:151], off offset:16 nt
	global_load_dwordx4 v[166:169], v[150:151], off nt
	global_load_dwordx4 v[146:149], v[150:151], off offset:528 nt
	s_nop 0
	global_load_dwordx4 v[150:153], v[150:151], off offset:512 nt
	v_lshlrev_b64 v[230:231], 11, v[220:221]
	v_readlane_b32 s60, v251, 56
	v_lshl_add_u64 v[230:231], v[230:231], 0, v[218:219]
	v_readlane_b32 s61, v251, 57
	v_readlane_b32 s62, v254, 8
	v_readlane_b32 s63, v254, 9
	s_waitcnt vmcnt(0)
	v_pk_fma_f32 v[140:141], s[58:59], v[140:141], v[248:249]
	v_pk_fma_f32 v[144:145], s[58:59], v[144:145], v[204:205]
	v_pk_fma_f32 v[142:143], s[46:47], v[142:143], v[202:203]
	v_lshl_add_u64 v[202:203], v[230:231], 2, s[60:61]
	v_pk_fma_f32 v[138:139], s[46:47], v[138:139], v[246:247]
	global_store_dwordx4 v[202:203], v[142:145], off nt
	global_store_dwordx4 v[202:203], v[138:141], off offset:16 nt
	v_mul_f32_e32 v202, v143, v143
	v_mul_f32_e32 v203, v145, v145
	v_fmac_f32_e32 v202, v142, v142
	v_fmac_f32_e32 v203, v144, v144
	v_add_f32_e32 v202, v202, v203
	v_mul_f32_e32 v203, v139, v139
	v_fmac_f32_e32 v203, v138, v138
	v_add_f32_e32 v202, v203, v202
	v_mul_f32_e32 v203, v141, v141
	v_fmac_f32_e32 v203, v140, v140
	v_add_f32_e32 v204, v203, v202
	v_pk_mul_f32 v[144:145], v[72:73], v[144:145]
	v_pk_mul_f32 v[142:143], v[70:71], v[142:143]
	v_pk_mul_f32 v[202:203], v[68:69], v[140:141]
	v_pk_mul_f32 v[140:141], v[66:67], v[138:139]
	v_cvt_pk_bf16_f32 v138, v142, v143
	v_cvt_pk_bf16_f32 v139, v144, v145
	v_cvt_pk_bf16_f32 v140, v140, v141
	v_cvt_pk_bf16_f32 v141, v202, v203
	v_lshl_add_u64 v[142:143], v[230:231], 1, s[62:63]
	v_or_b32_e32 v230, 0x80, v230
	global_store_dwordx4 v[142:143], v[138:141], off
	v_pk_fma_f32 v[136:137], s[58:59], v[136:137], v[200:201]
	v_pk_fma_f32 v[134:135], s[46:47], v[134:135], v[198:199]
	v_lshl_add_u64 v[138:139], v[230:231], 2, s[60:61]
	v_pk_fma_f32 v[132:133], s[58:59], v[132:133], v[196:197]
	v_pk_fma_f32 v[130:131], s[46:47], v[130:131], v[194:195]
	global_store_dwordx4 v[138:139], v[134:137], off nt
	global_store_dwordx4 v[138:139], v[130:133], off offset:16 nt
	v_mul_f32_e32 v138, v135, v135
	v_mul_f32_e32 v139, v137, v137
	v_fmac_f32_e32 v138, v134, v134
	v_fmac_f32_e32 v139, v136, v136
	v_add_f32_e32 v138, v138, v139
	v_mul_f32_e32 v139, v131, v131
	v_fmac_f32_e32 v139, v130, v130
	v_add_f32_e32 v138, v139, v138
	v_mul_f32_e32 v139, v133, v133
	v_fmac_f32_e32 v139, v132, v132
	v_add_f32_e32 v138, v139, v138
	v_add_f32_e32 v140, v204, v138
	v_pk_mul_f32 v[136:137], v[64:65], v[136:137]
	v_pk_mul_f32 v[134:135], v[62:63], v[134:135]
	v_pk_mul_f32 v[138:139], v[60:61], v[132:133]
	v_pk_mul_f32 v[132:133], v[58:59], v[130:131]
	v_cvt_pk_bf16_f32 v130, v134, v135
	v_cvt_pk_bf16_f32 v131, v136, v137
	v_cvt_pk_bf16_f32 v132, v132, v133
	v_cvt_pk_bf16_f32 v133, v138, v139
	v_lshl_add_u64 v[134:135], v[230:231], 1, s[62:63]
	global_store_dwordx4 v[134:135], v[130:133], off
	ds_bpermute_b32 v130, v245, v140
	v_lshl_add_u64 v[138:139], v[220:221], 2, s[56:57]
	s_waitcnt lgkmcnt(0)
	v_add_f32_e32 v130, v140, v130
	ds_bpermute_b32 v131, v244, v130
	s_and_saveexec_b64 s[60:61], s[36:37]
	s_cbranch_execz .LBB0_657
	s_waitcnt lgkmcnt(0)
	v_add_f32_e32 v130, v130, v131
	global_atomic_add_f32 v[138:139], v130, off
